# K-loops: loop-invariant B-fragment LDS read base hoisted to the preheader (no non-MFMA VALU left in the K-loops)
# baseline (speedup 1.0000x reference)
.LBB0_107:
	v_mov_b64_e32 v[2:3], 0x1600
	s_ashr_i32 s43, s42, 31
	v_cmp_lt_i64_e32 vcc, s[24:25], v[2:3]
	s_lshl_b64 s[24:25], s[42:43], 20
	s_add_u32 s48, s78, s24
	s_addc_u32 s49, s79, s25
	s_and_b64 s[24:25], vcc, exec
	s_cselect_b32 s43, s49, s51
	s_cselect_b32 s62, s48, s50
	s_ashr_i32 s23, s22, 31
	s_lshl_b64 s[24:25], s[22:23], 20
	s_add_u32 s24, s40, s24
	s_addc_u32 s25, s41, s25
	s_and_b64 s[52:53], vcc, exec
	s_cselect_b32 s23, s25, s27
	s_cselect_b32 s63, s24, s26
	s_add_u32 s50, s50, 0x80080
	s_addc_u32 s51, s51, 0
	s_add_u32 s64, s26, 0x100
	v_mov_b32_e32 v2, 0
	s_addc_u32 s65, s27, 0
	s_mov_b32 s66, -2
	v_mov_b32_e32 v3, v2
	v_mov_b32_e32 v4, v2
	v_mov_b32_e32 v5, v2
	v_mov_b32_e32 v10, v2
	v_mov_b32_e32 v11, v2
	v_mov_b32_e32 v12, v2
	v_mov_b32_e32 v13, v2
	v_mov_b32_e32 v18, v2
	v_mov_b32_e32 v19, v2
	v_mov_b32_e32 v20, v2
	v_mov_b32_e32 v21, v2
	v_mov_b32_e32 v26, v2
	v_mov_b32_e32 v27, v2
	v_mov_b32_e32 v28, v2
	v_mov_b32_e32 v29, v2
	v_mov_b32_e32 v34, v2
	v_mov_b32_e32 v35, v2
	v_mov_b32_e32 v36, v2
	v_mov_b32_e32 v37, v2
	v_mov_b32_e32 v42, v2
	v_mov_b32_e32 v43, v2
	v_mov_b32_e32 v44, v2
	v_mov_b32_e32 v45, v2
	v_mov_b32_e32 v50, v2
	v_mov_b32_e32 v51, v2
	v_mov_b32_e32 v52, v2
	v_mov_b32_e32 v53, v2
	v_mov_b32_e32 v58, v2
	v_mov_b32_e32 v59, v2
	v_mov_b32_e32 v60, v2
	v_mov_b32_e32 v61, v2
	v_mov_b32_e32 v6, v2
	v_mov_b32_e32 v7, v2
	v_mov_b32_e32 v8, v2
	v_mov_b32_e32 v9, v2
	v_mov_b32_e32 v14, v2
	v_mov_b32_e32 v15, v2
	v_mov_b32_e32 v16, v2
	v_mov_b32_e32 v17, v2
	v_mov_b32_e32 v22, v2
	v_mov_b32_e32 v23, v2
	v_mov_b32_e32 v24, v2
	v_mov_b32_e32 v25, v2
	v_mov_b32_e32 v30, v2
	v_mov_b32_e32 v31, v2
	v_mov_b32_e32 v32, v2
	v_mov_b32_e32 v33, v2
	v_mov_b32_e32 v38, v2
	v_mov_b32_e32 v39, v2
	v_mov_b32_e32 v40, v2
	v_mov_b32_e32 v41, v2
	v_mov_b32_e32 v46, v2
	v_mov_b32_e32 v47, v2
	v_mov_b32_e32 v48, v2
	v_mov_b32_e32 v49, v2
	v_mov_b32_e32 v54, v2
	v_mov_b32_e32 v55, v2
	v_mov_b32_e32 v56, v2
	v_mov_b32_e32 v57, v2
	v_mov_b32_e32 v62, v2
	v_mov_b32_e32 v63, v2
	v_mov_b32_e32 v64, v2
	v_mov_b32_e32 v65, v2
	v_mov_b32_e32 v66, v2
	v_mov_b32_e32 v67, v2
	v_mov_b32_e32 v68, v2
	v_mov_b32_e32 v69, v2
	v_mov_b32_e32 v74, v2
	v_mov_b32_e32 v75, v2
	v_mov_b32_e32 v76, v2
	v_mov_b32_e32 v77, v2
	v_mov_b32_e32 v82, v2
	v_mov_b32_e32 v83, v2
	v_mov_b32_e32 v84, v2
	v_mov_b32_e32 v85, v2
	v_mov_b32_e32 v90, v2
	v_mov_b32_e32 v91, v2
	v_mov_b32_e32 v92, v2
	v_mov_b32_e32 v93, v2
	v_mov_b32_e32 v98, v2
	v_mov_b32_e32 v99, v2
	v_mov_b32_e32 v100, v2
	v_mov_b32_e32 v101, v2
	v_mov_b32_e32 v106, v2
	v_mov_b32_e32 v107, v2
	v_mov_b32_e32 v108, v2
	v_mov_b32_e32 v109, v2
	v_mov_b32_e32 v114, v2
	v_mov_b32_e32 v115, v2
	v_mov_b32_e32 v116, v2
	v_mov_b32_e32 v117, v2
	v_mov_b32_e32 v122, v2
	v_mov_b32_e32 v123, v2
	v_mov_b32_e32 v124, v2
	v_mov_b32_e32 v125, v2
	v_mov_b32_e32 v70, v2
	v_mov_b32_e32 v71, v2
	v_mov_b32_e32 v72, v2
	v_mov_b32_e32 v73, v2
	v_mov_b32_e32 v78, v2
	v_mov_b32_e32 v79, v2
	v_mov_b32_e32 v80, v2
	v_mov_b32_e32 v81, v2
	v_mov_b32_e32 v86, v2
	v_mov_b32_e32 v87, v2
	v_mov_b32_e32 v88, v2
	v_mov_b32_e32 v89, v2
	v_mov_b32_e32 v94, v2
	v_mov_b32_e32 v95, v2
	v_mov_b32_e32 v96, v2
	v_mov_b32_e32 v97, v2
	v_mov_b32_e32 v102, v2
	v_mov_b32_e32 v103, v2
	v_mov_b32_e32 v104, v2
	v_mov_b32_e32 v105, v2
	v_mov_b32_e32 v110, v2
	v_mov_b32_e32 v111, v2
	v_mov_b32_e32 v112, v2
	v_mov_b32_e32 v113, v2
	v_mov_b32_e32 v118, v2
	v_mov_b32_e32 v119, v2
	v_mov_b32_e32 v120, v2
	v_mov_b32_e32 v121, v2
	v_mov_b32_e32 v126, v2
	v_mov_b32_e32 v127, v2
	v_mov_b32_e32 v128, v2
	v_mov_b32_e32 v129, v2
	v_add_u32_e32 v134, 0x10000, v180
.LBB0_108:
	s_add_u32 s26, s50, 0xfff80080
	s_addc_u32 s27, s51, -1
	s_add_i32 s67, 0, 0x10000
	ds_read_b128 v[182:185], v134
	ds_read_b128 v[186:189], v134 offset:1024
	ds_read_b128 v[190:193], v134 offset:2048
	ds_read_b128 v[194:197], v134 offset:3072
	s_cmp_eq_u32 s66, 28
	s_cselect_b32 s53, s43, s27
	s_cselect_b32 s52, s62, s26
	s_cselect_b32 s27, s23, s65
	s_cselect_b32 s26, s63, s64
	s_add_i32 m0, s7, 0xc000
	ds_read_b128 v[198:201], v181
	ds_read_b128 v[202:205], v181 offset:1024
	ds_read_b128 v[206:209], v181 offset:2048
	ds_read_b128 v[210:213], v181 offset:3072
	ds_read_b128 v[214:217], v181 offset:4096
	ds_read_b128 v[218:221], v181 offset:5120
	ds_read_b128 v[222:225], v181 offset:6144
	ds_read_b128 v[226:229], v181 offset:7168
	global_load_lds_dwordx4 v162, s[50:51]
	s_add_i32 m0, s7, 0xe000
	s_nop 0
	global_load_lds_dwordx4 v164, s[50:51]
	s_waitcnt lgkmcnt(8)
	s_barrier
	s_waitcnt lgkmcnt(0)
	s_setprio 1
	s_waitcnt lgkmcnt(0)
	v_mfma_f32_16x16x32_bf16 v[126:129], v[182:185], v[198:201], v[126:129]
	v_mfma_f32_16x16x32_bf16 v[118:121], v[190:193], v[198:201], v[118:121]
	v_mfma_f32_16x16x32_bf16 v[110:113], v[182:185], v[206:209], v[110:113]
	v_mfma_f32_16x16x32_bf16 v[102:105], v[190:193], v[206:209], v[102:105]
	v_mfma_f32_16x16x32_bf16 v[94:97], v[182:185], v[214:217], v[94:97]
	v_mfma_f32_16x16x32_bf16 v[86:89], v[190:193], v[214:217], v[86:89]
	v_mfma_f32_16x16x32_bf16 v[78:81], v[182:185], v[222:225], v[78:81]
	v_mfma_f32_16x16x32_bf16 v[70:73], v[190:193], v[222:225], v[70:73]
	v_mfma_f32_16x16x32_bf16 v[126:129], v[186:189], v[202:205], v[126:129]
	v_mfma_f32_16x16x32_bf16 v[118:121], v[194:197], v[202:205], v[118:121]
	v_mfma_f32_16x16x32_bf16 v[110:113], v[186:189], v[210:213], v[110:113]
	v_mfma_f32_16x16x32_bf16 v[102:105], v[194:197], v[210:213], v[102:105]
	v_mfma_f32_16x16x32_bf16 v[94:97], v[186:189], v[218:221], v[94:97]
	v_mfma_f32_16x16x32_bf16 v[86:89], v[194:197], v[218:221], v[86:89]
	v_mfma_f32_16x16x32_bf16 v[78:81], v[186:189], v[226:229], v[78:81]
	v_mfma_f32_16x16x32_bf16 v[70:73], v[194:197], v[226:229], v[70:73]
	s_setprio 0
	s_barrier
	s_add_i32 s70, 0, 0x14000
	s_add_i32 s67, s67, s6
	s_mov_b32 m0, s67
	ds_read_b128 v[230:233], v134 offset:16384
	ds_read_b128 v[234:237], v134 offset:17408
	ds_read_b128 v[238:241], v134 offset:18432
	ds_read_b128 v[242:245], v134 offset:19456
	global_load_lds_dwordx4 v0, s[26:27]
	s_add_i32 m0, s67, 0x2000
	s_nop 0
	global_load_lds_dwordx4 v138, s[26:27]
	s_barrier
	s_waitcnt lgkmcnt(0)
	s_setprio 1
	s_waitcnt lgkmcnt(0)
	v_mfma_f32_16x16x32_bf16 v[122:125], v[230:233], v[198:201], v[122:125]
	v_mfma_f32_16x16x32_bf16 v[114:117], v[238:241], v[198:201], v[114:117]
	v_mfma_f32_16x16x32_bf16 v[106:109], v[230:233], v[206:209], v[106:109]
	v_mfma_f32_16x16x32_bf16 v[98:101], v[238:241], v[206:209], v[98:101]
	v_mfma_f32_16x16x32_bf16 v[90:93], v[230:233], v[214:217], v[90:93]
	v_mfma_f32_16x16x32_bf16 v[82:85], v[238:241], v[214:217], v[82:85]
	v_mfma_f32_16x16x32_bf16 v[74:77], v[230:233], v[222:225], v[74:77]
	v_mfma_f32_16x16x32_bf16 v[66:69], v[238:241], v[222:225], v[66:69]
	v_mfma_f32_16x16x32_bf16 v[122:125], v[234:237], v[202:205], v[122:125]
	v_mfma_f32_16x16x32_bf16 v[114:117], v[242:245], v[202:205], v[114:117]
	v_mfma_f32_16x16x32_bf16 v[106:109], v[234:237], v[210:213], v[106:109]
	v_mfma_f32_16x16x32_bf16 v[98:101], v[242:245], v[210:213], v[98:101]
	v_mfma_f32_16x16x32_bf16 v[90:93], v[234:237], v[218:221], v[90:93]
	v_mfma_f32_16x16x32_bf16 v[82:85], v[242:245], v[218:221], v[82:85]
	v_mfma_f32_16x16x32_bf16 v[74:77], v[234:237], v[226:229], v[74:77]
	v_mfma_f32_16x16x32_bf16 v[66:69], v[242:245], v[226:229], v[66:69]
	s_setprio 0
	s_mov_b32 m0, s7
	s_add_u32 vcc_lo, s52, s10
	s_addc_u32 vcc_hi, s53, s11
	s_barrier
	ds_read_b128 v[198:201], v181 offset:16384
	ds_read_b128 v[202:205], v181 offset:17408
	ds_read_b128 v[206:209], v181 offset:18432
	ds_read_b128 v[210:213], v181 offset:19456
	ds_read_b128 v[214:217], v181 offset:20480
	ds_read_b128 v[218:221], v181 offset:21504
	ds_read_b128 v[222:225], v181 offset:22528
	ds_read_b128 v[226:229], v181 offset:23552
	global_load_lds_dwordx4 v142, s[52:53]
	s_mov_b32 m0, s14
	s_nop 0
	global_load_lds_dwordx4 v140, s[52:53]
	s_barrier
	s_waitcnt lgkmcnt(0)
	s_setprio 1
	s_waitcnt lgkmcnt(0)
	v_mfma_f32_16x16x32_bf16 v[62:65], v[182:185], v[198:201], v[62:65]
	v_mfma_f32_16x16x32_bf16 v[54:57], v[190:193], v[198:201], v[54:57]
	v_mfma_f32_16x16x32_bf16 v[46:49], v[182:185], v[206:209], v[46:49]
	v_mfma_f32_16x16x32_bf16 v[38:41], v[190:193], v[206:209], v[38:41]
	v_mfma_f32_16x16x32_bf16 v[30:33], v[182:185], v[214:217], v[30:33]
	v_mfma_f32_16x16x32_bf16 v[22:25], v[190:193], v[214:217], v[22:25]
	v_mfma_f32_16x16x32_bf16 v[14:17], v[182:185], v[222:225], v[14:17]
	v_mfma_f32_16x16x32_bf16 v[6:9], v[190:193], v[222:225], v[6:9]
	v_mfma_f32_16x16x32_bf16 v[62:65], v[186:189], v[202:205], v[62:65]
	v_mfma_f32_16x16x32_bf16 v[54:57], v[194:197], v[202:205], v[54:57]
	v_mfma_f32_16x16x32_bf16 v[46:49], v[186:189], v[210:213], v[46:49]
	v_mfma_f32_16x16x32_bf16 v[38:41], v[194:197], v[210:213], v[38:41]
	v_mfma_f32_16x16x32_bf16 v[30:33], v[186:189], v[218:221], v[30:33]
	v_mfma_f32_16x16x32_bf16 v[22:25], v[194:197], v[218:221], v[22:25]
	v_mfma_f32_16x16x32_bf16 v[14:17], v[186:189], v[226:229], v[14:17]
	v_mfma_f32_16x16x32_bf16 v[6:9], v[194:197], v[226:229], v[6:9]
	s_setprio 0
	s_barrier
	s_add_u32 s68, s26, 0x80000
	s_addc_u32 s69, s27, 0
	s_add_i32 s67, s70, s6
	s_mov_b32 m0, s67
	s_nop 0
	global_load_lds_dwordx4 v0, s[68:69]
	s_add_i32 m0, s67, 0x2000
	s_nop 0
	global_load_lds_dwordx4 v138, s[68:69]
	s_waitcnt vmcnt(6)
	s_barrier
	s_setprio 1
	v_mfma_f32_16x16x32_bf16 v[58:61], v[230:233], v[198:201], v[58:61]
	v_mfma_f32_16x16x32_bf16 v[50:53], v[238:241], v[198:201], v[50:53]
	v_mfma_f32_16x16x32_bf16 v[42:45], v[230:233], v[206:209], v[42:45]
	v_mfma_f32_16x16x32_bf16 v[34:37], v[238:241], v[206:209], v[34:37]
	v_mfma_f32_16x16x32_bf16 v[26:29], v[230:233], v[214:217], v[26:29]
	v_mfma_f32_16x16x32_bf16 v[18:21], v[238:241], v[214:217], v[18:21]
	v_mfma_f32_16x16x32_bf16 v[10:13], v[230:233], v[222:225], v[10:13]
	v_mfma_f32_16x16x32_bf16 v[2:5], v[238:241], v[222:225], v[2:5]
	v_mfma_f32_16x16x32_bf16 v[58:61], v[234:237], v[202:205], v[58:61]
	v_mfma_f32_16x16x32_bf16 v[50:53], v[242:245], v[202:205], v[50:53]
	v_mfma_f32_16x16x32_bf16 v[42:45], v[234:237], v[210:213], v[42:45]
	v_mfma_f32_16x16x32_bf16 v[34:37], v[242:245], v[210:213], v[34:37]
	v_mfma_f32_16x16x32_bf16 v[26:29], v[234:237], v[218:221], v[26:29]
	v_mfma_f32_16x16x32_bf16 v[18:21], v[242:245], v[218:221], v[18:21]
	v_mfma_f32_16x16x32_bf16 v[10:13], v[234:237], v[226:229], v[10:13]
	v_mfma_f32_16x16x32_bf16 v[2:5], v[242:245], v[226:229], v[2:5]
	s_setprio 0
	s_add_i32 s67, 0, 0x18000
	s_barrier
	ds_read_b128 v[182:185], v134 offset:32768
	ds_read_b128 v[186:189], v134 offset:33792
	ds_read_b128 v[190:193], v134 offset:34816
	ds_read_b128 v[194:197], v134 offset:35840
	s_add_u32 s52, s52, 0x80000
	s_addc_u32 s53, s53, 0
	s_mov_b32 m0, s54
	ds_read_b128 v[198:201], v181 offset:32768
	ds_read_b128 v[202:205], v181 offset:33792
	ds_read_b128 v[206:209], v181 offset:34816
	ds_read_b128 v[210:213], v181 offset:35840
	ds_read_b128 v[214:217], v181 offset:36864
	ds_read_b128 v[218:221], v181 offset:37888
	ds_read_b128 v[222:225], v181 offset:38912
	ds_read_b128 v[226:229], v181 offset:39936
	global_load_lds_dwordx4 v142, s[52:53]
	s_mov_b32 m0, s55
	s_nop 0
	global_load_lds_dwordx4 v140, s[52:53]
	s_waitcnt lgkmcnt(8)
	s_barrier
	s_waitcnt lgkmcnt(0)
	s_setprio 1
	s_waitcnt lgkmcnt(0)
	v_mfma_f32_16x16x32_bf16 v[126:129], v[182:185], v[198:201], v[126:129]
	v_mfma_f32_16x16x32_bf16 v[118:121], v[190:193], v[198:201], v[118:121]
	v_mfma_f32_16x16x32_bf16 v[110:113], v[182:185], v[206:209], v[110:113]
	v_mfma_f32_16x16x32_bf16 v[102:105], v[190:193], v[206:209], v[102:105]
	v_mfma_f32_16x16x32_bf16 v[94:97], v[182:185], v[214:217], v[94:97]
	v_mfma_f32_16x16x32_bf16 v[86:89], v[190:193], v[214:217], v[86:89]
	v_mfma_f32_16x16x32_bf16 v[78:81], v[182:185], v[222:225], v[78:81]
	v_mfma_f32_16x16x32_bf16 v[70:73], v[190:193], v[222:225], v[70:73]
	v_mfma_f32_16x16x32_bf16 v[126:129], v[186:189], v[202:205], v[126:129]
	v_mfma_f32_16x16x32_bf16 v[118:121], v[194:197], v[202:205], v[118:121]
	v_mfma_f32_16x16x32_bf16 v[110:113], v[186:189], v[210:213], v[110:113]
	v_mfma_f32_16x16x32_bf16 v[102:105], v[194:197], v[210:213], v[102:105]
	v_mfma_f32_16x16x32_bf16 v[94:97], v[186:189], v[218:221], v[94:97]
	v_mfma_f32_16x16x32_bf16 v[86:89], v[194:197], v[218:221], v[86:89]
	v_mfma_f32_16x16x32_bf16 v[78:81], v[186:189], v[226:229], v[78:81]
	v_mfma_f32_16x16x32_bf16 v[70:73], v[194:197], v[226:229], v[70:73]
	s_setprio 0
	s_barrier
	s_add_i32 s52, 0, 0x1c000
	s_add_i32 s53, s67, s6
	s_add_u32 s100, s26, s10
	s_addc_u32 s101, s27, s11
	s_mov_b32 m0, s53
	ds_read_b128 v[230:233], v134 offset:49152
	ds_read_b128 v[234:237], v134 offset:50176
	ds_read_b128 v[238:241], v134 offset:51200
	ds_read_b128 v[242:245], v134 offset:52224
	global_load_lds_dwordx4 v0, s[100:101]
	s_add_u32 s100, s26, s10
	s_addc_u32 s101, s27, s11
	s_add_i32 m0, s53, 0x2000
	s_nop 0
	global_load_lds_dwordx4 v138, s[100:101]
	s_barrier
	s_waitcnt lgkmcnt(0)
	s_setprio 1
	s_waitcnt lgkmcnt(0)
	v_mfma_f32_16x16x32_bf16 v[122:125], v[230:233], v[198:201], v[122:125]
	v_mfma_f32_16x16x32_bf16 v[114:117], v[238:241], v[198:201], v[114:117]
	v_mfma_f32_16x16x32_bf16 v[106:109], v[230:233], v[206:209], v[106:109]
	v_mfma_f32_16x16x32_bf16 v[98:101], v[238:241], v[206:209], v[98:101]
	v_mfma_f32_16x16x32_bf16 v[90:93], v[230:233], v[214:217], v[90:93]
	v_mfma_f32_16x16x32_bf16 v[82:85], v[238:241], v[214:217], v[82:85]
	v_mfma_f32_16x16x32_bf16 v[74:77], v[230:233], v[222:225], v[74:77]
	v_mfma_f32_16x16x32_bf16 v[66:69], v[238:241], v[222:225], v[66:69]
	v_mfma_f32_16x16x32_bf16 v[122:125], v[234:237], v[202:205], v[122:125]
	v_mfma_f32_16x16x32_bf16 v[114:117], v[242:245], v[202:205], v[114:117]
	v_mfma_f32_16x16x32_bf16 v[106:109], v[234:237], v[210:213], v[106:109]
	v_mfma_f32_16x16x32_bf16 v[98:101], v[242:245], v[210:213], v[98:101]
	v_mfma_f32_16x16x32_bf16 v[90:93], v[234:237], v[218:221], v[90:93]
	v_mfma_f32_16x16x32_bf16 v[82:85], v[242:245], v[218:221], v[82:85]
	v_mfma_f32_16x16x32_bf16 v[74:77], v[234:237], v[226:229], v[74:77]
	v_mfma_f32_16x16x32_bf16 v[66:69], v[242:245], v[226:229], v[66:69]
	s_setprio 0
	s_mov_b32 m0, s57
	s_barrier
	ds_read_b128 v[198:201], v181 offset:49152
	ds_read_b128 v[202:205], v181 offset:50176
	ds_read_b128 v[206:209], v181 offset:51200
	ds_read_b128 v[210:213], v181 offset:52224
	ds_read_b128 v[214:217], v181 offset:53248
	ds_read_b128 v[218:221], v181 offset:54272
	ds_read_b128 v[222:225], v181 offset:55296
	ds_read_b128 v[226:229], v181 offset:56320
	global_load_lds_dwordx4 v142, vcc
	s_mov_b32 m0, s58
	s_nop 0
	global_load_lds_dwordx4 v140, vcc
	s_barrier
	s_waitcnt lgkmcnt(0)
	s_setprio 1
	s_waitcnt lgkmcnt(0)
	v_mfma_f32_16x16x32_bf16 v[62:65], v[182:185], v[198:201], v[62:65]
	v_mfma_f32_16x16x32_bf16 v[54:57], v[190:193], v[198:201], v[54:57]
	v_mfma_f32_16x16x32_bf16 v[46:49], v[182:185], v[206:209], v[46:49]
	v_mfma_f32_16x16x32_bf16 v[38:41], v[190:193], v[206:209], v[38:41]
	v_mfma_f32_16x16x32_bf16 v[30:33], v[182:185], v[214:217], v[30:33]
	v_mfma_f32_16x16x32_bf16 v[22:25], v[190:193], v[214:217], v[22:25]
	v_mfma_f32_16x16x32_bf16 v[14:17], v[182:185], v[222:225], v[14:17]
	v_mfma_f32_16x16x32_bf16 v[6:9], v[190:193], v[222:225], v[6:9]
	v_mfma_f32_16x16x32_bf16 v[62:65], v[186:189], v[202:205], v[62:65]
	v_mfma_f32_16x16x32_bf16 v[54:57], v[194:197], v[202:205], v[54:57]
	v_mfma_f32_16x16x32_bf16 v[46:49], v[186:189], v[210:213], v[46:49]
	v_mfma_f32_16x16x32_bf16 v[38:41], v[194:197], v[210:213], v[38:41]
	v_mfma_f32_16x16x32_bf16 v[30:33], v[186:189], v[218:221], v[30:33]
	v_mfma_f32_16x16x32_bf16 v[22:25], v[194:197], v[218:221], v[22:25]
	v_mfma_f32_16x16x32_bf16 v[14:17], v[186:189], v[226:229], v[14:17]
	v_mfma_f32_16x16x32_bf16 v[6:9], v[194:197], v[226:229], v[6:9]
	s_setprio 0
	s_barrier
	s_add_u32 s26, s26, 0x80080
	s_addc_u32 s27, s27, 0
	s_add_i32 s52, s52, s6
	s_mov_b32 m0, s52
	s_nop 0
	global_load_lds_dwordx4 v0, s[26:27]
	s_add_i32 m0, s52, 0x2000
	s_nop 0
	global_load_lds_dwordx4 v138, s[26:27]
	s_waitcnt vmcnt(6)
	s_barrier
	s_setprio 1
	v_mfma_f32_16x16x32_bf16 v[58:61], v[230:233], v[198:201], v[58:61]
	v_mfma_f32_16x16x32_bf16 v[50:53], v[238:241], v[198:201], v[50:53]
	v_mfma_f32_16x16x32_bf16 v[42:45], v[230:233], v[206:209], v[42:45]
	v_mfma_f32_16x16x32_bf16 v[34:37], v[238:241], v[206:209], v[34:37]
	v_mfma_f32_16x16x32_bf16 v[26:29], v[230:233], v[214:217], v[26:29]
	v_mfma_f32_16x16x32_bf16 v[18:21], v[238:241], v[214:217], v[18:21]
	v_mfma_f32_16x16x32_bf16 v[10:13], v[230:233], v[222:225], v[10:13]
	v_mfma_f32_16x16x32_bf16 v[2:5], v[238:241], v[222:225], v[2:5]
	v_mfma_f32_16x16x32_bf16 v[58:61], v[234:237], v[202:205], v[58:61]
	v_mfma_f32_16x16x32_bf16 v[50:53], v[242:245], v[202:205], v[50:53]
	v_mfma_f32_16x16x32_bf16 v[42:45], v[234:237], v[210:213], v[42:45]
	v_mfma_f32_16x16x32_bf16 v[34:37], v[242:245], v[210:213], v[34:37]
	v_mfma_f32_16x16x32_bf16 v[26:29], v[234:237], v[218:221], v[26:29]
	v_mfma_f32_16x16x32_bf16 v[18:21], v[242:245], v[218:221], v[18:21]
	v_mfma_f32_16x16x32_bf16 v[10:13], v[234:237], v[226:229], v[10:13]
	v_mfma_f32_16x16x32_bf16 v[2:5], v[242:245], v[226:229], v[2:5]
	s_setprio 0
	s_add_i32 s66, s66, 2
	s_add_u32 s50, s50, 0x100
	s_addc_u32 s51, s51, 0
	s_add_u32 s64, s64, 0x100
	s_addc_u32 s65, s65, 0
	s_cmp_gt_u32 s66, 29
	s_barrier
	s_cbranch_scc0 .LBB0_108
	v_mul_f32_e32 v134, 0xbfb8aa3b, v126
	v_exp_f32_e32 v134, v134
	s_lshl_b32 s23, s61, 7
	s_or_b32 s23, s23, s56
	s_ashr_i32 s23, s23, 6
	v_add_f32_e32 v134, 1.0, v134
	v_rcp_f32_e32 v134, v134
	s_mul_i32 s26, s60, 0x58
	s_ashr_i32 s43, s23, 31
	s_mul_hi_i32 s27, s60, 0x58
	v_mul_f32_e32 v126, v126, v134
	v_mul_f32_e32 v122, v126, v122
	v_mul_f32_e32 v126, 0xbfb8aa3b, v118
	v_exp_f32_e32 v126, v126
	s_add_u32 s26, s26, s23
	s_addc_u32 s27, s27, s43
	s_lshl_b64 s[26:27], s[26:27], 15
	v_add_f32_e32 v126, 1.0, v126
	v_rcp_f32_e32 v126, v126
	v_lshl_add_u64 v[166:167], v[144:145], 0, s[26:27]
	s_and_b64 vcc, exec, s[38:39]
	s_mov_b32 s61, s22
	v_mul_f32_e32 v118, v118, v126
	v_mul_f32_e32 v126, v118, v114
	v_mul_f32_e32 v114, 0xbfb8aa3b, v127
	v_mul_f32_e32 v118, 0xbfb8aa3b, v119
	v_exp_f32_e32 v114, v114
	v_exp_f32_e32 v118, v118
	s_mov_b32 s60, s42
	s_mov_b64 s[26:27], s[24:25]
	v_add_f32_e32 v114, 1.0, v114
	v_add_f32_e32 v118, 1.0, v118
	v_rcp_f32_e32 v114, v114
	v_rcp_f32_e32 v118, v118
	s_mov_b64 s[50:51], s[48:49]
	v_readlane_b32 s70, v254, 38
	v_mul_f32_e32 v114, v127, v114
	v_mul_f32_e32 v118, v119, v118
	v_mul_f32_e32 v114, v114, v123
	v_mul_f32_e32 v123, v118, v115
	v_mul_f32_e32 v118, 0xbfb8aa3b, v120
	v_exp_f32_e32 v118, v118
	v_mul_f32_e32 v115, 0xbfb8aa3b, v128
	v_exp_f32_e32 v115, v115
	v_cvt_pk_bf16_f32 v114, v122, v114
	v_add_f32_e32 v118, 1.0, v118
	v_rcp_f32_e32 v118, v118
	v_add_f32_e32 v115, 1.0, v115
	v_rcp_f32_e32 v115, v115
	v_mul_f32_e32 v118, v120, v118
	v_mul_f32_e32 v120, v118, v116
	v_mul_f32_e32 v116, 0xbfb8aa3b, v129
	v_mul_f32_e32 v118, 0xbfb8aa3b, v121
	v_exp_f32_e32 v116, v116
	v_exp_f32_e32 v118, v118
	v_mul_f32_e32 v115, v128, v115
	v_mul_f32_e32 v115, v115, v124
	v_add_f32_e32 v116, 1.0, v116
	v_add_f32_e32 v118, 1.0, v118
	v_rcp_f32_e32 v116, v116
	v_rcp_f32_e32 v118, v118
	v_mul_f32_e32 v116, v129, v116
	v_mul_f32_e32 v118, v121, v118
	v_mul_f32_e32 v116, v116, v125
	v_mul_f32_e32 v117, v118, v117
	v_lshl_add_u64 v[118:119], v[166:167], 0, v[146:147]
	v_cvt_pk_bf16_f32 v115, v115, v116
	v_cvt_pk_bf16_f32 v116, v126, v123
	v_cvt_pk_bf16_f32 v117, v120, v117
	global_store_dwordx4 v[118:119], v[114:117], off
	s_nop 1
	v_mul_f32_e32 v114, 0xbfb8aa3b, v110
	v_exp_f32_e32 v114, v114
	s_nop 0
	v_add_f32_e32 v114, 1.0, v114
	v_rcp_f32_e32 v114, v114
	s_nop 0
	v_mul_f32_e32 v110, v110, v114
	v_mul_f32_e32 v106, v110, v106
	v_mul_f32_e32 v110, 0xbfb8aa3b, v102
	v_exp_f32_e32 v110, v110
	s_nop 0
	v_add_f32_e32 v110, 1.0, v110
	v_rcp_f32_e32 v110, v110
	s_nop 0
	v_mul_f32_e32 v102, v102, v110
	v_mul_f32_e32 v110, v102, v98
	v_mul_f32_e32 v98, 0xbfb8aa3b, v111
	v_mul_f32_e32 v102, 0xbfb8aa3b, v103
	v_exp_f32_e32 v98, v98
	v_exp_f32_e32 v102, v102
	v_add_f32_e32 v98, 1.0, v98
	v_add_f32_e32 v102, 1.0, v102
	v_rcp_f32_e32 v98, v98
	v_rcp_f32_e32 v102, v102
	v_mul_f32_e32 v98, v111, v98
	v_mul_f32_e32 v102, v103, v102
	v_mul_f32_e32 v98, v98, v107
	v_mul_f32_e32 v107, v102, v99
	v_mul_f32_e32 v102, 0xbfb8aa3b, v104
	v_exp_f32_e32 v102, v102
	v_mul_f32_e32 v99, 0xbfb8aa3b, v112
	v_exp_f32_e32 v99, v99
	v_cvt_pk_bf16_f32 v98, v106, v98
	v_add_f32_e32 v102, 1.0, v102
	v_rcp_f32_e32 v102, v102
	v_add_f32_e32 v99, 1.0, v99
	v_rcp_f32_e32 v99, v99
	v_mul_f32_e32 v102, v104, v102
	v_mul_f32_e32 v104, v102, v100
	v_mul_f32_e32 v100, 0xbfb8aa3b, v113
	v_mul_f32_e32 v102, 0xbfb8aa3b, v105
	v_exp_f32_e32 v100, v100
	v_exp_f32_e32 v102, v102
	v_mul_f32_e32 v99, v112, v99
	v_mul_f32_e32 v99, v99, v108
	v_add_f32_e32 v100, 1.0, v100
	v_add_f32_e32 v102, 1.0, v102
	v_rcp_f32_e32 v100, v100
	v_rcp_f32_e32 v102, v102
	v_mul_f32_e32 v100, v113, v100
	v_mul_f32_e32 v102, v105, v102
	v_mul_f32_e32 v100, v100, v109
	v_mul_f32_e32 v101, v102, v101
	v_lshl_add_u64 v[102:103], v[166:167], 0, v[148:149]
	v_cvt_pk_bf16_f32 v99, v99, v100
	v_cvt_pk_bf16_f32 v100, v110, v107
	v_cvt_pk_bf16_f32 v101, v104, v101
	global_store_dwordx4 v[102:103], v[98:101], off
	s_nop 1
	v_mul_f32_e32 v98, 0xbfb8aa3b, v94
	v_exp_f32_e32 v98, v98
	s_nop 0
	v_add_f32_e32 v98, 1.0, v98
	v_rcp_f32_e32 v98, v98
	s_nop 0
	v_mul_f32_e32 v94, v94, v98
	v_mul_f32_e32 v90, v94, v90
	v_mul_f32_e32 v94, 0xbfb8aa3b, v86
	v_exp_f32_e32 v94, v94
	s_nop 0
	v_add_f32_e32 v94, 1.0, v94
	v_rcp_f32_e32 v94, v94
	s_nop 0
	v_mul_f32_e32 v86, v86, v94
	v_mul_f32_e32 v94, v86, v82
	v_mul_f32_e32 v82, 0xbfb8aa3b, v95
	v_mul_f32_e32 v86, 0xbfb8aa3b, v87
	v_exp_f32_e32 v82, v82
	v_exp_f32_e32 v86, v86
	v_add_f32_e32 v82, 1.0, v82
	v_add_f32_e32 v86, 1.0, v86
	v_rcp_f32_e32 v82, v82
	v_rcp_f32_e32 v86, v86
	v_mul_f32_e32 v82, v95, v82
	v_mul_f32_e32 v86, v87, v86
	v_mul_f32_e32 v82, v82, v91
	v_mul_f32_e32 v91, v86, v83
	v_mul_f32_e32 v86, 0xbfb8aa3b, v88
	v_exp_f32_e32 v86, v86
	v_mul_f32_e32 v83, 0xbfb8aa3b, v96
	v_exp_f32_e32 v83, v83
	v_cvt_pk_bf16_f32 v82, v90, v82
	v_add_f32_e32 v86, 1.0, v86
	v_rcp_f32_e32 v86, v86
	v_add_f32_e32 v83, 1.0, v83
	v_rcp_f32_e32 v83, v83
	v_mul_f32_e32 v86, v88, v86
	v_mul_f32_e32 v88, v86, v84
	v_mul_f32_e32 v84, 0xbfb8aa3b, v97
	v_mul_f32_e32 v86, 0xbfb8aa3b, v89
	v_exp_f32_e32 v84, v84
	v_exp_f32_e32 v86, v86
	v_mul_f32_e32 v83, v96, v83
	v_mul_f32_e32 v83, v83, v92
	v_add_f32_e32 v84, 1.0, v84
	v_add_f32_e32 v86, 1.0, v86
	v_rcp_f32_e32 v84, v84
	v_rcp_f32_e32 v86, v86
	v_mul_f32_e32 v84, v97, v84
	v_mul_f32_e32 v86, v89, v86
	v_mul_f32_e32 v84, v84, v93
	v_mul_f32_e32 v85, v86, v85
	v_lshl_add_u64 v[86:87], v[166:167], 0, v[150:151]
	v_cvt_pk_bf16_f32 v83, v83, v84
	v_cvt_pk_bf16_f32 v84, v94, v91
	v_cvt_pk_bf16_f32 v85, v88, v85
	global_store_dwordx4 v[86:87], v[82:85], off
	s_nop 1
	v_mul_f32_e32 v82, 0xbfb8aa3b, v78
	v_exp_f32_e32 v82, v82
	s_nop 0
	v_add_f32_e32 v82, 1.0, v82
	v_rcp_f32_e32 v82, v82
	s_nop 0
	v_mul_f32_e32 v78, v78, v82
	v_mul_f32_e32 v74, v78, v74
	v_mul_f32_e32 v78, 0xbfb8aa3b, v70
	v_exp_f32_e32 v78, v78
	s_nop 0
	v_add_f32_e32 v78, 1.0, v78
	v_rcp_f32_e32 v78, v78
	s_nop 0
	v_mul_f32_e32 v70, v70, v78
	v_mul_f32_e32 v78, v70, v66
	v_mul_f32_e32 v66, 0xbfb8aa3b, v79
	v_mul_f32_e32 v70, 0xbfb8aa3b, v71
	v_exp_f32_e32 v66, v66
	v_exp_f32_e32 v70, v70
	v_add_f32_e32 v66, 1.0, v66
	v_add_f32_e32 v70, 1.0, v70
	v_rcp_f32_e32 v66, v66
	v_rcp_f32_e32 v70, v70
	v_mul_f32_e32 v66, v79, v66
	v_mul_f32_e32 v70, v71, v70
	v_mul_f32_e32 v66, v66, v75
	v_mul_f32_e32 v75, v70, v67
	v_mul_f32_e32 v70, 0xbfb8aa3b, v72
	v_exp_f32_e32 v70, v70
	v_mul_f32_e32 v67, 0xbfb8aa3b, v80
	v_exp_f32_e32 v67, v67
	v_cvt_pk_bf16_f32 v66, v74, v66
	v_add_f32_e32 v70, 1.0, v70
	v_rcp_f32_e32 v70, v70
	v_add_f32_e32 v67, 1.0, v67
	v_rcp_f32_e32 v67, v67
	v_mul_f32_e32 v70, v72, v70
	v_mul_f32_e32 v72, v70, v68
	v_mul_f32_e32 v68, 0xbfb8aa3b, v81
	v_mul_f32_e32 v70, 0xbfb8aa3b, v73
	v_exp_f32_e32 v68, v68
	v_exp_f32_e32 v70, v70
	v_mul_f32_e32 v67, v80, v67
	v_mul_f32_e32 v67, v67, v76
	v_add_f32_e32 v68, 1.0, v68
	v_add_f32_e32 v70, 1.0, v70
	v_rcp_f32_e32 v68, v68
	v_rcp_f32_e32 v70, v70
	v_mul_f32_e32 v68, v81, v68
	v_mul_f32_e32 v70, v73, v70
	v_mul_f32_e32 v68, v68, v77
	v_mul_f32_e32 v69, v70, v69
	v_lshl_add_u64 v[70:71], v[166:167], 0, v[152:153]
	v_cvt_pk_bf16_f32 v67, v67, v68
	v_cvt_pk_bf16_f32 v68, v78, v75
	v_cvt_pk_bf16_f32 v69, v72, v69
	global_store_dwordx4 v[70:71], v[66:69], off
	s_nop 1
	v_mul_f32_e32 v66, 0xbfb8aa3b, v62
	v_exp_f32_e32 v66, v66
	s_nop 0
	v_add_f32_e32 v66, 1.0, v66
	v_rcp_f32_e32 v66, v66
	s_nop 0
	v_mul_f32_e32 v62, v62, v66
	v_mul_f32_e32 v58, v62, v58
	v_mul_f32_e32 v62, 0xbfb8aa3b, v54
	v_exp_f32_e32 v62, v62
	s_nop 0
	v_add_f32_e32 v62, 1.0, v62
	v_rcp_f32_e32 v62, v62
	s_nop 0
	v_mul_f32_e32 v54, v54, v62
	v_mul_f32_e32 v62, v54, v50
	v_mul_f32_e32 v50, 0xbfb8aa3b, v63
	v_mul_f32_e32 v54, 0xbfb8aa3b, v55
	v_exp_f32_e32 v50, v50
	v_exp_f32_e32 v54, v54
	v_add_f32_e32 v50, 1.0, v50
	v_add_f32_e32 v54, 1.0, v54
	v_rcp_f32_e32 v50, v50
	v_rcp_f32_e32 v54, v54
	v_mul_f32_e32 v50, v63, v50
	v_mul_f32_e32 v54, v55, v54
	v_mul_f32_e32 v50, v50, v59
	v_mul_f32_e32 v59, v54, v51
	v_mul_f32_e32 v54, 0xbfb8aa3b, v56
	v_exp_f32_e32 v54, v54
	v_mul_f32_e32 v51, 0xbfb8aa3b, v64
	v_exp_f32_e32 v51, v51
	v_cvt_pk_bf16_f32 v50, v58, v50
	v_add_f32_e32 v54, 1.0, v54
	v_rcp_f32_e32 v54, v54
	v_add_f32_e32 v51, 1.0, v51
	v_rcp_f32_e32 v51, v51
	v_mul_f32_e32 v54, v56, v54
	v_mul_f32_e32 v56, v54, v52
	v_mul_f32_e32 v52, 0xbfb8aa3b, v65
	v_mul_f32_e32 v54, 0xbfb8aa3b, v57
	v_exp_f32_e32 v52, v52
	v_exp_f32_e32 v54, v54
	v_mul_f32_e32 v51, v64, v51
	v_mul_f32_e32 v51, v51, v60
	v_add_f32_e32 v52, 1.0, v52
	v_add_f32_e32 v54, 1.0, v54
	v_rcp_f32_e32 v52, v52
	v_rcp_f32_e32 v54, v54
	v_mul_f32_e32 v52, v65, v52
	v_mul_f32_e32 v54, v57, v54
	v_mul_f32_e32 v52, v52, v61
	v_mul_f32_e32 v53, v54, v53
	v_lshl_add_u64 v[54:55], v[166:167], 0, v[154:155]
	v_cvt_pk_bf16_f32 v51, v51, v52
	v_cvt_pk_bf16_f32 v52, v62, v59
	v_cvt_pk_bf16_f32 v53, v56, v53
	global_store_dwordx4 v[54:55], v[50:53], off
	s_nop 1
	v_mul_f32_e32 v50, 0xbfb8aa3b, v46
	v_exp_f32_e32 v50, v50
	s_nop 0
	v_add_f32_e32 v50, 1.0, v50
	v_rcp_f32_e32 v50, v50
	s_nop 0
	v_mul_f32_e32 v46, v46, v50
	v_mul_f32_e32 v42, v46, v42
	v_mul_f32_e32 v46, 0xbfb8aa3b, v38
	v_exp_f32_e32 v46, v46
	s_nop 0
	v_add_f32_e32 v46, 1.0, v46
	v_rcp_f32_e32 v46, v46
	s_nop 0
	v_mul_f32_e32 v38, v38, v46
	v_mul_f32_e32 v46, v38, v34
	v_mul_f32_e32 v34, 0xbfb8aa3b, v47
	v_mul_f32_e32 v38, 0xbfb8aa3b, v39
	v_exp_f32_e32 v34, v34
	v_exp_f32_e32 v38, v38
	v_add_f32_e32 v34, 1.0, v34
	v_add_f32_e32 v38, 1.0, v38
	v_rcp_f32_e32 v34, v34
	v_rcp_f32_e32 v38, v38
	v_mul_f32_e32 v34, v47, v34
	v_mul_f32_e32 v38, v39, v38
	v_mul_f32_e32 v34, v34, v43
	v_mul_f32_e32 v43, v38, v35
	v_mul_f32_e32 v38, 0xbfb8aa3b, v40
	v_exp_f32_e32 v38, v38
	v_mul_f32_e32 v35, 0xbfb8aa3b, v48
	v_exp_f32_e32 v35, v35
	v_cvt_pk_bf16_f32 v34, v42, v34
	v_add_f32_e32 v38, 1.0, v38
	v_rcp_f32_e32 v38, v38
	v_add_f32_e32 v35, 1.0, v35
	v_rcp_f32_e32 v35, v35
	v_mul_f32_e32 v38, v40, v38
	v_mul_f32_e32 v40, v38, v36
	v_mul_f32_e32 v36, 0xbfb8aa3b, v49
	v_mul_f32_e32 v38, 0xbfb8aa3b, v41
	v_exp_f32_e32 v36, v36
	v_exp_f32_e32 v38, v38
	v_mul_f32_e32 v35, v48, v35
	v_mul_f32_e32 v35, v35, v44
	v_add_f32_e32 v36, 1.0, v36
	v_add_f32_e32 v38, 1.0, v38
	v_rcp_f32_e32 v36, v36
	v_rcp_f32_e32 v38, v38
	v_mul_f32_e32 v36, v49, v36
	v_mul_f32_e32 v38, v41, v38
	v_mul_f32_e32 v36, v36, v45
	v_mul_f32_e32 v37, v38, v37
	v_lshl_add_u64 v[38:39], v[166:167], 0, v[156:157]
	v_cvt_pk_bf16_f32 v35, v35, v36
	v_cvt_pk_bf16_f32 v36, v46, v43
	v_cvt_pk_bf16_f32 v37, v40, v37
	global_store_dwordx4 v[38:39], v[34:37], off
	s_nop 1
	v_mul_f32_e32 v34, 0xbfb8aa3b, v30
	v_exp_f32_e32 v34, v34
	s_nop 0
	v_add_f32_e32 v34, 1.0, v34
	v_rcp_f32_e32 v34, v34
	s_nop 0
	v_mul_f32_e32 v30, v30, v34
	v_mul_f32_e32 v26, v30, v26
	v_mul_f32_e32 v30, 0xbfb8aa3b, v22
	v_exp_f32_e32 v30, v30
	s_nop 0
	v_add_f32_e32 v30, 1.0, v30
	v_rcp_f32_e32 v30, v30
	s_nop 0
	v_mul_f32_e32 v22, v22, v30
	v_mul_f32_e32 v30, v22, v18
	v_mul_f32_e32 v18, 0xbfb8aa3b, v31
	v_mul_f32_e32 v22, 0xbfb8aa3b, v23
	v_exp_f32_e32 v18, v18
	v_exp_f32_e32 v22, v22
	v_add_f32_e32 v18, 1.0, v18
	v_add_f32_e32 v22, 1.0, v22
	v_rcp_f32_e32 v18, v18
	v_rcp_f32_e32 v22, v22
	v_mul_f32_e32 v18, v31, v18
	v_mul_f32_e32 v22, v23, v22
	v_mul_f32_e32 v18, v18, v27
	v_mul_f32_e32 v27, v22, v19
	v_mul_f32_e32 v22, 0xbfb8aa3b, v24
	v_exp_f32_e32 v22, v22
	v_mul_f32_e32 v19, 0xbfb8aa3b, v32
	v_exp_f32_e32 v19, v19
	v_cvt_pk_bf16_f32 v18, v26, v18
	v_add_f32_e32 v22, 1.0, v22
	v_rcp_f32_e32 v22, v22
	v_add_f32_e32 v19, 1.0, v19
	v_rcp_f32_e32 v19, v19
	v_mul_f32_e32 v22, v24, v22
	v_mul_f32_e32 v24, v22, v20
	v_mul_f32_e32 v20, 0xbfb8aa3b, v33
	v_mul_f32_e32 v22, 0xbfb8aa3b, v25
	v_exp_f32_e32 v20, v20
	v_exp_f32_e32 v22, v22
	v_mul_f32_e32 v19, v32, v19
	v_mul_f32_e32 v19, v19, v28
	v_add_f32_e32 v20, 1.0, v20
	v_add_f32_e32 v22, 1.0, v22
	v_rcp_f32_e32 v20, v20
	v_rcp_f32_e32 v22, v22
	v_mul_f32_e32 v20, v33, v20
	v_mul_f32_e32 v22, v25, v22
	v_mul_f32_e32 v20, v20, v29
	v_mul_f32_e32 v21, v22, v21
	v_lshl_add_u64 v[22:23], v[166:167], 0, v[158:159]
	v_cvt_pk_bf16_f32 v19, v19, v20
	v_cvt_pk_bf16_f32 v20, v30, v27
	v_cvt_pk_bf16_f32 v21, v24, v21
	global_store_dwordx4 v[22:23], v[18:21], off
	s_nop 1
	v_mul_f32_e32 v18, 0xbfb8aa3b, v14
	v_exp_f32_e32 v18, v18
	s_nop 0
	v_add_f32_e32 v18, 1.0, v18
	v_rcp_f32_e32 v18, v18
	s_nop 0
	v_mul_f32_e32 v14, v14, v18
	v_mul_f32_e32 v10, v14, v10
	v_mul_f32_e32 v14, 0xbfb8aa3b, v6
	v_exp_f32_e32 v14, v14
	s_nop 0
	v_add_f32_e32 v14, 1.0, v14
	v_rcp_f32_e32 v14, v14
	s_nop 0
	v_mul_f32_e32 v6, v6, v14
	v_mul_f32_e32 v14, v6, v2
	v_mul_f32_e32 v2, 0xbfb8aa3b, v15
	v_mul_f32_e32 v6, 0xbfb8aa3b, v7
	v_exp_f32_e32 v2, v2
	v_exp_f32_e32 v6, v6
	v_add_f32_e32 v2, 1.0, v2
	v_add_f32_e32 v6, 1.0, v6
	v_rcp_f32_e32 v2, v2
	v_rcp_f32_e32 v6, v6
	v_mul_f32_e32 v2, v15, v2
	v_mul_f32_e32 v6, v7, v6
	v_mul_f32_e32 v2, v2, v11
	v_mul_f32_e32 v11, v6, v3
	v_mul_f32_e32 v6, 0xbfb8aa3b, v8
	v_exp_f32_e32 v6, v6
	v_mul_f32_e32 v3, 0xbfb8aa3b, v16
	v_exp_f32_e32 v3, v3
	v_cvt_pk_bf16_f32 v2, v10, v2
	v_add_f32_e32 v6, 1.0, v6
	v_rcp_f32_e32 v6, v6
	v_add_f32_e32 v3, 1.0, v3
	v_rcp_f32_e32 v3, v3
	v_mul_f32_e32 v6, v8, v6
	v_mul_f32_e32 v8, v6, v4
	v_mul_f32_e32 v4, 0xbfb8aa3b, v17
	v_mul_f32_e32 v6, 0xbfb8aa3b, v9
	v_exp_f32_e32 v4, v4
	v_exp_f32_e32 v6, v6
	v_mul_f32_e32 v3, v16, v3
	v_mul_f32_e32 v3, v3, v12
	v_add_f32_e32 v4, 1.0, v4
	v_add_f32_e32 v6, 1.0, v6
	v_rcp_f32_e32 v4, v4
	v_rcp_f32_e32 v6, v6
	v_mul_f32_e32 v4, v17, v4
	v_mul_f32_e32 v6, v9, v6
	v_mul_f32_e32 v4, v4, v13
	v_mul_f32_e32 v5, v6, v5
	v_lshl_add_u64 v[6:7], v[166:167], 0, v[160:161]
	v_cvt_pk_bf16_f32 v3, v3, v4
	v_cvt_pk_bf16_f32 v4, v14, v11
	v_cvt_pk_bf16_f32 v5, v8, v5
	global_store_dwordx4 v[6:7], v[2:5], off
	s_cbranch_vccz .LBB0_105
	s_waitcnt vmcnt(0)
	v_readlane_b32 s50, v254, 28
	v_readlane_b32 s56, v254, 30
	v_readlane_b32 s60, v254, 39
	s_cmpk_gt_u32 s4, 0xff
	v_readlane_b32 s51, v254, 29
	v_readlane_b32 s57, v254, 31
	v_readlane_b32 s61, v254, 40
	s_mov_b64 s[58:59], s[84:85]
	s_cbranch_scc1 .LBB0_112
	s_barrier

.LBB0_181:
	s_add_u32 s59, s26, 0x100
	s_addc_u32 s60, s27, 0
	s_add_u32 s38, s38, 0xc000
	v_mov_b32_e32 v2, 0
	s_addc_u32 s39, s39, 0
	s_mov_b32 s61, -2
	v_mov_b32_e32 v3, v2
	v_mov_b32_e32 v4, v2
	v_mov_b32_e32 v5, v2
	v_mov_b32_e32 v6, v2
	v_mov_b32_e32 v7, v2
	v_mov_b32_e32 v8, v2
	v_mov_b32_e32 v9, v2
	v_mov_b32_e32 v18, v2
	v_mov_b32_e32 v19, v2
	v_mov_b32_e32 v20, v2
	v_mov_b32_e32 v21, v2
	v_mov_b32_e32 v22, v2
	v_mov_b32_e32 v23, v2
	v_mov_b32_e32 v24, v2
	v_mov_b32_e32 v25, v2
	v_mov_b32_e32 v34, v2
	v_mov_b32_e32 v35, v2
	v_mov_b32_e32 v36, v2
	v_mov_b32_e32 v37, v2
	v_mov_b32_e32 v38, v2
	v_mov_b32_e32 v39, v2
	v_mov_b32_e32 v40, v2
	v_mov_b32_e32 v41, v2
	v_mov_b32_e32 v50, v2
	v_mov_b32_e32 v51, v2
	v_mov_b32_e32 v52, v2
	v_mov_b32_e32 v53, v2
	v_mov_b32_e32 v54, v2
	v_mov_b32_e32 v55, v2
	v_mov_b32_e32 v56, v2
	v_mov_b32_e32 v57, v2
	v_mov_b32_e32 v10, v2
	v_mov_b32_e32 v11, v2
	v_mov_b32_e32 v12, v2
	v_mov_b32_e32 v13, v2
	v_mov_b32_e32 v14, v2
	v_mov_b32_e32 v15, v2
	v_mov_b32_e32 v16, v2
	v_mov_b32_e32 v17, v2
	v_mov_b32_e32 v26, v2
	v_mov_b32_e32 v27, v2
	v_mov_b32_e32 v28, v2
	v_mov_b32_e32 v29, v2
	v_mov_b32_e32 v30, v2
	v_mov_b32_e32 v31, v2
	v_mov_b32_e32 v32, v2
	v_mov_b32_e32 v33, v2
	v_mov_b32_e32 v42, v2
	v_mov_b32_e32 v43, v2
	v_mov_b32_e32 v44, v2
	v_mov_b32_e32 v45, v2
	v_mov_b32_e32 v46, v2
	v_mov_b32_e32 v47, v2
	v_mov_b32_e32 v48, v2
	v_mov_b32_e32 v49, v2
	v_mov_b32_e32 v58, v2
	v_mov_b32_e32 v59, v2
	v_mov_b32_e32 v60, v2
	v_mov_b32_e32 v61, v2
	v_mov_b32_e32 v62, v2
	v_mov_b32_e32 v63, v2
	v_mov_b32_e32 v64, v2
	v_mov_b32_e32 v65, v2
	v_mov_b32_e32 v66, v2
	v_mov_b32_e32 v67, v2
	v_mov_b32_e32 v68, v2
	v_mov_b32_e32 v69, v2
	v_mov_b32_e32 v70, v2
	v_mov_b32_e32 v71, v2
	v_mov_b32_e32 v72, v2
	v_mov_b32_e32 v73, v2
	v_mov_b32_e32 v82, v2
	v_mov_b32_e32 v83, v2
	v_mov_b32_e32 v84, v2
	v_mov_b32_e32 v85, v2
	v_mov_b32_e32 v86, v2
	v_mov_b32_e32 v87, v2
	v_mov_b32_e32 v88, v2
	v_mov_b32_e32 v89, v2
	v_mov_b32_e32 v98, v2
	v_mov_b32_e32 v99, v2
	v_mov_b32_e32 v100, v2
	v_mov_b32_e32 v101, v2
	v_mov_b32_e32 v102, v2
	v_mov_b32_e32 v103, v2
	v_mov_b32_e32 v104, v2
	v_mov_b32_e32 v105, v2
	v_mov_b32_e32 v114, v2
	v_mov_b32_e32 v115, v2
	v_mov_b32_e32 v116, v2
	v_mov_b32_e32 v117, v2
	v_mov_b32_e32 v118, v2
	v_mov_b32_e32 v119, v2
	v_mov_b32_e32 v120, v2
	v_mov_b32_e32 v121, v2
	v_mov_b32_e32 v74, v2
	v_mov_b32_e32 v75, v2
	v_mov_b32_e32 v76, v2
	v_mov_b32_e32 v77, v2
	v_mov_b32_e32 v78, v2
	v_mov_b32_e32 v79, v2
	v_mov_b32_e32 v80, v2
	v_mov_b32_e32 v81, v2
	v_mov_b32_e32 v90, v2
	v_mov_b32_e32 v91, v2
	v_mov_b32_e32 v92, v2
	v_mov_b32_e32 v93, v2
	v_mov_b32_e32 v94, v2
	v_mov_b32_e32 v95, v2
	v_mov_b32_e32 v96, v2
	v_mov_b32_e32 v97, v2
	v_mov_b32_e32 v106, v2
	v_mov_b32_e32 v107, v2
	v_mov_b32_e32 v108, v2
	v_mov_b32_e32 v109, v2
	v_mov_b32_e32 v110, v2
	v_mov_b32_e32 v111, v2
	v_mov_b32_e32 v112, v2
	v_mov_b32_e32 v113, v2
	v_mov_b32_e32 v122, v2
	v_mov_b32_e32 v123, v2
	v_mov_b32_e32 v124, v2
	v_mov_b32_e32 v125, v2
	v_mov_b32_e32 v126, v2
	v_mov_b32_e32 v127, v2
	v_mov_b32_e32 v128, v2
	v_mov_b32_e32 v129, v2
	v_add_u32_e32 v134, 0x10000, v155
.LBB0_182:
	s_add_u32 s26, s38, 0x4000
	s_addc_u32 s27, s39, 0
	s_cmpk_eq_i32 s61, 0x54
	s_cselect_b32 s48, s0, s26
	s_cselect_b32 s49, s1, s27
	s_cselect_b32 s26, s24, s59
	s_cselect_b32 s27, s25, s60
	s_add_u32 s42, s48, 0x8000
	s_addc_u32 s43, s49, 0
	s_add_i32 s62, 0, 0x10000
	ds_read_b128 v[148:151], v134
	ds_read_b128 v[158:161], v134 offset:1024
	ds_read_b128 v[162:165], v134 offset:2048
	ds_read_b128 v[180:183], v134 offset:3072
	s_add_i32 m0, s7, 0xc000
	ds_read_b128 v[184:187], v157
	ds_read_b128 v[188:191], v157 offset:1024
	ds_read_b128 v[192:195], v157 offset:2048
	ds_read_b128 v[196:199], v157 offset:3072
	ds_read_b128 v[200:203], v157 offset:4096
	ds_read_b128 v[204:207], v157 offset:5120
	ds_read_b128 v[208:211], v157 offset:6144
	ds_read_b128 v[212:215], v157 offset:7168
	global_load_lds_dwordx4 v144, s[38:39]
	s_add_i32 m0, s7, 0xe000
	s_nop 0
	global_load_lds_dwordx4 v146, s[38:39]
	s_waitcnt lgkmcnt(8)
	s_barrier
	s_waitcnt lgkmcnt(0)
	s_setprio 1
	s_waitcnt lgkmcnt(0)
	v_mfma_f32_16x16x32_bf16 v[126:129], v[148:151], v[184:187], v[126:129]
	v_mfma_f32_16x16x32_bf16 v[122:125], v[162:165], v[184:187], v[122:125]
	v_mfma_f32_16x16x32_bf16 v[110:113], v[148:151], v[192:195], v[110:113]
	v_mfma_f32_16x16x32_bf16 v[106:109], v[162:165], v[192:195], v[106:109]
	v_mfma_f32_16x16x32_bf16 v[94:97], v[148:151], v[200:203], v[94:97]
	v_mfma_f32_16x16x32_bf16 v[90:93], v[162:165], v[200:203], v[90:93]
	v_mfma_f32_16x16x32_bf16 v[78:81], v[148:151], v[208:211], v[78:81]
	v_mfma_f32_16x16x32_bf16 v[74:77], v[162:165], v[208:211], v[74:77]
	v_mfma_f32_16x16x32_bf16 v[126:129], v[158:161], v[188:191], v[126:129]
	v_mfma_f32_16x16x32_bf16 v[122:125], v[180:183], v[188:191], v[122:125]
	v_mfma_f32_16x16x32_bf16 v[110:113], v[158:161], v[196:199], v[110:113]
	v_mfma_f32_16x16x32_bf16 v[106:109], v[180:183], v[196:199], v[106:109]
	v_mfma_f32_16x16x32_bf16 v[94:97], v[158:161], v[204:207], v[94:97]
	v_mfma_f32_16x16x32_bf16 v[90:93], v[180:183], v[204:207], v[90:93]
	v_mfma_f32_16x16x32_bf16 v[78:81], v[158:161], v[212:215], v[78:81]
	v_mfma_f32_16x16x32_bf16 v[74:77], v[180:183], v[212:215], v[74:77]
	s_setprio 0
	s_barrier
	s_add_i32 s64, 0, 0x14000
	s_add_i32 s62, s62, s6
	ds_read_b128 v[216:219], v134 offset:16384
	ds_read_b128 v[220:223], v134 offset:17408
	ds_read_b128 v[224:227], v134 offset:18432
	ds_read_b128 v[228:231], v134 offset:19456
	s_mov_b32 m0, s62
	global_load_lds_dwordx4 v0, s[26:27]
	s_add_i32 m0, s62, 0x2000
	s_nop 0
	global_load_lds_dwordx4 v138, s[26:27]
	s_barrier
	s_waitcnt lgkmcnt(0)
	s_setprio 1
	s_waitcnt lgkmcnt(0)
	v_mfma_f32_16x16x32_bf16 v[118:121], v[216:219], v[184:187], v[118:121]
	v_mfma_f32_16x16x32_bf16 v[114:117], v[224:227], v[184:187], v[114:117]
	v_mfma_f32_16x16x32_bf16 v[102:105], v[216:219], v[192:195], v[102:105]
	v_mfma_f32_16x16x32_bf16 v[98:101], v[224:227], v[192:195], v[98:101]
	v_mfma_f32_16x16x32_bf16 v[86:89], v[216:219], v[200:203], v[86:89]
	v_mfma_f32_16x16x32_bf16 v[82:85], v[224:227], v[200:203], v[82:85]
	v_mfma_f32_16x16x32_bf16 v[70:73], v[216:219], v[208:211], v[70:73]
	v_mfma_f32_16x16x32_bf16 v[66:69], v[224:227], v[208:211], v[66:69]
	v_mfma_f32_16x16x32_bf16 v[118:121], v[220:223], v[188:191], v[118:121]
	v_mfma_f32_16x16x32_bf16 v[114:117], v[228:231], v[188:191], v[114:117]
	v_mfma_f32_16x16x32_bf16 v[102:105], v[220:223], v[196:199], v[102:105]
	v_mfma_f32_16x16x32_bf16 v[98:101], v[228:231], v[196:199], v[98:101]
	v_mfma_f32_16x16x32_bf16 v[86:89], v[220:223], v[204:207], v[86:89]
	v_mfma_f32_16x16x32_bf16 v[82:85], v[228:231], v[204:207], v[82:85]
	v_mfma_f32_16x16x32_bf16 v[70:73], v[220:223], v[212:215], v[70:73]
	v_mfma_f32_16x16x32_bf16 v[66:69], v[228:231], v[212:215], v[66:69]
	s_setprio 0
	s_mov_b32 m0, s7
	s_barrier
	ds_read_b128 v[184:187], v157 offset:16384
	ds_read_b128 v[188:191], v157 offset:17408
	ds_read_b128 v[192:195], v157 offset:18432
	ds_read_b128 v[196:199], v157 offset:19456
	ds_read_b128 v[200:203], v157 offset:20480
	ds_read_b128 v[204:207], v157 offset:21504
	ds_read_b128 v[208:211], v157 offset:22528
	ds_read_b128 v[212:215], v157 offset:23552
	global_load_lds_dwordx4 v142, s[48:49]
	s_mov_b32 m0, s14
	s_nop 0
	global_load_lds_dwordx4 v140, s[48:49]
	s_barrier
	s_waitcnt lgkmcnt(0)
	s_setprio 1
	s_waitcnt lgkmcnt(0)
	v_mfma_f32_16x16x32_bf16 v[62:65], v[148:151], v[184:187], v[62:65]
	v_mfma_f32_16x16x32_bf16 v[58:61], v[162:165], v[184:187], v[58:61]
	v_mfma_f32_16x16x32_bf16 v[46:49], v[148:151], v[192:195], v[46:49]
	v_mfma_f32_16x16x32_bf16 v[42:45], v[162:165], v[192:195], v[42:45]
	v_mfma_f32_16x16x32_bf16 v[30:33], v[148:151], v[200:203], v[30:33]
	v_mfma_f32_16x16x32_bf16 v[26:29], v[162:165], v[200:203], v[26:29]
	v_mfma_f32_16x16x32_bf16 v[14:17], v[148:151], v[208:211], v[14:17]
	v_mfma_f32_16x16x32_bf16 v[10:13], v[162:165], v[208:211], v[10:13]
	v_mfma_f32_16x16x32_bf16 v[62:65], v[158:161], v[188:191], v[62:65]
	v_mfma_f32_16x16x32_bf16 v[58:61], v[180:183], v[188:191], v[58:61]
	v_mfma_f32_16x16x32_bf16 v[46:49], v[158:161], v[196:199], v[46:49]
	v_mfma_f32_16x16x32_bf16 v[42:45], v[180:183], v[196:199], v[42:45]
	v_mfma_f32_16x16x32_bf16 v[30:33], v[158:161], v[204:207], v[30:33]
	v_mfma_f32_16x16x32_bf16 v[26:29], v[180:183], v[204:207], v[26:29]
	v_mfma_f32_16x16x32_bf16 v[14:17], v[158:161], v[212:215], v[14:17]
	v_mfma_f32_16x16x32_bf16 v[10:13], v[180:183], v[212:215], v[10:13]
	s_setprio 0
	s_barrier
	s_add_u32 s62, s26, 0x160000
	s_addc_u32 s63, s27, 0
	s_add_i32 s64, s64, s6
	s_mov_b32 m0, s64
	s_nop 0
	global_load_lds_dwordx4 v0, s[62:63]
	s_add_i32 m0, s64, 0x2000
	s_nop 0
	global_load_lds_dwordx4 v138, s[62:63]
	s_waitcnt vmcnt(6)
	s_barrier
	s_setprio 1
	v_mfma_f32_16x16x32_bf16 v[54:57], v[216:219], v[184:187], v[54:57]
	v_mfma_f32_16x16x32_bf16 v[50:53], v[224:227], v[184:187], v[50:53]
	v_mfma_f32_16x16x32_bf16 v[38:41], v[216:219], v[192:195], v[38:41]
	v_mfma_f32_16x16x32_bf16 v[34:37], v[224:227], v[192:195], v[34:37]
	v_mfma_f32_16x16x32_bf16 v[22:25], v[216:219], v[200:203], v[22:25]
	v_mfma_f32_16x16x32_bf16 v[18:21], v[224:227], v[200:203], v[18:21]
	v_mfma_f32_16x16x32_bf16 v[6:9], v[216:219], v[208:211], v[6:9]
	v_mfma_f32_16x16x32_bf16 v[2:5], v[224:227], v[208:211], v[2:5]
	v_mfma_f32_16x16x32_bf16 v[54:57], v[220:223], v[188:191], v[54:57]
	v_mfma_f32_16x16x32_bf16 v[50:53], v[228:231], v[188:191], v[50:53]
	v_mfma_f32_16x16x32_bf16 v[38:41], v[220:223], v[196:199], v[38:41]
	v_mfma_f32_16x16x32_bf16 v[34:37], v[228:231], v[196:199], v[34:37]
	v_mfma_f32_16x16x32_bf16 v[22:25], v[220:223], v[204:207], v[22:25]
	v_mfma_f32_16x16x32_bf16 v[18:21], v[228:231], v[204:207], v[18:21]
	v_mfma_f32_16x16x32_bf16 v[6:9], v[220:223], v[212:215], v[6:9]
	v_mfma_f32_16x16x32_bf16 v[2:5], v[228:231], v[212:215], v[2:5]
	s_setprio 0
	s_add_i32 s62, 0, 0x18000
	s_barrier
	ds_read_b128 v[148:151], v134 offset:32768
	ds_read_b128 v[158:161], v134 offset:33792
	ds_read_b128 v[162:165], v134 offset:34816
	ds_read_b128 v[180:183], v134 offset:35840
	s_add_u32 s48, s48, 0x4000
	s_addc_u32 s49, s49, 0
	s_mov_b32 m0, s50
	ds_read_b128 v[184:187], v157 offset:32768
	ds_read_b128 v[188:191], v157 offset:33792
	ds_read_b128 v[192:195], v157 offset:34816
	ds_read_b128 v[196:199], v157 offset:35840
	ds_read_b128 v[200:203], v157 offset:36864
	ds_read_b128 v[204:207], v157 offset:37888
	ds_read_b128 v[208:211], v157 offset:38912
	ds_read_b128 v[212:215], v157 offset:39936
	global_load_lds_dwordx4 v142, s[48:49]
	s_mov_b32 m0, s51
	s_nop 0
	global_load_lds_dwordx4 v140, s[48:49]
	s_waitcnt lgkmcnt(8)
	s_barrier
	s_waitcnt lgkmcnt(0)
	s_setprio 1
	s_waitcnt lgkmcnt(0)
	v_mfma_f32_16x16x32_bf16 v[126:129], v[148:151], v[184:187], v[126:129]
	v_mfma_f32_16x16x32_bf16 v[122:125], v[162:165], v[184:187], v[122:125]
	v_mfma_f32_16x16x32_bf16 v[110:113], v[148:151], v[192:195], v[110:113]
	v_mfma_f32_16x16x32_bf16 v[106:109], v[162:165], v[192:195], v[106:109]
	v_mfma_f32_16x16x32_bf16 v[94:97], v[148:151], v[200:203], v[94:97]
	v_mfma_f32_16x16x32_bf16 v[90:93], v[162:165], v[200:203], v[90:93]
	v_mfma_f32_16x16x32_bf16 v[78:81], v[148:151], v[208:211], v[78:81]
	v_mfma_f32_16x16x32_bf16 v[74:77], v[162:165], v[208:211], v[74:77]
	v_mfma_f32_16x16x32_bf16 v[126:129], v[158:161], v[188:191], v[126:129]
	v_mfma_f32_16x16x32_bf16 v[122:125], v[180:183], v[188:191], v[122:125]
	v_mfma_f32_16x16x32_bf16 v[110:113], v[158:161], v[196:199], v[110:113]
	v_mfma_f32_16x16x32_bf16 v[106:109], v[180:183], v[196:199], v[106:109]
	v_mfma_f32_16x16x32_bf16 v[94:97], v[158:161], v[204:207], v[94:97]
	v_mfma_f32_16x16x32_bf16 v[90:93], v[180:183], v[204:207], v[90:93]
	v_mfma_f32_16x16x32_bf16 v[78:81], v[158:161], v[212:215], v[78:81]
	v_mfma_f32_16x16x32_bf16 v[74:77], v[180:183], v[212:215], v[74:77]
	s_setprio 0
	s_barrier
	s_add_i32 s48, 0, 0x1c000
	s_add_i32 s49, s62, s6
	s_add_u32 s100, s26, s10
	s_addc_u32 s101, s27, s11
	s_mov_b32 m0, s49
	ds_read_b128 v[216:219], v134 offset:49152
	ds_read_b128 v[220:223], v134 offset:50176
	ds_read_b128 v[224:227], v134 offset:51200
	ds_read_b128 v[228:231], v134 offset:52224
	global_load_lds_dwordx4 v0, s[100:101]
	s_add_u32 s100, s26, s10
	s_addc_u32 s101, s27, s11
	s_add_i32 m0, s49, 0x2000
	s_nop 0
	global_load_lds_dwordx4 v138, s[100:101]
	s_barrier
	s_waitcnt lgkmcnt(0)
	s_setprio 1
	s_waitcnt lgkmcnt(0)
	v_mfma_f32_16x16x32_bf16 v[118:121], v[216:219], v[184:187], v[118:121]
	v_mfma_f32_16x16x32_bf16 v[114:117], v[224:227], v[184:187], v[114:117]
	v_mfma_f32_16x16x32_bf16 v[102:105], v[216:219], v[192:195], v[102:105]
	v_mfma_f32_16x16x32_bf16 v[98:101], v[224:227], v[192:195], v[98:101]
	v_mfma_f32_16x16x32_bf16 v[86:89], v[216:219], v[200:203], v[86:89]
	v_mfma_f32_16x16x32_bf16 v[82:85], v[224:227], v[200:203], v[82:85]
	v_mfma_f32_16x16x32_bf16 v[70:73], v[216:219], v[208:211], v[70:73]
	v_mfma_f32_16x16x32_bf16 v[66:69], v[224:227], v[208:211], v[66:69]
	v_mfma_f32_16x16x32_bf16 v[118:121], v[220:223], v[188:191], v[118:121]
	v_mfma_f32_16x16x32_bf16 v[114:117], v[228:231], v[188:191], v[114:117]
	v_mfma_f32_16x16x32_bf16 v[102:105], v[220:223], v[196:199], v[102:105]
	v_mfma_f32_16x16x32_bf16 v[98:101], v[228:231], v[196:199], v[98:101]
	v_mfma_f32_16x16x32_bf16 v[86:89], v[220:223], v[204:207], v[86:89]
	v_mfma_f32_16x16x32_bf16 v[82:85], v[228:231], v[204:207], v[82:85]
	v_mfma_f32_16x16x32_bf16 v[70:73], v[220:223], v[212:215], v[70:73]
	v_mfma_f32_16x16x32_bf16 v[66:69], v[228:231], v[212:215], v[66:69]
	s_setprio 0
	s_mov_b32 m0, s52
	s_barrier
	ds_read_b128 v[184:187], v157 offset:49152
	ds_read_b128 v[188:191], v157 offset:50176
	ds_read_b128 v[192:195], v157 offset:51200
	ds_read_b128 v[196:199], v157 offset:52224
	ds_read_b128 v[200:203], v157 offset:53248
	ds_read_b128 v[204:207], v157 offset:54272
	ds_read_b128 v[208:211], v157 offset:55296
	ds_read_b128 v[212:215], v157 offset:56320
	global_load_lds_dwordx4 v142, s[42:43]
	s_mov_b32 m0, s53
	s_nop 0
	global_load_lds_dwordx4 v140, s[42:43]
	s_barrier
	s_waitcnt lgkmcnt(0)
	s_setprio 1
	s_waitcnt lgkmcnt(0)
	v_mfma_f32_16x16x32_bf16 v[62:65], v[148:151], v[184:187], v[62:65]
	v_mfma_f32_16x16x32_bf16 v[58:61], v[162:165], v[184:187], v[58:61]
	v_mfma_f32_16x16x32_bf16 v[46:49], v[148:151], v[192:195], v[46:49]
	v_mfma_f32_16x16x32_bf16 v[42:45], v[162:165], v[192:195], v[42:45]
	v_mfma_f32_16x16x32_bf16 v[30:33], v[148:151], v[200:203], v[30:33]
	v_mfma_f32_16x16x32_bf16 v[26:29], v[162:165], v[200:203], v[26:29]
	v_mfma_f32_16x16x32_bf16 v[14:17], v[148:151], v[208:211], v[14:17]
	v_mfma_f32_16x16x32_bf16 v[10:13], v[162:165], v[208:211], v[10:13]
	v_mfma_f32_16x16x32_bf16 v[62:65], v[158:161], v[188:191], v[62:65]
	v_mfma_f32_16x16x32_bf16 v[58:61], v[180:183], v[188:191], v[58:61]
	v_mfma_f32_16x16x32_bf16 v[46:49], v[158:161], v[196:199], v[46:49]
	v_mfma_f32_16x16x32_bf16 v[42:45], v[180:183], v[196:199], v[42:45]
	v_mfma_f32_16x16x32_bf16 v[30:33], v[158:161], v[204:207], v[30:33]
	v_mfma_f32_16x16x32_bf16 v[26:29], v[180:183], v[204:207], v[26:29]
	v_mfma_f32_16x16x32_bf16 v[14:17], v[158:161], v[212:215], v[14:17]
	v_mfma_f32_16x16x32_bf16 v[10:13], v[180:183], v[212:215], v[10:13]
	s_setprio 0
	s_barrier
	s_add_u32 s26, s26, 0x160080
	s_addc_u32 s27, s27, 0
	s_add_i32 s42, s48, s6
	s_mov_b32 m0, s42
	s_nop 0
	global_load_lds_dwordx4 v0, s[26:27]
	s_add_i32 m0, s42, 0x2000
	s_nop 0
	global_load_lds_dwordx4 v138, s[26:27]
	s_waitcnt vmcnt(6)
	s_barrier
	s_setprio 1
	v_mfma_f32_16x16x32_bf16 v[54:57], v[216:219], v[184:187], v[54:57]
	v_mfma_f32_16x16x32_bf16 v[50:53], v[224:227], v[184:187], v[50:53]
	v_mfma_f32_16x16x32_bf16 v[38:41], v[216:219], v[192:195], v[38:41]
	v_mfma_f32_16x16x32_bf16 v[34:37], v[224:227], v[192:195], v[34:37]
	v_mfma_f32_16x16x32_bf16 v[22:25], v[216:219], v[200:203], v[22:25]
	v_mfma_f32_16x16x32_bf16 v[18:21], v[224:227], v[200:203], v[18:21]
	v_mfma_f32_16x16x32_bf16 v[6:9], v[216:219], v[208:211], v[6:9]
	v_mfma_f32_16x16x32_bf16 v[2:5], v[224:227], v[208:211], v[2:5]
	v_mfma_f32_16x16x32_bf16 v[54:57], v[220:223], v[188:191], v[54:57]
	v_mfma_f32_16x16x32_bf16 v[50:53], v[228:231], v[188:191], v[50:53]
	v_mfma_f32_16x16x32_bf16 v[38:41], v[220:223], v[196:199], v[38:41]
	v_mfma_f32_16x16x32_bf16 v[34:37], v[228:231], v[196:199], v[34:37]
	v_mfma_f32_16x16x32_bf16 v[22:25], v[220:223], v[204:207], v[22:25]
	v_mfma_f32_16x16x32_bf16 v[18:21], v[228:231], v[204:207], v[18:21]
	v_mfma_f32_16x16x32_bf16 v[6:9], v[220:223], v[212:215], v[6:9]
	v_mfma_f32_16x16x32_bf16 v[2:5], v[228:231], v[212:215], v[2:5]
	s_setprio 0
	s_add_i32 s61, s61, 2
	s_add_u32 s59, s59, 0x100
	s_addc_u32 s60, s60, 0
	s_add_u32 s38, s38, 0x10000
	s_addc_u32 s39, s39, 0
	s_cmpk_gt_u32 s61, 0x55
	s_barrier
	s_cbranch_scc0 .LBB0_182
	v_lshl_add_u32 v152, s58, 8, v154
	v_lshl_or_b32 v150, s57, 8, v156
	v_ashrrev_i32_e32 v153, 31, v152
	v_ashrrev_i32_e32 v151, 31, v150
	v_lshlrev_b64 v[134:135], 11, v[152:153]
	v_lshl_add_u64 v[134:135], v[134:135], 0, v[150:151]
	v_lshlrev_b64 v[148:149], 2, v[134:135]
	v_lshl_add_u64 v[134:135], s[22:23], 0, v[148:149]
	v_lshl_add_u64 v[158:159], s[76:77], 0, v[148:149]
	v_readlane_b32 s62, v254, 34
	v_readlane_b32 s64, v254, 36
	v_readlane_b32 s60, v254, 39
	s_and_b64 vcc, exec, s[40:41]
	s_mov_b32 s57, s55
	s_mov_b32 s58, s56
	s_mov_b64 s[38:39], s[0:1]
	v_readlane_b32 s63, v254, 35
	v_readlane_b32 s65, v254, 37
	v_readlane_b32 s61, v254, 40
	v_mov_b64_e32 v[162:163], v[134:135]
	v_mov_b64_e32 v[152:153], v[158:159]
	global_load_dwordx4 v[180:183], v[162:163], off
	global_load_dwordx4 v[184:187], v[162:163], off offset:16
	global_load_dwordx4 v[188:191], v[162:163], off offset:512
	global_load_dwordx4 v[192:195], v[162:163], off offset:528
	s_mov_b64 s[26:27], 0x20000
	v_lshl_add_u64 v[164:165], v[134:135], 0, s[26:27]
	v_lshl_add_u64 v[160:161], v[158:159], 0, s[26:27]
	global_load_dwordx4 v[196:199], v[164:165], off
	global_load_dwordx4 v[200:203], v[164:165], off offset:16
	global_load_dwordx4 v[204:207], v[164:165], off offset:512
	global_load_dwordx4 v[208:211], v[164:165], off offset:528
	s_mov_b64 s[26:27], 0x40000
	v_lshl_add_u64 v[150:151], v[134:135], 0, s[26:27]
	v_lshl_add_u64 v[148:149], v[158:159], 0, s[26:27]
	global_load_dwordx4 v[212:215], v[150:151], off
	global_load_dwordx4 v[216:219], v[150:151], off offset:16
	global_load_dwordx4 v[220:223], v[150:151], off offset:512
	global_load_dwordx4 v[224:227], v[150:151], off offset:528
	s_waitcnt vmcnt(8)
	v_pk_fma_f32 v[126:127], v[126:127], 0.5, v[180:181] op_sel_hi:[1,0,1]
	v_pk_fma_f32 v[128:129], v[128:129], 0.5, v[182:183] op_sel_hi:[1,0,1]
	v_pk_fma_f32 v[122:123], v[122:123], 0.5, v[184:185] op_sel_hi:[1,0,1]
	v_pk_fma_f32 v[124:125], v[124:125], 0.5, v[186:187] op_sel_hi:[1,0,1]
	v_pk_fma_f32 v[118:119], v[118:119], 0.5, v[188:189] op_sel_hi:[1,0,1]
	v_pk_fma_f32 v[120:121], v[120:121], 0.5, v[190:191] op_sel_hi:[1,0,1]
	v_pk_fma_f32 v[114:115], v[114:115], 0.5, v[192:193] op_sel_hi:[1,0,1]
	v_pk_fma_f32 v[116:117], v[116:117], 0.5, v[194:195] op_sel_hi:[1,0,1]
	global_store_dwordx4 v[152:153], v[126:129], off
	global_store_dwordx4 v[152:153], v[122:125], off offset:16
	global_store_dwordx4 v[152:153], v[118:121], off offset:512
	global_store_dwordx4 v[152:153], v[114:117], off offset:528
	s_mov_b64 s[26:27], 0x60000
	v_lshl_add_u64 v[228:229], v[134:135], 0, s[26:27]
	v_lshl_add_u64 v[230:231], v[158:159], 0, s[26:27]
	global_load_dwordx4 v[180:183], v[228:229], off
	global_load_dwordx4 v[184:187], v[228:229], off offset:16
	global_load_dwordx4 v[188:191], v[228:229], off offset:512
	global_load_dwordx4 v[192:195], v[228:229], off offset:528
	s_waitcnt vmcnt(12)
	v_pk_fma_f32 v[110:111], v[110:111], 0.5, v[196:197] op_sel_hi:[1,0,1]
	v_pk_fma_f32 v[112:113], v[112:113], 0.5, v[198:199] op_sel_hi:[1,0,1]
	v_pk_fma_f32 v[106:107], v[106:107], 0.5, v[200:201] op_sel_hi:[1,0,1]
	v_pk_fma_f32 v[108:109], v[108:109], 0.5, v[202:203] op_sel_hi:[1,0,1]
	v_pk_fma_f32 v[102:103], v[102:103], 0.5, v[204:205] op_sel_hi:[1,0,1]
	v_pk_fma_f32 v[104:105], v[104:105], 0.5, v[206:207] op_sel_hi:[1,0,1]
	v_pk_fma_f32 v[98:99], v[98:99], 0.5, v[208:209] op_sel_hi:[1,0,1]
	v_pk_fma_f32 v[100:101], v[100:101], 0.5, v[210:211] op_sel_hi:[1,0,1]
	global_store_dwordx4 v[160:161], v[110:113], off
	global_store_dwordx4 v[160:161], v[106:109], off offset:16
	global_store_dwordx4 v[160:161], v[102:105], off offset:512
	global_store_dwordx4 v[160:161], v[98:101], off offset:528
	s_mov_b64 s[26:27], 0x100000
	v_lshl_add_u64 v[162:163], v[134:135], 0, s[26:27]
	v_lshl_add_u64 v[152:153], v[158:159], 0, s[26:27]
	global_load_dwordx4 v[196:199], v[162:163], off
	global_load_dwordx4 v[200:203], v[162:163], off offset:16
	global_load_dwordx4 v[204:207], v[162:163], off offset:512
	global_load_dwordx4 v[208:211], v[162:163], off offset:528
	s_waitcnt vmcnt(16)
	v_pk_fma_f32 v[94:95], v[94:95], 0.5, v[212:213] op_sel_hi:[1,0,1]
	v_pk_fma_f32 v[96:97], v[96:97], 0.5, v[214:215] op_sel_hi:[1,0,1]
	v_pk_fma_f32 v[90:91], v[90:91], 0.5, v[216:217] op_sel_hi:[1,0,1]
	v_pk_fma_f32 v[92:93], v[92:93], 0.5, v[218:219] op_sel_hi:[1,0,1]
	v_pk_fma_f32 v[86:87], v[86:87], 0.5, v[220:221] op_sel_hi:[1,0,1]
	v_pk_fma_f32 v[88:89], v[88:89], 0.5, v[222:223] op_sel_hi:[1,0,1]
	v_pk_fma_f32 v[82:83], v[82:83], 0.5, v[224:225] op_sel_hi:[1,0,1]
	v_pk_fma_f32 v[84:85], v[84:85], 0.5, v[226:227] op_sel_hi:[1,0,1]
	global_store_dwordx4 v[148:149], v[94:97], off
	global_store_dwordx4 v[148:149], v[90:93], off offset:16
	global_store_dwordx4 v[148:149], v[86:89], off offset:512
	global_store_dwordx4 v[148:149], v[82:85], off offset:528
	s_mov_b64 s[26:27], 0x120000
	v_lshl_add_u64 v[164:165], v[134:135], 0, s[26:27]
	v_lshl_add_u64 v[160:161], v[158:159], 0, s[26:27]
	global_load_dwordx4 v[212:215], v[164:165], off
	global_load_dwordx4 v[216:219], v[164:165], off offset:16
	global_load_dwordx4 v[220:223], v[164:165], off offset:512
	global_load_dwordx4 v[224:227], v[164:165], off offset:528
	s_waitcnt vmcnt(16)
	v_pk_fma_f32 v[78:79], v[78:79], 0.5, v[180:181] op_sel_hi:[1,0,1]
	v_pk_fma_f32 v[80:81], v[80:81], 0.5, v[182:183] op_sel_hi:[1,0,1]
	v_pk_fma_f32 v[74:75], v[74:75], 0.5, v[184:185] op_sel_hi:[1,0,1]
	v_pk_fma_f32 v[76:77], v[76:77], 0.5, v[186:187] op_sel_hi:[1,0,1]
	v_pk_fma_f32 v[70:71], v[70:71], 0.5, v[188:189] op_sel_hi:[1,0,1]
	v_pk_fma_f32 v[72:73], v[72:73], 0.5, v[190:191] op_sel_hi:[1,0,1]
	v_pk_fma_f32 v[66:67], v[66:67], 0.5, v[192:193] op_sel_hi:[1,0,1]
	v_pk_fma_f32 v[68:69], v[68:69], 0.5, v[194:195] op_sel_hi:[1,0,1]
	global_store_dwordx4 v[230:231], v[78:81], off
	global_store_dwordx4 v[230:231], v[74:77], off offset:16
	global_store_dwordx4 v[230:231], v[70:73], off offset:512
	global_store_dwordx4 v[230:231], v[66:69], off offset:528
	s_mov_b64 s[26:27], 0x140000
	v_lshl_add_u64 v[150:151], v[134:135], 0, s[26:27]
	v_lshl_add_u64 v[148:149], v[158:159], 0, s[26:27]
	global_load_dwordx4 v[180:183], v[150:151], off
	global_load_dwordx4 v[184:187], v[150:151], off offset:16
	global_load_dwordx4 v[188:191], v[150:151], off offset:512
	global_load_dwordx4 v[192:195], v[150:151], off offset:528
	s_waitcnt vmcnt(16)
	v_pk_fma_f32 v[62:63], v[62:63], 0.5, v[196:197] op_sel_hi:[1,0,1]
	v_pk_fma_f32 v[64:65], v[64:65], 0.5, v[198:199] op_sel_hi:[1,0,1]
	v_pk_fma_f32 v[58:59], v[58:59], 0.5, v[200:201] op_sel_hi:[1,0,1]
	v_pk_fma_f32 v[60:61], v[60:61], 0.5, v[202:203] op_sel_hi:[1,0,1]
	v_pk_fma_f32 v[54:55], v[54:55], 0.5, v[204:205] op_sel_hi:[1,0,1]
	v_pk_fma_f32 v[56:57], v[56:57], 0.5, v[206:207] op_sel_hi:[1,0,1]
	v_pk_fma_f32 v[50:51], v[50:51], 0.5, v[208:209] op_sel_hi:[1,0,1]
	v_pk_fma_f32 v[52:53], v[52:53], 0.5, v[210:211] op_sel_hi:[1,0,1]
	global_store_dwordx4 v[152:153], v[62:65], off
	global_store_dwordx4 v[152:153], v[58:61], off offset:16
	global_store_dwordx4 v[152:153], v[54:57], off offset:512
	global_store_dwordx4 v[152:153], v[50:53], off offset:528
	s_mov_b64 s[26:27], 0x160000
	v_lshl_add_u64 v[228:229], v[134:135], 0, s[26:27]
	v_lshl_add_u64 v[230:231], v[158:159], 0, s[26:27]
	global_load_dwordx4 v[196:199], v[228:229], off
	global_load_dwordx4 v[200:203], v[228:229], off offset:16
	global_load_dwordx4 v[204:207], v[228:229], off offset:512
	global_load_dwordx4 v[208:211], v[228:229], off offset:528
	s_waitcnt vmcnt(16)
	v_pk_fma_f32 v[46:47], v[46:47], 0.5, v[212:213] op_sel_hi:[1,0,1]
	v_pk_fma_f32 v[48:49], v[48:49], 0.5, v[214:215] op_sel_hi:[1,0,1]
	v_pk_fma_f32 v[42:43], v[42:43], 0.5, v[216:217] op_sel_hi:[1,0,1]
	v_pk_fma_f32 v[44:45], v[44:45], 0.5, v[218:219] op_sel_hi:[1,0,1]
	v_pk_fma_f32 v[38:39], v[38:39], 0.5, v[220:221] op_sel_hi:[1,0,1]
	v_pk_fma_f32 v[40:41], v[40:41], 0.5, v[222:223] op_sel_hi:[1,0,1]
	v_pk_fma_f32 v[34:35], v[34:35], 0.5, v[224:225] op_sel_hi:[1,0,1]
	v_pk_fma_f32 v[36:37], v[36:37], 0.5, v[226:227] op_sel_hi:[1,0,1]
	global_store_dwordx4 v[160:161], v[46:49], off
	global_store_dwordx4 v[160:161], v[42:45], off offset:16
	global_store_dwordx4 v[160:161], v[38:41], off offset:512
	global_store_dwordx4 v[160:161], v[34:37], off offset:528
	s_waitcnt vmcnt(12)
	v_pk_fma_f32 v[30:31], v[30:31], 0.5, v[180:181] op_sel_hi:[1,0,1]
	v_pk_fma_f32 v[32:33], v[32:33], 0.5, v[182:183] op_sel_hi:[1,0,1]
	v_pk_fma_f32 v[26:27], v[26:27], 0.5, v[184:185] op_sel_hi:[1,0,1]
	v_pk_fma_f32 v[28:29], v[28:29], 0.5, v[186:187] op_sel_hi:[1,0,1]
	v_pk_fma_f32 v[22:23], v[22:23], 0.5, v[188:189] op_sel_hi:[1,0,1]
	v_pk_fma_f32 v[24:25], v[24:25], 0.5, v[190:191] op_sel_hi:[1,0,1]
	v_pk_fma_f32 v[18:19], v[18:19], 0.5, v[192:193] op_sel_hi:[1,0,1]
	v_pk_fma_f32 v[20:21], v[20:21], 0.5, v[194:195] op_sel_hi:[1,0,1]
	global_store_dwordx4 v[148:149], v[30:33], off
	global_store_dwordx4 v[148:149], v[26:29], off offset:16
	global_store_dwordx4 v[148:149], v[22:25], off offset:512
	global_store_dwordx4 v[148:149], v[18:21], off offset:528
	s_waitcnt vmcnt(8)
	v_pk_fma_f32 v[14:15], v[14:15], 0.5, v[196:197] op_sel_hi:[1,0,1]
	v_pk_fma_f32 v[16:17], v[16:17], 0.5, v[198:199] op_sel_hi:[1,0,1]
	v_pk_fma_f32 v[10:11], v[10:11], 0.5, v[200:201] op_sel_hi:[1,0,1]
	v_pk_fma_f32 v[12:13], v[12:13], 0.5, v[202:203] op_sel_hi:[1,0,1]
	v_pk_fma_f32 v[6:7], v[6:7], 0.5, v[204:205] op_sel_hi:[1,0,1]
	v_pk_fma_f32 v[8:9], v[8:9], 0.5, v[206:207] op_sel_hi:[1,0,1]
	v_pk_fma_f32 v[2:3], v[2:3], 0.5, v[208:209] op_sel_hi:[1,0,1]
	v_pk_fma_f32 v[4:5], v[4:5], 0.5, v[210:211] op_sel_hi:[1,0,1]
	global_store_dwordx4 v[230:231], v[14:17], off
	global_store_dwordx4 v[230:231], v[10:13], off offset:16
	global_store_dwordx4 v[230:231], v[6:9], off offset:512
	global_store_dwordx4 v[230:231], v[2:5], off offset:528
	s_mov_b64 s[26:27], s[24:25]
	s_cbranch_vccz .LBB0_171
	s_waitcnt vmcnt(0)
	v_readlane_b32 s52, v254, 26
	v_readlane_b32 s56, v254, 30
	v_readlane_b32 s54, v254, 32
	s_cmpk_gt_u32 s4, 0xff
	v_readlane_b32 s53, v254, 27
	v_readlane_b32 s57, v254, 31
	v_readlane_b32 s55, v254, 33
	s_mov_b64 s[58:59], s[84:85]
	s_cbranch_scc1 .LBB0_186
	s_barrier

.LBB0_359:
	v_mov_b64_e32 v[2:3], 0x500
	s_ashr_i32 s23, s22, 31
	v_cmp_lt_i64_e32 vcc, s[24:25], v[2:3]
	s_lshl_b64 s[24:25], s[22:23], 20
	s_add_u32 s24, s78, s24
	s_addc_u32 s25, s79, s25
	s_and_b64 s[38:39], vcc, exec
	s_cselect_b32 s23, s25, s43
	s_cselect_b32 s53, s24, s42
	s_ashr_i32 s1, s0, 31
	s_lshl_b64 s[38:39], s[0:1], 20
	s_add_u32 s38, s72, s38
	s_addc_u32 s39, s73, s39
	s_and_b64 s[44:45], vcc, exec
	s_cselect_b32 s1, s39, s27
	s_cselect_b32 s54, s38, s26
	s_add_u32 s42, s42, 0x80080
	s_addc_u32 s43, s43, 0
	s_add_u32 s55, s26, 0x100
	v_mov_b32_e32 v2, 0
	s_addc_u32 s56, s27, 0
	s_mov_b32 s57, -2
	v_mov_b32_e32 v3, v2
	v_mov_b32_e32 v4, v2
	v_mov_b32_e32 v5, v2
	v_mov_b32_e32 v6, v2
	v_mov_b32_e32 v7, v2
	v_mov_b32_e32 v8, v2
	v_mov_b32_e32 v9, v2
	v_mov_b32_e32 v10, v2
	v_mov_b32_e32 v11, v2
	v_mov_b32_e32 v12, v2
	v_mov_b32_e32 v13, v2
	v_mov_b32_e32 v18, v2
	v_mov_b32_e32 v19, v2
	v_mov_b32_e32 v20, v2
	v_mov_b32_e32 v21, v2
	v_mov_b32_e32 v26, v2
	v_mov_b32_e32 v27, v2
	v_mov_b32_e32 v28, v2
	v_mov_b32_e32 v29, v2
	v_mov_b32_e32 v34, v2
	v_mov_b32_e32 v35, v2
	v_mov_b32_e32 v36, v2
	v_mov_b32_e32 v37, v2
	v_mov_b32_e32 v42, v2
	v_mov_b32_e32 v43, v2
	v_mov_b32_e32 v44, v2
	v_mov_b32_e32 v45, v2
	v_mov_b32_e32 v50, v2
	v_mov_b32_e32 v51, v2
	v_mov_b32_e32 v52, v2
	v_mov_b32_e32 v53, v2
	v_mov_b32_e32 v14, v2
	v_mov_b32_e32 v15, v2
	v_mov_b32_e32 v16, v2
	v_mov_b32_e32 v17, v2
	v_mov_b32_e32 v22, v2
	v_mov_b32_e32 v23, v2
	v_mov_b32_e32 v24, v2
	v_mov_b32_e32 v25, v2
	v_mov_b32_e32 v30, v2
	v_mov_b32_e32 v31, v2
	v_mov_b32_e32 v32, v2
	v_mov_b32_e32 v33, v2
	v_mov_b32_e32 v38, v2
	v_mov_b32_e32 v39, v2
	v_mov_b32_e32 v40, v2
	v_mov_b32_e32 v41, v2
	v_mov_b32_e32 v46, v2
	v_mov_b32_e32 v47, v2
	v_mov_b32_e32 v48, v2
	v_mov_b32_e32 v49, v2
	v_mov_b32_e32 v54, v2
	v_mov_b32_e32 v55, v2
	v_mov_b32_e32 v56, v2
	v_mov_b32_e32 v57, v2
	v_mov_b32_e32 v58, v2
	v_mov_b32_e32 v59, v2
	v_mov_b32_e32 v60, v2
	v_mov_b32_e32 v61, v2
	v_mov_b32_e32 v62, v2
	v_mov_b32_e32 v63, v2
	v_mov_b32_e32 v64, v2
	v_mov_b32_e32 v65, v2
	v_mov_b32_e32 v66, v2
	v_mov_b32_e32 v67, v2
	v_mov_b32_e32 v68, v2
	v_mov_b32_e32 v69, v2
	v_mov_b32_e32 v70, v2
	v_mov_b32_e32 v71, v2
	v_mov_b32_e32 v72, v2
	v_mov_b32_e32 v73, v2
	v_mov_b32_e32 v74, v2
	v_mov_b32_e32 v75, v2
	v_mov_b32_e32 v76, v2
	v_mov_b32_e32 v77, v2
	v_mov_b32_e32 v82, v2
	v_mov_b32_e32 v83, v2
	v_mov_b32_e32 v84, v2
	v_mov_b32_e32 v85, v2
	v_mov_b32_e32 v90, v2
	v_mov_b32_e32 v91, v2
	v_mov_b32_e32 v92, v2
	v_mov_b32_e32 v93, v2
	v_mov_b32_e32 v98, v2
	v_mov_b32_e32 v99, v2
	v_mov_b32_e32 v100, v2
	v_mov_b32_e32 v101, v2
	v_mov_b32_e32 v106, v2
	v_mov_b32_e32 v107, v2
	v_mov_b32_e32 v108, v2
	v_mov_b32_e32 v109, v2
	v_mov_b32_e32 v114, v2
	v_mov_b32_e32 v115, v2
	v_mov_b32_e32 v116, v2
	v_mov_b32_e32 v117, v2
	v_mov_b32_e32 v78, v2
	v_mov_b32_e32 v79, v2
	v_mov_b32_e32 v80, v2
	v_mov_b32_e32 v81, v2
	v_mov_b32_e32 v86, v2
	v_mov_b32_e32 v87, v2
	v_mov_b32_e32 v88, v2
	v_mov_b32_e32 v89, v2
	v_mov_b32_e32 v94, v2
	v_mov_b32_e32 v95, v2
	v_mov_b32_e32 v96, v2
	v_mov_b32_e32 v97, v2
	v_mov_b32_e32 v102, v2
	v_mov_b32_e32 v103, v2
	v_mov_b32_e32 v104, v2
	v_mov_b32_e32 v105, v2
	v_mov_b32_e32 v110, v2
	v_mov_b32_e32 v111, v2
	v_mov_b32_e32 v112, v2
	v_mov_b32_e32 v113, v2
	v_mov_b32_e32 v118, v2
	v_mov_b32_e32 v119, v2
	v_mov_b32_e32 v120, v2
	v_mov_b32_e32 v121, v2
	v_mov_b32_e32 v122, v2
	v_mov_b32_e32 v123, v2
	v_mov_b32_e32 v124, v2
	v_mov_b32_e32 v125, v2
	v_mov_b32_e32 v126, v2
	v_mov_b32_e32 v127, v2
	v_mov_b32_e32 v128, v2
	v_mov_b32_e32 v129, v2
	v_add_u32_e32 v134, 0x10000, v153
.LBB0_360:
	s_add_u32 s26, s42, 0xfff80080
	s_addc_u32 s27, s43, -1
	s_add_i32 s58, 0, 0x10000
	ds_read_b128 v[148:151], v134
	ds_read_b128 v[156:159], v134 offset:1024
	ds_read_b128 v[160:163], v134 offset:2048
	ds_read_b128 v[164:167], v134 offset:3072
	s_cmp_eq_u32 s57, 28
	s_cselect_b32 s45, s23, s27
	s_cselect_b32 s44, s53, s26
	s_cselect_b32 s27, s1, s56
	s_cselect_b32 s26, s54, s55
	s_add_i32 m0, s7, 0xc000
	ds_read_b128 v[180:183], v155
	ds_read_b128 v[184:187], v155 offset:1024
	ds_read_b128 v[188:191], v155 offset:2048
	ds_read_b128 v[192:195], v155 offset:3072
	ds_read_b128 v[196:199], v155 offset:4096
	ds_read_b128 v[200:203], v155 offset:5120
	ds_read_b128 v[204:207], v155 offset:6144
	ds_read_b128 v[208:211], v155 offset:7168
	global_load_lds_dwordx4 v144, s[42:43]
	s_add_i32 m0, s7, 0xe000
	s_nop 0
	global_load_lds_dwordx4 v146, s[42:43]
	s_waitcnt lgkmcnt(8)
	s_barrier
	s_waitcnt lgkmcnt(0)
	s_setprio 1
	s_waitcnt lgkmcnt(0)
	v_mfma_f32_16x16x32_bf16 v[126:129], v[148:151], v[180:183], v[126:129]
	v_mfma_f32_16x16x32_bf16 v[122:125], v[160:163], v[180:183], v[122:125]
	v_mfma_f32_16x16x32_bf16 v[118:121], v[148:151], v[188:191], v[118:121]
	v_mfma_f32_16x16x32_bf16 v[110:113], v[160:163], v[188:191], v[110:113]
	v_mfma_f32_16x16x32_bf16 v[102:105], v[148:151], v[196:199], v[102:105]
	v_mfma_f32_16x16x32_bf16 v[94:97], v[160:163], v[196:199], v[94:97]
	v_mfma_f32_16x16x32_bf16 v[86:89], v[148:151], v[204:207], v[86:89]
	v_mfma_f32_16x16x32_bf16 v[78:81], v[160:163], v[204:207], v[78:81]
	v_mfma_f32_16x16x32_bf16 v[126:129], v[156:159], v[184:187], v[126:129]
	v_mfma_f32_16x16x32_bf16 v[122:125], v[164:167], v[184:187], v[122:125]
	v_mfma_f32_16x16x32_bf16 v[118:121], v[156:159], v[192:195], v[118:121]
	v_mfma_f32_16x16x32_bf16 v[110:113], v[164:167], v[192:195], v[110:113]
	v_mfma_f32_16x16x32_bf16 v[102:105], v[156:159], v[200:203], v[102:105]
	v_mfma_f32_16x16x32_bf16 v[94:97], v[164:167], v[200:203], v[94:97]
	v_mfma_f32_16x16x32_bf16 v[86:89], v[156:159], v[208:211], v[86:89]
	v_mfma_f32_16x16x32_bf16 v[78:81], v[164:167], v[208:211], v[78:81]
	s_setprio 0
	s_barrier
	s_add_i32 s60, 0, 0x14000
	s_add_i32 s58, s58, s6
	ds_read_b128 v[212:215], v134 offset:16384
	ds_read_b128 v[216:219], v134 offset:17408
	ds_read_b128 v[220:223], v134 offset:18432
	ds_read_b128 v[224:227], v134 offset:19456
	s_mov_b32 m0, s58
	global_load_lds_dwordx4 v0, s[26:27]
	s_add_i32 m0, s58, 0x2000
	s_nop 0
	global_load_lds_dwordx4 v138, s[26:27]
	s_barrier
	s_waitcnt lgkmcnt(0)
	s_setprio 1
	s_waitcnt lgkmcnt(0)
	v_mfma_f32_16x16x32_bf16 v[114:117], v[212:215], v[180:183], v[114:117]
	v_mfma_f32_16x16x32_bf16 v[106:109], v[220:223], v[180:183], v[106:109]
	v_mfma_f32_16x16x32_bf16 v[98:101], v[212:215], v[188:191], v[98:101]
	v_mfma_f32_16x16x32_bf16 v[90:93], v[220:223], v[188:191], v[90:93]
	v_mfma_f32_16x16x32_bf16 v[82:85], v[212:215], v[196:199], v[82:85]
	v_mfma_f32_16x16x32_bf16 v[74:77], v[220:223], v[196:199], v[74:77]
	v_mfma_f32_16x16x32_bf16 v[70:73], v[212:215], v[204:207], v[70:73]
	v_mfma_f32_16x16x32_bf16 v[66:69], v[220:223], v[204:207], v[66:69]
	v_mfma_f32_16x16x32_bf16 v[114:117], v[216:219], v[184:187], v[114:117]
	v_mfma_f32_16x16x32_bf16 v[106:109], v[224:227], v[184:187], v[106:109]
	v_mfma_f32_16x16x32_bf16 v[98:101], v[216:219], v[192:195], v[98:101]
	v_mfma_f32_16x16x32_bf16 v[90:93], v[224:227], v[192:195], v[90:93]
	v_mfma_f32_16x16x32_bf16 v[82:85], v[216:219], v[200:203], v[82:85]
	v_mfma_f32_16x16x32_bf16 v[74:77], v[224:227], v[200:203], v[74:77]
	v_mfma_f32_16x16x32_bf16 v[70:73], v[216:219], v[208:211], v[70:73]
	v_mfma_f32_16x16x32_bf16 v[66:69], v[224:227], v[208:211], v[66:69]
	s_setprio 0
	s_mov_b32 m0, s7
	s_add_u32 vcc_lo, s44, s10
	s_addc_u32 vcc_hi, s45, s11
	s_barrier
	ds_read_b128 v[180:183], v155 offset:16384
	ds_read_b128 v[184:187], v155 offset:17408
	ds_read_b128 v[188:191], v155 offset:18432
	ds_read_b128 v[192:195], v155 offset:19456
	ds_read_b128 v[196:199], v155 offset:20480
	ds_read_b128 v[200:203], v155 offset:21504
	ds_read_b128 v[204:207], v155 offset:22528
	ds_read_b128 v[208:211], v155 offset:23552
	global_load_lds_dwordx4 v142, s[44:45]
	s_mov_b32 m0, s14
	s_nop 0
	global_load_lds_dwordx4 v140, s[44:45]
	s_barrier
	s_waitcnt lgkmcnt(0)
	s_setprio 1
	s_waitcnt lgkmcnt(0)
	v_mfma_f32_16x16x32_bf16 v[62:65], v[148:151], v[180:183], v[62:65]
	v_mfma_f32_16x16x32_bf16 v[58:61], v[160:163], v[180:183], v[58:61]
	v_mfma_f32_16x16x32_bf16 v[54:57], v[148:151], v[188:191], v[54:57]
	v_mfma_f32_16x16x32_bf16 v[46:49], v[160:163], v[188:191], v[46:49]
	v_mfma_f32_16x16x32_bf16 v[38:41], v[148:151], v[196:199], v[38:41]
	v_mfma_f32_16x16x32_bf16 v[30:33], v[160:163], v[196:199], v[30:33]
	v_mfma_f32_16x16x32_bf16 v[22:25], v[148:151], v[204:207], v[22:25]
	v_mfma_f32_16x16x32_bf16 v[14:17], v[160:163], v[204:207], v[14:17]
	v_mfma_f32_16x16x32_bf16 v[62:65], v[156:159], v[184:187], v[62:65]
	v_mfma_f32_16x16x32_bf16 v[58:61], v[164:167], v[184:187], v[58:61]
	v_mfma_f32_16x16x32_bf16 v[54:57], v[156:159], v[192:195], v[54:57]
	v_mfma_f32_16x16x32_bf16 v[46:49], v[164:167], v[192:195], v[46:49]
	v_mfma_f32_16x16x32_bf16 v[38:41], v[156:159], v[200:203], v[38:41]
	v_mfma_f32_16x16x32_bf16 v[30:33], v[164:167], v[200:203], v[30:33]
	v_mfma_f32_16x16x32_bf16 v[22:25], v[156:159], v[208:211], v[22:25]
	v_mfma_f32_16x16x32_bf16 v[14:17], v[164:167], v[208:211], v[14:17]
	s_setprio 0
	s_barrier
	s_add_u32 s58, s26, 0x80000
	s_addc_u32 s59, s27, 0
	s_add_i32 s60, s60, s6
	s_mov_b32 m0, s60
	s_nop 0
	global_load_lds_dwordx4 v0, s[58:59]
	s_add_i32 m0, s60, 0x2000
	s_nop 0
	global_load_lds_dwordx4 v138, s[58:59]
	s_waitcnt vmcnt(6)
	s_barrier
	s_setprio 1
	v_mfma_f32_16x16x32_bf16 v[50:53], v[212:215], v[180:183], v[50:53]
	v_mfma_f32_16x16x32_bf16 v[42:45], v[220:223], v[180:183], v[42:45]
	v_mfma_f32_16x16x32_bf16 v[34:37], v[212:215], v[188:191], v[34:37]
	v_mfma_f32_16x16x32_bf16 v[26:29], v[220:223], v[188:191], v[26:29]
	v_mfma_f32_16x16x32_bf16 v[18:21], v[212:215], v[196:199], v[18:21]
	v_mfma_f32_16x16x32_bf16 v[10:13], v[220:223], v[196:199], v[10:13]
	v_mfma_f32_16x16x32_bf16 v[6:9], v[212:215], v[204:207], v[6:9]
	v_mfma_f32_16x16x32_bf16 v[2:5], v[220:223], v[204:207], v[2:5]
	v_mfma_f32_16x16x32_bf16 v[50:53], v[216:219], v[184:187], v[50:53]
	v_mfma_f32_16x16x32_bf16 v[42:45], v[224:227], v[184:187], v[42:45]
	v_mfma_f32_16x16x32_bf16 v[34:37], v[216:219], v[192:195], v[34:37]
	v_mfma_f32_16x16x32_bf16 v[26:29], v[224:227], v[192:195], v[26:29]
	v_mfma_f32_16x16x32_bf16 v[18:21], v[216:219], v[200:203], v[18:21]
	v_mfma_f32_16x16x32_bf16 v[10:13], v[224:227], v[200:203], v[10:13]
	v_mfma_f32_16x16x32_bf16 v[6:9], v[216:219], v[208:211], v[6:9]
	v_mfma_f32_16x16x32_bf16 v[2:5], v[224:227], v[208:211], v[2:5]
	s_setprio 0
	s_add_i32 s58, 0, 0x18000
	s_barrier
	ds_read_b128 v[148:151], v134 offset:32768
	ds_read_b128 v[156:159], v134 offset:33792
	ds_read_b128 v[160:163], v134 offset:34816
	ds_read_b128 v[164:167], v134 offset:35840
	s_add_u32 s44, s44, 0x80000
	s_addc_u32 s45, s45, 0
	s_mov_b32 m0, s46
	ds_read_b128 v[180:183], v155 offset:32768
	ds_read_b128 v[184:187], v155 offset:33792
	ds_read_b128 v[188:191], v155 offset:34816
	ds_read_b128 v[192:195], v155 offset:35840
	ds_read_b128 v[196:199], v155 offset:36864
	ds_read_b128 v[200:203], v155 offset:37888
	ds_read_b128 v[204:207], v155 offset:38912
	ds_read_b128 v[208:211], v155 offset:39936
	global_load_lds_dwordx4 v142, s[44:45]
	s_mov_b32 m0, s47
	s_nop 0
	global_load_lds_dwordx4 v140, s[44:45]
	s_waitcnt lgkmcnt(8)
	s_barrier
	s_waitcnt lgkmcnt(0)
	s_setprio 1
	s_waitcnt lgkmcnt(0)
	v_mfma_f32_16x16x32_bf16 v[126:129], v[148:151], v[180:183], v[126:129]
	v_mfma_f32_16x16x32_bf16 v[122:125], v[160:163], v[180:183], v[122:125]
	v_mfma_f32_16x16x32_bf16 v[118:121], v[148:151], v[188:191], v[118:121]
	v_mfma_f32_16x16x32_bf16 v[110:113], v[160:163], v[188:191], v[110:113]
	v_mfma_f32_16x16x32_bf16 v[102:105], v[148:151], v[196:199], v[102:105]
	v_mfma_f32_16x16x32_bf16 v[94:97], v[160:163], v[196:199], v[94:97]
	v_mfma_f32_16x16x32_bf16 v[86:89], v[148:151], v[204:207], v[86:89]
	v_mfma_f32_16x16x32_bf16 v[78:81], v[160:163], v[204:207], v[78:81]
	v_mfma_f32_16x16x32_bf16 v[126:129], v[156:159], v[184:187], v[126:129]
	v_mfma_f32_16x16x32_bf16 v[122:125], v[164:167], v[184:187], v[122:125]
	v_mfma_f32_16x16x32_bf16 v[118:121], v[156:159], v[192:195], v[118:121]
	v_mfma_f32_16x16x32_bf16 v[110:113], v[164:167], v[192:195], v[110:113]
	v_mfma_f32_16x16x32_bf16 v[102:105], v[156:159], v[200:203], v[102:105]
	v_mfma_f32_16x16x32_bf16 v[94:97], v[164:167], v[200:203], v[94:97]
	v_mfma_f32_16x16x32_bf16 v[86:89], v[156:159], v[208:211], v[86:89]
	v_mfma_f32_16x16x32_bf16 v[78:81], v[164:167], v[208:211], v[78:81]
	s_setprio 0
	s_barrier
	s_add_i32 s44, 0, 0x1c000
	s_add_i32 s45, s58, s6
	s_add_u32 s100, s26, s10
	s_addc_u32 s101, s27, s11
	s_mov_b32 m0, s45
	ds_read_b128 v[212:215], v134 offset:49152
	ds_read_b128 v[216:219], v134 offset:50176
	ds_read_b128 v[220:223], v134 offset:51200
	ds_read_b128 v[224:227], v134 offset:52224
	global_load_lds_dwordx4 v0, s[100:101]
	s_add_u32 s100, s26, s10
	s_addc_u32 s101, s27, s11
	s_add_i32 m0, s45, 0x2000
	s_nop 0
	global_load_lds_dwordx4 v138, s[100:101]
	s_barrier
	s_waitcnt lgkmcnt(0)
	s_setprio 1
	s_waitcnt lgkmcnt(0)
	v_mfma_f32_16x16x32_bf16 v[114:117], v[212:215], v[180:183], v[114:117]
	v_mfma_f32_16x16x32_bf16 v[106:109], v[220:223], v[180:183], v[106:109]
	v_mfma_f32_16x16x32_bf16 v[98:101], v[212:215], v[188:191], v[98:101]
	v_mfma_f32_16x16x32_bf16 v[90:93], v[220:223], v[188:191], v[90:93]
	v_mfma_f32_16x16x32_bf16 v[82:85], v[212:215], v[196:199], v[82:85]
	v_mfma_f32_16x16x32_bf16 v[74:77], v[220:223], v[196:199], v[74:77]
	v_mfma_f32_16x16x32_bf16 v[70:73], v[212:215], v[204:207], v[70:73]
	v_mfma_f32_16x16x32_bf16 v[66:69], v[220:223], v[204:207], v[66:69]
	v_mfma_f32_16x16x32_bf16 v[114:117], v[216:219], v[184:187], v[114:117]
	v_mfma_f32_16x16x32_bf16 v[106:109], v[224:227], v[184:187], v[106:109]
	v_mfma_f32_16x16x32_bf16 v[98:101], v[216:219], v[192:195], v[98:101]
	v_mfma_f32_16x16x32_bf16 v[90:93], v[224:227], v[192:195], v[90:93]
	v_mfma_f32_16x16x32_bf16 v[82:85], v[216:219], v[200:203], v[82:85]
	v_mfma_f32_16x16x32_bf16 v[74:77], v[224:227], v[200:203], v[74:77]
	v_mfma_f32_16x16x32_bf16 v[70:73], v[216:219], v[208:211], v[70:73]
	v_mfma_f32_16x16x32_bf16 v[66:69], v[224:227], v[208:211], v[66:69]
	s_setprio 0
	s_mov_b32 m0, s48
	s_barrier
	ds_read_b128 v[180:183], v155 offset:49152
	ds_read_b128 v[184:187], v155 offset:50176
	ds_read_b128 v[188:191], v155 offset:51200
	ds_read_b128 v[192:195], v155 offset:52224
	ds_read_b128 v[196:199], v155 offset:53248
	ds_read_b128 v[200:203], v155 offset:54272
	ds_read_b128 v[204:207], v155 offset:55296
	ds_read_b128 v[208:211], v155 offset:56320
	global_load_lds_dwordx4 v142, vcc
	s_mov_b32 m0, s49
	s_nop 0
	global_load_lds_dwordx4 v140, vcc
	s_barrier
	s_waitcnt lgkmcnt(0)
	s_setprio 1
	s_waitcnt lgkmcnt(0)
	v_mfma_f32_16x16x32_bf16 v[62:65], v[148:151], v[180:183], v[62:65]
	v_mfma_f32_16x16x32_bf16 v[58:61], v[160:163], v[180:183], v[58:61]
	v_mfma_f32_16x16x32_bf16 v[54:57], v[148:151], v[188:191], v[54:57]
	v_mfma_f32_16x16x32_bf16 v[46:49], v[160:163], v[188:191], v[46:49]
	v_mfma_f32_16x16x32_bf16 v[38:41], v[148:151], v[196:199], v[38:41]
	v_mfma_f32_16x16x32_bf16 v[30:33], v[160:163], v[196:199], v[30:33]
	v_mfma_f32_16x16x32_bf16 v[22:25], v[148:151], v[204:207], v[22:25]
	v_mfma_f32_16x16x32_bf16 v[14:17], v[160:163], v[204:207], v[14:17]
	v_mfma_f32_16x16x32_bf16 v[62:65], v[156:159], v[184:187], v[62:65]
	v_mfma_f32_16x16x32_bf16 v[58:61], v[164:167], v[184:187], v[58:61]
	v_mfma_f32_16x16x32_bf16 v[54:57], v[156:159], v[192:195], v[54:57]
	v_mfma_f32_16x16x32_bf16 v[46:49], v[164:167], v[192:195], v[46:49]
	v_mfma_f32_16x16x32_bf16 v[38:41], v[156:159], v[200:203], v[38:41]
	v_mfma_f32_16x16x32_bf16 v[30:33], v[164:167], v[200:203], v[30:33]
	v_mfma_f32_16x16x32_bf16 v[22:25], v[156:159], v[208:211], v[22:25]
	v_mfma_f32_16x16x32_bf16 v[14:17], v[164:167], v[208:211], v[14:17]
	s_setprio 0
	s_barrier
	s_add_u32 s26, s26, 0x80080
	s_addc_u32 s27, s27, 0
	s_add_i32 s44, s44, s6
	s_mov_b32 m0, s44
	s_nop 0
	global_load_lds_dwordx4 v0, s[26:27]
	s_add_i32 m0, s44, 0x2000
	s_nop 0
	global_load_lds_dwordx4 v138, s[26:27]
	s_waitcnt vmcnt(6)
	s_barrier
	s_setprio 1
	v_mfma_f32_16x16x32_bf16 v[50:53], v[212:215], v[180:183], v[50:53]
	v_mfma_f32_16x16x32_bf16 v[42:45], v[220:223], v[180:183], v[42:45]
	v_mfma_f32_16x16x32_bf16 v[34:37], v[212:215], v[188:191], v[34:37]
	v_mfma_f32_16x16x32_bf16 v[26:29], v[220:223], v[188:191], v[26:29]
	v_mfma_f32_16x16x32_bf16 v[18:21], v[212:215], v[196:199], v[18:21]
	v_mfma_f32_16x16x32_bf16 v[10:13], v[220:223], v[196:199], v[10:13]
	v_mfma_f32_16x16x32_bf16 v[6:9], v[212:215], v[204:207], v[6:9]
	v_mfma_f32_16x16x32_bf16 v[2:5], v[220:223], v[204:207], v[2:5]
	v_mfma_f32_16x16x32_bf16 v[50:53], v[216:219], v[184:187], v[50:53]
	v_mfma_f32_16x16x32_bf16 v[42:45], v[224:227], v[184:187], v[42:45]
	v_mfma_f32_16x16x32_bf16 v[34:37], v[216:219], v[192:195], v[34:37]
	v_mfma_f32_16x16x32_bf16 v[26:29], v[224:227], v[192:195], v[26:29]
	v_mfma_f32_16x16x32_bf16 v[18:21], v[216:219], v[200:203], v[18:21]
	v_mfma_f32_16x16x32_bf16 v[10:13], v[224:227], v[200:203], v[10:13]
	v_mfma_f32_16x16x32_bf16 v[6:9], v[216:219], v[208:211], v[6:9]
	v_mfma_f32_16x16x32_bf16 v[2:5], v[224:227], v[208:211], v[2:5]
	s_setprio 0
	s_add_i32 s57, s57, 2
	s_add_u32 s42, s42, 0x100
	s_addc_u32 s43, s43, 0
	s_add_u32 s55, s55, 0x100
	s_addc_u32 s56, s56, 0
	s_cmp_gt_u32 s57, 29
	s_barrier
	s_cbranch_scc0 .LBB0_360
	v_lshl_or_b32 v134, s51, 8, v154
	v_lshl_add_u32 v158, s52, 8, v152
	v_ashrrev_i32_e32 v135, 31, v134
	v_mov_b64_e32 v[148:149], s[88:89]
	v_mad_i64_i32 v[156:157], s[26:27], v158, s35, v[148:149]
	v_lshlrev_b64 v[150:151], 1, v[134:135]
	v_lshl_add_u64 v[134:135], v[156:157], 0, v[150:151]
	v_cvt_pk_bf16_f32 v126, v126, v127
	v_cvt_pk_bf16_f32 v127, v128, v129
	v_cvt_pk_bf16_f32 v128, v122, v123
	v_cvt_pk_bf16_f32 v129, v124, v125
	global_store_dwordx4 v[134:135], v[126:129], off
	v_cvt_pk_bf16_f32 v114, v114, v115
	v_cvt_pk_bf16_f32 v115, v116, v117
	v_cvt_pk_bf16_f32 v116, v106, v107
	v_or_b32_e32 v106, 16, v158
	v_mad_i64_i32 v[106:107], s[26:27], v106, s35, v[148:149]
	v_cvt_pk_bf16_f32 v117, v108, v109
	global_store_dwordx4 v[134:135], v[114:117], off offset:256
	s_and_b64 vcc, exec, s[40:41]
	s_mov_b32 s51, s0
	v_lshl_add_u64 v[114:115], v[106:107], 0, v[150:151]
	v_cvt_pk_bf16_f32 v106, v118, v119
	v_cvt_pk_bf16_f32 v107, v120, v121
	v_cvt_pk_bf16_f32 v108, v110, v111
	v_cvt_pk_bf16_f32 v109, v112, v113
	global_store_dwordx4 v[114:115], v[106:109], off
	v_cvt_pk_bf16_f32 v98, v98, v99
	v_cvt_pk_bf16_f32 v99, v100, v101
	v_cvt_pk_bf16_f32 v100, v90, v91
	v_or_b32_e32 v90, 32, v158
	v_mad_i64_i32 v[90:91], s[26:27], v90, s35, v[148:149]
	v_cvt_pk_bf16_f32 v101, v92, v93
	global_store_dwordx4 v[114:115], v[98:101], off offset:256
	s_mov_b32 s52, s22
	s_mov_b64 s[42:43], s[24:25]
	v_lshl_add_u64 v[98:99], v[90:91], 0, v[150:151]
	v_cvt_pk_bf16_f32 v90, v102, v103
	v_cvt_pk_bf16_f32 v91, v104, v105
	v_cvt_pk_bf16_f32 v92, v94, v95
	v_cvt_pk_bf16_f32 v93, v96, v97
	global_store_dwordx4 v[98:99], v[90:93], off
	v_cvt_pk_bf16_f32 v82, v82, v83
	v_cvt_pk_bf16_f32 v83, v84, v85
	v_cvt_pk_bf16_f32 v84, v74, v75
	v_or_b32_e32 v74, 48, v158
	v_mad_i64_i32 v[74:75], s[26:27], v74, s35, v[148:149]
	v_cvt_pk_bf16_f32 v85, v76, v77
	global_store_dwordx4 v[98:99], v[82:85], off offset:256
	s_nop 1
	v_lshl_add_u64 v[82:83], v[74:75], 0, v[150:151]
	v_cvt_pk_bf16_f32 v74, v86, v87
	v_cvt_pk_bf16_f32 v75, v88, v89
	v_cvt_pk_bf16_f32 v76, v78, v79
	v_cvt_pk_bf16_f32 v77, v80, v81
	global_store_dwordx4 v[82:83], v[74:77], off
	v_cvt_pk_bf16_f32 v70, v70, v71
	v_cvt_pk_bf16_f32 v71, v72, v73
	v_cvt_pk_bf16_f32 v72, v66, v67
	v_add_u32_e32 v66, 0x80, v158
	v_mad_i64_i32 v[66:67], s[26:27], v66, s35, v[148:149]
	v_lshl_add_u64 v[66:67], v[66:67], 0, v[150:151]
	v_cvt_pk_bf16_f32 v73, v68, v69
	global_store_dwordx4 v[82:83], v[70:73], off offset:256
	v_cvt_pk_bf16_f32 v62, v62, v63
	v_cvt_pk_bf16_f32 v63, v64, v65
	v_cvt_pk_bf16_f32 v64, v58, v59
	v_cvt_pk_bf16_f32 v65, v60, v61
	global_store_dwordx4 v[66:67], v[62:65], off
	v_cvt_pk_bf16_f32 v50, v50, v51
	v_cvt_pk_bf16_f32 v51, v52, v53
	v_cvt_pk_bf16_f32 v52, v42, v43
	v_add_u32_e32 v42, 0x90, v158
	v_mad_i64_i32 v[42:43], s[26:27], v42, s35, v[148:149]
	v_cvt_pk_bf16_f32 v53, v44, v45
	global_store_dwordx4 v[66:67], v[50:53], off offset:256
	s_nop 1
	v_lshl_add_u64 v[50:51], v[42:43], 0, v[150:151]
	v_cvt_pk_bf16_f32 v42, v54, v55
	v_cvt_pk_bf16_f32 v43, v56, v57
	v_cvt_pk_bf16_f32 v44, v46, v47
	v_cvt_pk_bf16_f32 v45, v48, v49
	global_store_dwordx4 v[50:51], v[42:45], off
	v_cvt_pk_bf16_f32 v34, v34, v35
	v_cvt_pk_bf16_f32 v35, v36, v37
	v_cvt_pk_bf16_f32 v36, v26, v27
	v_add_u32_e32 v26, 0xa0, v158
	v_mad_i64_i32 v[26:27], s[26:27], v26, s35, v[148:149]
	v_cvt_pk_bf16_f32 v37, v28, v29
	global_store_dwordx4 v[50:51], v[34:37], off offset:256
	s_nop 1
	v_lshl_add_u64 v[34:35], v[26:27], 0, v[150:151]
	v_cvt_pk_bf16_f32 v26, v38, v39
	v_cvt_pk_bf16_f32 v27, v40, v41
	v_cvt_pk_bf16_f32 v28, v30, v31
	v_cvt_pk_bf16_f32 v29, v32, v33
	global_store_dwordx4 v[34:35], v[26:29], off
	v_cvt_pk_bf16_f32 v18, v18, v19
	v_cvt_pk_bf16_f32 v19, v20, v21
	v_cvt_pk_bf16_f32 v20, v10, v11
	v_add_u32_e32 v10, 0xb0, v158
	v_mad_i64_i32 v[10:11], s[26:27], v10, s35, v[148:149]
	v_cvt_pk_bf16_f32 v21, v12, v13
	global_store_dwordx4 v[34:35], v[18:21], off offset:256
	s_mov_b64 s[26:27], s[38:39]
	s_nop 0
	v_lshl_add_u64 v[18:19], v[10:11], 0, v[150:151]
	v_cvt_pk_bf16_f32 v10, v22, v23
	v_cvt_pk_bf16_f32 v11, v24, v25
	v_cvt_pk_bf16_f32 v12, v14, v15
	v_cvt_pk_bf16_f32 v13, v16, v17
	global_store_dwordx4 v[18:19], v[10:13], off
	v_cvt_pk_bf16_f32 v6, v6, v7
	v_cvt_pk_bf16_f32 v7, v8, v9
	v_cvt_pk_bf16_f32 v8, v2, v3
	v_cvt_pk_bf16_f32 v9, v4, v5
	global_store_dwordx4 v[18:19], v[6:9], off offset:256
	s_cbranch_vccz .LBB0_357
	s_waitcnt vmcnt(0)
	v_readlane_b32 s52, v254, 26
	v_readlane_b32 s50, v254, 28
	s_cmpk_gt_u32 s4, 0xff
	v_readlane_b32 s53, v254, 27
	v_readlane_b32 s51, v254, 29
	s_cbranch_scc1 .LBB0_364
	s_barrier

.LBB0_626:
	s_ashr_i32 s23, s22, 31
	v_cmp_lt_i64_e32 vcc, s[24:25], v[136:137]
	s_lshl_b64 s[24:25], s[22:23], 20
	s_add_u32 s24, s78, s24
	s_addc_u32 s25, s79, s25
	s_and_b64 s[38:39], vcc, exec
	s_cselect_b32 s23, s25, s43
	s_cselect_b32 s53, s24, s42
	s_ashr_i32 s1, s0, 31
	s_lshl_b64 s[38:39], s[0:1], 20
	s_add_u32 s38, s61, s38
	v_readlane_b32 s1, v253, 18
	s_addc_u32 s39, s1, s39
	s_and_b64 s[44:45], vcc, exec
	s_cselect_b32 s1, s39, s27
	s_cselect_b32 s54, s38, s26
	s_add_u32 s42, s42, 0x80080
	s_addc_u32 s43, s43, 0
	s_add_u32 s55, s26, 0x100
	v_mov_b32_e32 v2, 0
	s_addc_u32 s56, s27, 0
	s_mov_b32 s57, -2
	v_mov_b32_e32 v3, v2
	v_mov_b32_e32 v4, v2
	v_mov_b32_e32 v5, v2
	v_mov_b32_e32 v6, v2
	v_mov_b32_e32 v7, v2
	v_mov_b32_e32 v8, v2
	v_mov_b32_e32 v9, v2
	v_mov_b32_e32 v10, v2
	v_mov_b32_e32 v11, v2
	v_mov_b32_e32 v12, v2
	v_mov_b32_e32 v13, v2
	v_mov_b32_e32 v18, v2
	v_mov_b32_e32 v19, v2
	v_mov_b32_e32 v20, v2
	v_mov_b32_e32 v21, v2
	v_mov_b32_e32 v26, v2
	v_mov_b32_e32 v27, v2
	v_mov_b32_e32 v28, v2
	v_mov_b32_e32 v29, v2
	v_mov_b32_e32 v34, v2
	v_mov_b32_e32 v35, v2
	v_mov_b32_e32 v36, v2
	v_mov_b32_e32 v37, v2
	v_mov_b32_e32 v42, v2
	v_mov_b32_e32 v43, v2
	v_mov_b32_e32 v44, v2
	v_mov_b32_e32 v45, v2
	v_mov_b32_e32 v50, v2
	v_mov_b32_e32 v51, v2
	v_mov_b32_e32 v52, v2
	v_mov_b32_e32 v53, v2
	v_mov_b32_e32 v14, v2
	v_mov_b32_e32 v15, v2
	v_mov_b32_e32 v16, v2
	v_mov_b32_e32 v17, v2
	v_mov_b32_e32 v22, v2
	v_mov_b32_e32 v23, v2
	v_mov_b32_e32 v24, v2
	v_mov_b32_e32 v25, v2
	v_mov_b32_e32 v30, v2
	v_mov_b32_e32 v31, v2
	v_mov_b32_e32 v32, v2
	v_mov_b32_e32 v33, v2
	v_mov_b32_e32 v38, v2
	v_mov_b32_e32 v39, v2
	v_mov_b32_e32 v40, v2
	v_mov_b32_e32 v41, v2
	v_mov_b32_e32 v46, v2
	v_mov_b32_e32 v47, v2
	v_mov_b32_e32 v48, v2
	v_mov_b32_e32 v49, v2
	v_mov_b32_e32 v54, v2
	v_mov_b32_e32 v55, v2
	v_mov_b32_e32 v56, v2
	v_mov_b32_e32 v57, v2
	v_mov_b32_e32 v58, v2
	v_mov_b32_e32 v59, v2
	v_mov_b32_e32 v60, v2
	v_mov_b32_e32 v61, v2
	v_mov_b32_e32 v62, v2
	v_mov_b32_e32 v63, v2
	v_mov_b32_e32 v64, v2
	v_mov_b32_e32 v65, v2
	v_mov_b32_e32 v66, v2
	v_mov_b32_e32 v67, v2
	v_mov_b32_e32 v68, v2
	v_mov_b32_e32 v69, v2
	v_mov_b32_e32 v70, v2
	v_mov_b32_e32 v71, v2
	v_mov_b32_e32 v72, v2
	v_mov_b32_e32 v73, v2
	v_mov_b32_e32 v74, v2
	v_mov_b32_e32 v75, v2
	v_mov_b32_e32 v76, v2
	v_mov_b32_e32 v77, v2
	v_mov_b32_e32 v82, v2
	v_mov_b32_e32 v83, v2
	v_mov_b32_e32 v84, v2
	v_mov_b32_e32 v85, v2
	v_mov_b32_e32 v90, v2
	v_mov_b32_e32 v91, v2
	v_mov_b32_e32 v92, v2
	v_mov_b32_e32 v93, v2
	v_mov_b32_e32 v98, v2
	v_mov_b32_e32 v99, v2
	v_mov_b32_e32 v100, v2
	v_mov_b32_e32 v101, v2
	v_mov_b32_e32 v106, v2
	v_mov_b32_e32 v107, v2
	v_mov_b32_e32 v108, v2
	v_mov_b32_e32 v109, v2
	v_mov_b32_e32 v114, v2
	v_mov_b32_e32 v115, v2
	v_mov_b32_e32 v116, v2
	v_mov_b32_e32 v117, v2
	v_mov_b32_e32 v78, v2
	v_mov_b32_e32 v79, v2
	v_mov_b32_e32 v80, v2
	v_mov_b32_e32 v81, v2
	v_mov_b32_e32 v86, v2
	v_mov_b32_e32 v87, v2
	v_mov_b32_e32 v88, v2
	v_mov_b32_e32 v89, v2
	v_mov_b32_e32 v94, v2
	v_mov_b32_e32 v95, v2
	v_mov_b32_e32 v96, v2
	v_mov_b32_e32 v97, v2
	v_mov_b32_e32 v102, v2
	v_mov_b32_e32 v103, v2
	v_mov_b32_e32 v104, v2
	v_mov_b32_e32 v105, v2
	v_mov_b32_e32 v110, v2
	v_mov_b32_e32 v111, v2
	v_mov_b32_e32 v112, v2
	v_mov_b32_e32 v113, v2
	v_mov_b32_e32 v118, v2
	v_mov_b32_e32 v119, v2
	v_mov_b32_e32 v120, v2
	v_mov_b32_e32 v121, v2
	v_mov_b32_e32 v122, v2
	v_mov_b32_e32 v123, v2
	v_mov_b32_e32 v124, v2
	v_mov_b32_e32 v125, v2
	v_mov_b32_e32 v126, v2
	v_mov_b32_e32 v127, v2
	v_mov_b32_e32 v128, v2
	v_mov_b32_e32 v129, v2
	v_add_u32_e32 v134, 0x10000, v153
.LBB0_627:
	s_add_u32 s26, s42, 0xfff80080
	s_addc_u32 s27, s43, -1
	s_add_i32 s58, 0, 0x10000
	ds_read_b128 v[148:151], v134
	ds_read_b128 v[156:159], v134 offset:1024
	ds_read_b128 v[160:163], v134 offset:2048
	ds_read_b128 v[164:167], v134 offset:3072
	s_cmp_eq_u32 s57, 28
	s_cselect_b32 s45, s23, s27
	s_cselect_b32 s44, s53, s26
	s_cselect_b32 s27, s1, s56
	s_cselect_b32 s26, s54, s55
	s_add_i32 m0, s7, 0xc000
	ds_read_b128 v[180:183], v155
	ds_read_b128 v[184:187], v155 offset:1024
	ds_read_b128 v[188:191], v155 offset:2048
	ds_read_b128 v[192:195], v155 offset:3072
	ds_read_b128 v[196:199], v155 offset:4096
	ds_read_b128 v[200:203], v155 offset:5120
	ds_read_b128 v[204:207], v155 offset:6144
	ds_read_b128 v[208:211], v155 offset:7168
	global_load_lds_dwordx4 v144, s[42:43]
	s_add_i32 m0, s7, 0xe000
	s_nop 0
	global_load_lds_dwordx4 v146, s[42:43]
	s_waitcnt lgkmcnt(8)
	s_barrier
	s_waitcnt lgkmcnt(0)
	s_setprio 1
	s_waitcnt lgkmcnt(0)
	v_mfma_f32_16x16x32_bf16 v[126:129], v[148:151], v[180:183], v[126:129]
	v_mfma_f32_16x16x32_bf16 v[122:125], v[160:163], v[180:183], v[122:125]
	v_mfma_f32_16x16x32_bf16 v[118:121], v[148:151], v[188:191], v[118:121]
	v_mfma_f32_16x16x32_bf16 v[110:113], v[160:163], v[188:191], v[110:113]
	v_mfma_f32_16x16x32_bf16 v[102:105], v[148:151], v[196:199], v[102:105]
	v_mfma_f32_16x16x32_bf16 v[94:97], v[160:163], v[196:199], v[94:97]
	v_mfma_f32_16x16x32_bf16 v[86:89], v[148:151], v[204:207], v[86:89]
	v_mfma_f32_16x16x32_bf16 v[78:81], v[160:163], v[204:207], v[78:81]
	v_mfma_f32_16x16x32_bf16 v[126:129], v[156:159], v[184:187], v[126:129]
	v_mfma_f32_16x16x32_bf16 v[122:125], v[164:167], v[184:187], v[122:125]
	v_mfma_f32_16x16x32_bf16 v[118:121], v[156:159], v[192:195], v[118:121]
	v_mfma_f32_16x16x32_bf16 v[110:113], v[164:167], v[192:195], v[110:113]
	v_mfma_f32_16x16x32_bf16 v[102:105], v[156:159], v[200:203], v[102:105]
	v_mfma_f32_16x16x32_bf16 v[94:97], v[164:167], v[200:203], v[94:97]
	v_mfma_f32_16x16x32_bf16 v[86:89], v[156:159], v[208:211], v[86:89]
	v_mfma_f32_16x16x32_bf16 v[78:81], v[164:167], v[208:211], v[78:81]
	s_setprio 0
	s_barrier
	s_add_i32 s60, 0, 0x14000
	s_add_i32 s58, s58, s6
	ds_read_b128 v[212:215], v134 offset:16384
	ds_read_b128 v[216:219], v134 offset:17408
	ds_read_b128 v[220:223], v134 offset:18432
	ds_read_b128 v[224:227], v134 offset:19456
	s_mov_b32 m0, s58
	global_load_lds_dwordx4 v0, s[26:27]
	s_add_i32 m0, s58, 0x2000
	s_nop 0
	global_load_lds_dwordx4 v138, s[26:27]
	s_barrier
	s_waitcnt lgkmcnt(0)
	s_setprio 1
	s_waitcnt lgkmcnt(0)
	v_mfma_f32_16x16x32_bf16 v[114:117], v[212:215], v[180:183], v[114:117]
	v_mfma_f32_16x16x32_bf16 v[106:109], v[220:223], v[180:183], v[106:109]
	v_mfma_f32_16x16x32_bf16 v[98:101], v[212:215], v[188:191], v[98:101]
	v_mfma_f32_16x16x32_bf16 v[90:93], v[220:223], v[188:191], v[90:93]
	v_mfma_f32_16x16x32_bf16 v[82:85], v[212:215], v[196:199], v[82:85]
	v_mfma_f32_16x16x32_bf16 v[74:77], v[220:223], v[196:199], v[74:77]
	v_mfma_f32_16x16x32_bf16 v[70:73], v[212:215], v[204:207], v[70:73]
	v_mfma_f32_16x16x32_bf16 v[66:69], v[220:223], v[204:207], v[66:69]
	v_mfma_f32_16x16x32_bf16 v[114:117], v[216:219], v[184:187], v[114:117]
	v_mfma_f32_16x16x32_bf16 v[106:109], v[224:227], v[184:187], v[106:109]
	v_mfma_f32_16x16x32_bf16 v[98:101], v[216:219], v[192:195], v[98:101]
	v_mfma_f32_16x16x32_bf16 v[90:93], v[224:227], v[192:195], v[90:93]
	v_mfma_f32_16x16x32_bf16 v[82:85], v[216:219], v[200:203], v[82:85]
	v_mfma_f32_16x16x32_bf16 v[74:77], v[224:227], v[200:203], v[74:77]
	v_mfma_f32_16x16x32_bf16 v[70:73], v[216:219], v[208:211], v[70:73]
	v_mfma_f32_16x16x32_bf16 v[66:69], v[224:227], v[208:211], v[66:69]
	s_setprio 0
	s_mov_b32 m0, s7
	s_add_u32 vcc_lo, s44, s10
	s_addc_u32 vcc_hi, s45, s11
	s_barrier
	ds_read_b128 v[180:183], v155 offset:16384
	ds_read_b128 v[184:187], v155 offset:17408
	ds_read_b128 v[188:191], v155 offset:18432
	ds_read_b128 v[192:195], v155 offset:19456
	ds_read_b128 v[196:199], v155 offset:20480
	ds_read_b128 v[200:203], v155 offset:21504
	ds_read_b128 v[204:207], v155 offset:22528
	ds_read_b128 v[208:211], v155 offset:23552
	global_load_lds_dwordx4 v142, s[44:45]
	s_mov_b32 m0, s14
	s_nop 0
	global_load_lds_dwordx4 v140, s[44:45]
	s_barrier
	s_waitcnt lgkmcnt(0)
	s_setprio 1
	s_waitcnt lgkmcnt(0)
	v_mfma_f32_16x16x32_bf16 v[62:65], v[148:151], v[180:183], v[62:65]
	v_mfma_f32_16x16x32_bf16 v[58:61], v[160:163], v[180:183], v[58:61]
	v_mfma_f32_16x16x32_bf16 v[54:57], v[148:151], v[188:191], v[54:57]
	v_mfma_f32_16x16x32_bf16 v[46:49], v[160:163], v[188:191], v[46:49]
	v_mfma_f32_16x16x32_bf16 v[38:41], v[148:151], v[196:199], v[38:41]
	v_mfma_f32_16x16x32_bf16 v[30:33], v[160:163], v[196:199], v[30:33]
	v_mfma_f32_16x16x32_bf16 v[22:25], v[148:151], v[204:207], v[22:25]
	v_mfma_f32_16x16x32_bf16 v[14:17], v[160:163], v[204:207], v[14:17]
	v_mfma_f32_16x16x32_bf16 v[62:65], v[156:159], v[184:187], v[62:65]
	v_mfma_f32_16x16x32_bf16 v[58:61], v[164:167], v[184:187], v[58:61]
	v_mfma_f32_16x16x32_bf16 v[54:57], v[156:159], v[192:195], v[54:57]
	v_mfma_f32_16x16x32_bf16 v[46:49], v[164:167], v[192:195], v[46:49]
	v_mfma_f32_16x16x32_bf16 v[38:41], v[156:159], v[200:203], v[38:41]
	v_mfma_f32_16x16x32_bf16 v[30:33], v[164:167], v[200:203], v[30:33]
	v_mfma_f32_16x16x32_bf16 v[22:25], v[156:159], v[208:211], v[22:25]
	v_mfma_f32_16x16x32_bf16 v[14:17], v[164:167], v[208:211], v[14:17]
	s_setprio 0
	s_barrier
	s_add_u32 s58, s26, 0x80000
	s_addc_u32 s59, s27, 0
	s_add_i32 s60, s60, s6
	s_mov_b32 m0, s60
	s_nop 0
	global_load_lds_dwordx4 v0, s[58:59]
	s_add_i32 m0, s60, 0x2000
	s_nop 0
	global_load_lds_dwordx4 v138, s[58:59]
	s_waitcnt vmcnt(6)
	s_barrier
	s_setprio 1
	v_mfma_f32_16x16x32_bf16 v[50:53], v[212:215], v[180:183], v[50:53]
	v_mfma_f32_16x16x32_bf16 v[42:45], v[220:223], v[180:183], v[42:45]
	v_mfma_f32_16x16x32_bf16 v[34:37], v[212:215], v[188:191], v[34:37]
	v_mfma_f32_16x16x32_bf16 v[26:29], v[220:223], v[188:191], v[26:29]
	v_mfma_f32_16x16x32_bf16 v[18:21], v[212:215], v[196:199], v[18:21]
	v_mfma_f32_16x16x32_bf16 v[10:13], v[220:223], v[196:199], v[10:13]
	v_mfma_f32_16x16x32_bf16 v[6:9], v[212:215], v[204:207], v[6:9]
	v_mfma_f32_16x16x32_bf16 v[2:5], v[220:223], v[204:207], v[2:5]
	v_mfma_f32_16x16x32_bf16 v[50:53], v[216:219], v[184:187], v[50:53]
	v_mfma_f32_16x16x32_bf16 v[42:45], v[224:227], v[184:187], v[42:45]
	v_mfma_f32_16x16x32_bf16 v[34:37], v[216:219], v[192:195], v[34:37]
	v_mfma_f32_16x16x32_bf16 v[26:29], v[224:227], v[192:195], v[26:29]
	v_mfma_f32_16x16x32_bf16 v[18:21], v[216:219], v[200:203], v[18:21]
	v_mfma_f32_16x16x32_bf16 v[10:13], v[224:227], v[200:203], v[10:13]
	v_mfma_f32_16x16x32_bf16 v[6:9], v[216:219], v[208:211], v[6:9]
	v_mfma_f32_16x16x32_bf16 v[2:5], v[224:227], v[208:211], v[2:5]
	s_setprio 0
	s_add_i32 s58, 0, 0x18000
	s_barrier
	ds_read_b128 v[148:151], v134 offset:32768
	ds_read_b128 v[156:159], v134 offset:33792
	ds_read_b128 v[160:163], v134 offset:34816
	ds_read_b128 v[164:167], v134 offset:35840
	s_add_u32 s44, s44, 0x80000
	s_addc_u32 s45, s45, 0
	s_mov_b32 m0, s46
	ds_read_b128 v[180:183], v155 offset:32768
	ds_read_b128 v[184:187], v155 offset:33792
	ds_read_b128 v[188:191], v155 offset:34816
	ds_read_b128 v[192:195], v155 offset:35840
	ds_read_b128 v[196:199], v155 offset:36864
	ds_read_b128 v[200:203], v155 offset:37888
	ds_read_b128 v[204:207], v155 offset:38912
	ds_read_b128 v[208:211], v155 offset:39936
	global_load_lds_dwordx4 v142, s[44:45]
	s_mov_b32 m0, s47
	s_nop 0
	global_load_lds_dwordx4 v140, s[44:45]
	s_waitcnt lgkmcnt(8)
	s_barrier
	s_waitcnt lgkmcnt(0)
	s_setprio 1
	s_waitcnt lgkmcnt(0)
	v_mfma_f32_16x16x32_bf16 v[126:129], v[148:151], v[180:183], v[126:129]
	v_mfma_f32_16x16x32_bf16 v[122:125], v[160:163], v[180:183], v[122:125]
	v_mfma_f32_16x16x32_bf16 v[118:121], v[148:151], v[188:191], v[118:121]
	v_mfma_f32_16x16x32_bf16 v[110:113], v[160:163], v[188:191], v[110:113]
	v_mfma_f32_16x16x32_bf16 v[102:105], v[148:151], v[196:199], v[102:105]
	v_mfma_f32_16x16x32_bf16 v[94:97], v[160:163], v[196:199], v[94:97]
	v_mfma_f32_16x16x32_bf16 v[86:89], v[148:151], v[204:207], v[86:89]
	v_mfma_f32_16x16x32_bf16 v[78:81], v[160:163], v[204:207], v[78:81]
	v_mfma_f32_16x16x32_bf16 v[126:129], v[156:159], v[184:187], v[126:129]
	v_mfma_f32_16x16x32_bf16 v[122:125], v[164:167], v[184:187], v[122:125]
	v_mfma_f32_16x16x32_bf16 v[118:121], v[156:159], v[192:195], v[118:121]
	v_mfma_f32_16x16x32_bf16 v[110:113], v[164:167], v[192:195], v[110:113]
	v_mfma_f32_16x16x32_bf16 v[102:105], v[156:159], v[200:203], v[102:105]
	v_mfma_f32_16x16x32_bf16 v[94:97], v[164:167], v[200:203], v[94:97]
	v_mfma_f32_16x16x32_bf16 v[86:89], v[156:159], v[208:211], v[86:89]
	v_mfma_f32_16x16x32_bf16 v[78:81], v[164:167], v[208:211], v[78:81]
	s_setprio 0
	s_barrier
	s_add_i32 s44, 0, 0x1c000
	s_add_i32 s45, s58, s6
	s_add_u32 s100, s26, s10
	s_addc_u32 s101, s27, s11
	s_mov_b32 m0, s45
	ds_read_b128 v[212:215], v134 offset:49152
	ds_read_b128 v[216:219], v134 offset:50176
	ds_read_b128 v[220:223], v134 offset:51200
	ds_read_b128 v[224:227], v134 offset:52224
	global_load_lds_dwordx4 v0, s[100:101]
	s_add_u32 s100, s26, s10
	s_addc_u32 s101, s27, s11
	s_add_i32 m0, s45, 0x2000
	s_nop 0
	global_load_lds_dwordx4 v138, s[100:101]
	s_barrier
	s_waitcnt lgkmcnt(0)
	s_setprio 1
	s_waitcnt lgkmcnt(0)
	v_mfma_f32_16x16x32_bf16 v[114:117], v[212:215], v[180:183], v[114:117]
	v_mfma_f32_16x16x32_bf16 v[106:109], v[220:223], v[180:183], v[106:109]
	v_mfma_f32_16x16x32_bf16 v[98:101], v[212:215], v[188:191], v[98:101]
	v_mfma_f32_16x16x32_bf16 v[90:93], v[220:223], v[188:191], v[90:93]
	v_mfma_f32_16x16x32_bf16 v[82:85], v[212:215], v[196:199], v[82:85]
	v_mfma_f32_16x16x32_bf16 v[74:77], v[220:223], v[196:199], v[74:77]
	v_mfma_f32_16x16x32_bf16 v[70:73], v[212:215], v[204:207], v[70:73]
	v_mfma_f32_16x16x32_bf16 v[66:69], v[220:223], v[204:207], v[66:69]
	v_mfma_f32_16x16x32_bf16 v[114:117], v[216:219], v[184:187], v[114:117]
	v_mfma_f32_16x16x32_bf16 v[106:109], v[224:227], v[184:187], v[106:109]
	v_mfma_f32_16x16x32_bf16 v[98:101], v[216:219], v[192:195], v[98:101]
	v_mfma_f32_16x16x32_bf16 v[90:93], v[224:227], v[192:195], v[90:93]
	v_mfma_f32_16x16x32_bf16 v[82:85], v[216:219], v[200:203], v[82:85]
	v_mfma_f32_16x16x32_bf16 v[74:77], v[224:227], v[200:203], v[74:77]
	v_mfma_f32_16x16x32_bf16 v[70:73], v[216:219], v[208:211], v[70:73]
	v_mfma_f32_16x16x32_bf16 v[66:69], v[224:227], v[208:211], v[66:69]
	s_setprio 0
	s_mov_b32 m0, s48
	s_barrier
	ds_read_b128 v[180:183], v155 offset:49152
	ds_read_b128 v[184:187], v155 offset:50176
	ds_read_b128 v[188:191], v155 offset:51200
	ds_read_b128 v[192:195], v155 offset:52224
	ds_read_b128 v[196:199], v155 offset:53248
	ds_read_b128 v[200:203], v155 offset:54272
	ds_read_b128 v[204:207], v155 offset:55296
	ds_read_b128 v[208:211], v155 offset:56320
	global_load_lds_dwordx4 v142, vcc
	s_mov_b32 m0, s49
	s_nop 0
	global_load_lds_dwordx4 v140, vcc
	s_barrier
	s_waitcnt lgkmcnt(0)
	s_setprio 1
	s_waitcnt lgkmcnt(0)
	v_mfma_f32_16x16x32_bf16 v[62:65], v[148:151], v[180:183], v[62:65]
	v_mfma_f32_16x16x32_bf16 v[58:61], v[160:163], v[180:183], v[58:61]
	v_mfma_f32_16x16x32_bf16 v[54:57], v[148:151], v[188:191], v[54:57]
	v_mfma_f32_16x16x32_bf16 v[46:49], v[160:163], v[188:191], v[46:49]
	v_mfma_f32_16x16x32_bf16 v[38:41], v[148:151], v[196:199], v[38:41]
	v_mfma_f32_16x16x32_bf16 v[30:33], v[160:163], v[196:199], v[30:33]
	v_mfma_f32_16x16x32_bf16 v[22:25], v[148:151], v[204:207], v[22:25]
	v_mfma_f32_16x16x32_bf16 v[14:17], v[160:163], v[204:207], v[14:17]
	v_mfma_f32_16x16x32_bf16 v[62:65], v[156:159], v[184:187], v[62:65]
	v_mfma_f32_16x16x32_bf16 v[58:61], v[164:167], v[184:187], v[58:61]
	v_mfma_f32_16x16x32_bf16 v[54:57], v[156:159], v[192:195], v[54:57]
	v_mfma_f32_16x16x32_bf16 v[46:49], v[164:167], v[192:195], v[46:49]
	v_mfma_f32_16x16x32_bf16 v[38:41], v[156:159], v[200:203], v[38:41]
	v_mfma_f32_16x16x32_bf16 v[30:33], v[164:167], v[200:203], v[30:33]
	v_mfma_f32_16x16x32_bf16 v[22:25], v[156:159], v[208:211], v[22:25]
	v_mfma_f32_16x16x32_bf16 v[14:17], v[164:167], v[208:211], v[14:17]
	s_setprio 0
	s_barrier
	s_add_u32 s26, s26, 0x80080
	s_addc_u32 s27, s27, 0
	s_add_i32 s44, s44, s6
	s_mov_b32 m0, s44
	s_nop 0
	global_load_lds_dwordx4 v0, s[26:27]
	s_add_i32 m0, s44, 0x2000
	s_nop 0
	global_load_lds_dwordx4 v138, s[26:27]
	s_waitcnt vmcnt(6)
	s_barrier
	s_setprio 1
	v_mfma_f32_16x16x32_bf16 v[50:53], v[212:215], v[180:183], v[50:53]
	v_mfma_f32_16x16x32_bf16 v[42:45], v[220:223], v[180:183], v[42:45]
	v_mfma_f32_16x16x32_bf16 v[34:37], v[212:215], v[188:191], v[34:37]
	v_mfma_f32_16x16x32_bf16 v[26:29], v[220:223], v[188:191], v[26:29]
	v_mfma_f32_16x16x32_bf16 v[18:21], v[212:215], v[196:199], v[18:21]
	v_mfma_f32_16x16x32_bf16 v[10:13], v[220:223], v[196:199], v[10:13]
	v_mfma_f32_16x16x32_bf16 v[6:9], v[212:215], v[204:207], v[6:9]
	v_mfma_f32_16x16x32_bf16 v[2:5], v[220:223], v[204:207], v[2:5]
	v_mfma_f32_16x16x32_bf16 v[50:53], v[216:219], v[184:187], v[50:53]
	v_mfma_f32_16x16x32_bf16 v[42:45], v[224:227], v[184:187], v[42:45]
	v_mfma_f32_16x16x32_bf16 v[34:37], v[216:219], v[192:195], v[34:37]
	v_mfma_f32_16x16x32_bf16 v[26:29], v[224:227], v[192:195], v[26:29]
	v_mfma_f32_16x16x32_bf16 v[18:21], v[216:219], v[200:203], v[18:21]
	v_mfma_f32_16x16x32_bf16 v[10:13], v[224:227], v[200:203], v[10:13]
	v_mfma_f32_16x16x32_bf16 v[6:9], v[216:219], v[208:211], v[6:9]
	v_mfma_f32_16x16x32_bf16 v[2:5], v[224:227], v[208:211], v[2:5]
	s_setprio 0
	s_add_i32 s57, s57, 2
	s_add_u32 s42, s42, 0x100
	s_addc_u32 s43, s43, 0
	s_add_u32 s55, s55, 0x100
	s_addc_u32 s56, s56, 0
	s_cmp_gt_u32 s57, 29
	s_barrier
	s_cbranch_scc0 .LBB0_627
	v_lshl_or_b32 v134, s51, 8, v154
	v_lshl_add_u32 v158, s52, 8, v152
	v_ashrrev_i32_e32 v135, 31, v134
	v_mov_b64_e32 v[148:149], s[88:89]
	s_movk_i32 s1, 0x2200
	v_mad_i64_i32 v[156:157], s[26:27], v158, s1, v[148:149]
	v_lshlrev_b64 v[150:151], 1, v[134:135]
	v_lshl_add_u64 v[134:135], v[156:157], 0, v[150:151]
	v_cvt_pk_bf16_f32 v126, v126, v127
	v_cvt_pk_bf16_f32 v127, v128, v129
	v_cvt_pk_bf16_f32 v128, v122, v123
	v_cvt_pk_bf16_f32 v129, v124, v125
	global_store_dwordx4 v[134:135], v[126:129], off
	v_cvt_pk_bf16_f32 v114, v114, v115
	v_cvt_pk_bf16_f32 v115, v116, v117
	v_cvt_pk_bf16_f32 v116, v106, v107
	v_or_b32_e32 v106, 16, v158
	v_mad_i64_i32 v[106:107], s[26:27], v106, s1, v[148:149]
	v_cvt_pk_bf16_f32 v117, v108, v109
	global_store_dwordx4 v[134:135], v[114:117], off offset:256
	s_and_b64 vcc, exec, s[40:41]
	s_mov_b32 s51, s0
	v_lshl_add_u64 v[114:115], v[106:107], 0, v[150:151]
	v_cvt_pk_bf16_f32 v106, v118, v119
	v_cvt_pk_bf16_f32 v107, v120, v121
	v_cvt_pk_bf16_f32 v108, v110, v111
	v_cvt_pk_bf16_f32 v109, v112, v113
	global_store_dwordx4 v[114:115], v[106:109], off
	v_cvt_pk_bf16_f32 v98, v98, v99
	v_cvt_pk_bf16_f32 v99, v100, v101
	v_cvt_pk_bf16_f32 v100, v90, v91
	v_or_b32_e32 v90, 32, v158
	v_mad_i64_i32 v[90:91], s[26:27], v90, s1, v[148:149]
	v_cvt_pk_bf16_f32 v101, v92, v93
	global_store_dwordx4 v[114:115], v[98:101], off offset:256
	s_mov_b32 s52, s22
	s_mov_b64 s[42:43], s[24:25]
	v_lshl_add_u64 v[98:99], v[90:91], 0, v[150:151]
	v_cvt_pk_bf16_f32 v90, v102, v103
	v_cvt_pk_bf16_f32 v91, v104, v105
	v_cvt_pk_bf16_f32 v92, v94, v95
	v_cvt_pk_bf16_f32 v93, v96, v97
	global_store_dwordx4 v[98:99], v[90:93], off
	v_cvt_pk_bf16_f32 v82, v82, v83
	v_cvt_pk_bf16_f32 v83, v84, v85
	v_cvt_pk_bf16_f32 v84, v74, v75
	v_or_b32_e32 v74, 48, v158
	v_mad_i64_i32 v[74:75], s[26:27], v74, s1, v[148:149]
	v_cvt_pk_bf16_f32 v85, v76, v77
	global_store_dwordx4 v[98:99], v[82:85], off offset:256
	s_nop 1
	v_lshl_add_u64 v[82:83], v[74:75], 0, v[150:151]
	v_cvt_pk_bf16_f32 v74, v86, v87
	v_cvt_pk_bf16_f32 v75, v88, v89
	v_cvt_pk_bf16_f32 v76, v78, v79
	v_cvt_pk_bf16_f32 v77, v80, v81
	global_store_dwordx4 v[82:83], v[74:77], off
	v_cvt_pk_bf16_f32 v70, v70, v71
	v_cvt_pk_bf16_f32 v71, v72, v73
	v_cvt_pk_bf16_f32 v72, v66, v67
	v_add_u32_e32 v66, 0x80, v158
	v_mad_i64_i32 v[66:67], s[26:27], v66, s1, v[148:149]
	v_lshl_add_u64 v[66:67], v[66:67], 0, v[150:151]
	v_cvt_pk_bf16_f32 v73, v68, v69
	global_store_dwordx4 v[82:83], v[70:73], off offset:256
	v_cvt_pk_bf16_f32 v62, v62, v63
	v_cvt_pk_bf16_f32 v63, v64, v65
	v_cvt_pk_bf16_f32 v64, v58, v59
	v_cvt_pk_bf16_f32 v65, v60, v61
	global_store_dwordx4 v[66:67], v[62:65], off
	v_cvt_pk_bf16_f32 v50, v50, v51
	v_cvt_pk_bf16_f32 v51, v52, v53
	v_cvt_pk_bf16_f32 v52, v42, v43
	v_add_u32_e32 v42, 0x90, v158
	v_mad_i64_i32 v[42:43], s[26:27], v42, s1, v[148:149]
	v_cvt_pk_bf16_f32 v53, v44, v45
	global_store_dwordx4 v[66:67], v[50:53], off offset:256
	s_nop 1
	v_lshl_add_u64 v[50:51], v[42:43], 0, v[150:151]
	v_cvt_pk_bf16_f32 v42, v54, v55
	v_cvt_pk_bf16_f32 v43, v56, v57
	v_cvt_pk_bf16_f32 v44, v46, v47
	v_cvt_pk_bf16_f32 v45, v48, v49
	global_store_dwordx4 v[50:51], v[42:45], off
	v_cvt_pk_bf16_f32 v34, v34, v35
	v_cvt_pk_bf16_f32 v35, v36, v37
	v_cvt_pk_bf16_f32 v36, v26, v27
	v_add_u32_e32 v26, 0xa0, v158
	v_mad_i64_i32 v[26:27], s[26:27], v26, s1, v[148:149]
	v_cvt_pk_bf16_f32 v37, v28, v29
	global_store_dwordx4 v[50:51], v[34:37], off offset:256
	s_nop 1
	v_lshl_add_u64 v[34:35], v[26:27], 0, v[150:151]
	v_cvt_pk_bf16_f32 v26, v38, v39
	v_cvt_pk_bf16_f32 v27, v40, v41
	v_cvt_pk_bf16_f32 v28, v30, v31
	v_cvt_pk_bf16_f32 v29, v32, v33
	global_store_dwordx4 v[34:35], v[26:29], off
	v_cvt_pk_bf16_f32 v18, v18, v19
	v_cvt_pk_bf16_f32 v19, v20, v21
	v_cvt_pk_bf16_f32 v20, v10, v11
	v_add_u32_e32 v10, 0xb0, v158
	v_mad_i64_i32 v[10:11], s[26:27], v10, s1, v[148:149]
	v_cvt_pk_bf16_f32 v21, v12, v13
	global_store_dwordx4 v[34:35], v[18:21], off offset:256
	s_mov_b64 s[26:27], s[38:39]
	s_nop 0
	v_lshl_add_u64 v[18:19], v[10:11], 0, v[150:151]
	v_cvt_pk_bf16_f32 v10, v22, v23
	v_cvt_pk_bf16_f32 v11, v24, v25
	v_cvt_pk_bf16_f32 v12, v14, v15
	v_cvt_pk_bf16_f32 v13, v16, v17
	global_store_dwordx4 v[18:19], v[10:13], off
	v_cvt_pk_bf16_f32 v6, v6, v7
	v_cvt_pk_bf16_f32 v7, v8, v9
	v_cvt_pk_bf16_f32 v8, v2, v3
	v_cvt_pk_bf16_f32 v9, v4, v5
	global_store_dwordx4 v[18:19], v[6:9], off offset:256
	s_cbranch_vccz .LBB0_624
	s_waitcnt vmcnt(0)
	v_readlane_b32 s52, v254, 26
	v_readlane_b32 s50, v254, 28
	s_cmpk_gt_u32 s4, 0xff
	v_readlane_b32 s53, v254, 27
	v_readlane_b32 s51, v254, 29
	s_cbranch_scc1 .LBB0_631
	s_barrier

.LBB0_1033:
	s_ashr_i32 s23, s22, 31
	v_cmp_lt_i64_e32 vcc, s[24:25], v[130:131]
	s_lshl_b64 s[24:25], s[22:23], 20
	s_add_u32 s24, s78, s24
	s_addc_u32 s25, s79, s25
	s_and_b64 s[40:41], vcc, exec
	s_cselect_b32 s23, s25, s43
	s_cselect_b32 s53, s24, s42
	s_ashr_i32 s1, s0, 31
	s_lshl_b64 s[40:41], s[0:1], 20
	s_add_u32 s40, s68, s40
	s_addc_u32 s41, s69, s41
	s_and_b64 s[44:45], vcc, exec
	s_cselect_b32 s1, s41, s27
	s_cselect_b32 s54, s40, s26
	s_add_u32 s42, s42, 0x80080
	s_addc_u32 s43, s43, 0
	s_add_u32 s55, s26, 0x100
	v_mov_b32_e32 v2, 0
	s_addc_u32 s56, s27, 0
	s_mov_b32 s57, -2
	v_mov_b32_e32 v3, v2
	v_mov_b32_e32 v4, v2
	v_mov_b32_e32 v5, v2
	v_mov_b32_e32 v6, v2
	v_mov_b32_e32 v7, v2
	v_mov_b32_e32 v8, v2
	v_mov_b32_e32 v9, v2
	v_mov_b32_e32 v18, v2
	v_mov_b32_e32 v19, v2
	v_mov_b32_e32 v20, v2
	v_mov_b32_e32 v21, v2
	v_mov_b32_e32 v22, v2
	v_mov_b32_e32 v23, v2
	v_mov_b32_e32 v24, v2
	v_mov_b32_e32 v25, v2
	v_mov_b32_e32 v34, v2
	v_mov_b32_e32 v35, v2
	v_mov_b32_e32 v36, v2
	v_mov_b32_e32 v37, v2
	v_mov_b32_e32 v38, v2
	v_mov_b32_e32 v39, v2
	v_mov_b32_e32 v40, v2
	v_mov_b32_e32 v41, v2
	v_mov_b32_e32 v50, v2
	v_mov_b32_e32 v51, v2
	v_mov_b32_e32 v52, v2
	v_mov_b32_e32 v53, v2
	v_mov_b32_e32 v54, v2
	v_mov_b32_e32 v55, v2
	v_mov_b32_e32 v56, v2
	v_mov_b32_e32 v57, v2
	v_mov_b32_e32 v10, v2
	v_mov_b32_e32 v11, v2
	v_mov_b32_e32 v12, v2
	v_mov_b32_e32 v13, v2
	v_mov_b32_e32 v14, v2
	v_mov_b32_e32 v15, v2
	v_mov_b32_e32 v16, v2
	v_mov_b32_e32 v17, v2
	v_mov_b32_e32 v26, v2
	v_mov_b32_e32 v27, v2
	v_mov_b32_e32 v28, v2
	v_mov_b32_e32 v29, v2
	v_mov_b32_e32 v30, v2
	v_mov_b32_e32 v31, v2
	v_mov_b32_e32 v32, v2
	v_mov_b32_e32 v33, v2
	v_mov_b32_e32 v42, v2
	v_mov_b32_e32 v43, v2
	v_mov_b32_e32 v44, v2
	v_mov_b32_e32 v45, v2
	v_mov_b32_e32 v46, v2
	v_mov_b32_e32 v47, v2
	v_mov_b32_e32 v48, v2
	v_mov_b32_e32 v49, v2
	v_mov_b32_e32 v58, v2
	v_mov_b32_e32 v59, v2
	v_mov_b32_e32 v60, v2
	v_mov_b32_e32 v61, v2
	v_mov_b32_e32 v62, v2
	v_mov_b32_e32 v63, v2
	v_mov_b32_e32 v64, v2
	v_mov_b32_e32 v65, v2
	v_mov_b32_e32 v66, v2
	v_mov_b32_e32 v67, v2
	v_mov_b32_e32 v68, v2
	v_mov_b32_e32 v69, v2
	v_mov_b32_e32 v70, v2
	v_mov_b32_e32 v71, v2
	v_mov_b32_e32 v72, v2
	v_mov_b32_e32 v73, v2
	v_mov_b32_e32 v82, v2
	v_mov_b32_e32 v83, v2
	v_mov_b32_e32 v84, v2
	v_mov_b32_e32 v85, v2
	v_mov_b32_e32 v86, v2
	v_mov_b32_e32 v87, v2
	v_mov_b32_e32 v88, v2
	v_mov_b32_e32 v89, v2
	v_mov_b32_e32 v98, v2
	v_mov_b32_e32 v99, v2
	v_mov_b32_e32 v100, v2
	v_mov_b32_e32 v101, v2
	v_mov_b32_e32 v102, v2
	v_mov_b32_e32 v103, v2
	v_mov_b32_e32 v104, v2
	v_mov_b32_e32 v105, v2
	v_mov_b32_e32 v114, v2
	v_mov_b32_e32 v115, v2
	v_mov_b32_e32 v116, v2
	v_mov_b32_e32 v117, v2
	v_mov_b32_e32 v118, v2
	v_mov_b32_e32 v119, v2
	v_mov_b32_e32 v120, v2
	v_mov_b32_e32 v121, v2
	v_mov_b32_e32 v74, v2
	v_mov_b32_e32 v75, v2
	v_mov_b32_e32 v76, v2
	v_mov_b32_e32 v77, v2
	v_mov_b32_e32 v78, v2
	v_mov_b32_e32 v79, v2
	v_mov_b32_e32 v80, v2
	v_mov_b32_e32 v81, v2
	v_mov_b32_e32 v90, v2
	v_mov_b32_e32 v91, v2
	v_mov_b32_e32 v92, v2
	v_mov_b32_e32 v93, v2
	v_mov_b32_e32 v94, v2
	v_mov_b32_e32 v95, v2
	v_mov_b32_e32 v96, v2
	v_mov_b32_e32 v97, v2
	v_mov_b32_e32 v106, v2
	v_mov_b32_e32 v107, v2
	v_mov_b32_e32 v108, v2
	v_mov_b32_e32 v109, v2
	v_mov_b32_e32 v110, v2
	v_mov_b32_e32 v111, v2
	v_mov_b32_e32 v112, v2
	v_mov_b32_e32 v113, v2
	v_mov_b32_e32 v122, v2
	v_mov_b32_e32 v123, v2
	v_mov_b32_e32 v124, v2
	v_mov_b32_e32 v125, v2
	v_mov_b32_e32 v126, v2
	v_mov_b32_e32 v127, v2
	v_mov_b32_e32 v128, v2
	v_mov_b32_e32 v129, v2
	v_add_u32_e32 v134, 0x10000, v155
.LBB0_1034:
	s_add_u32 s26, s42, 0xfff80080
	s_addc_u32 s27, s43, -1
	s_add_i32 s58, 0, 0x10000
	ds_read_b128 v[148:151], v134
	ds_read_b128 v[158:161], v134 offset:1024
	ds_read_b128 v[162:165], v134 offset:2048
	ds_read_b128 v[180:183], v134 offset:3072
	s_cmp_eq_u32 s57, 28
	s_cselect_b32 s45, s23, s27
	s_cselect_b32 s44, s53, s26
	s_cselect_b32 s27, s1, s56
	s_cselect_b32 s26, s54, s55
	s_add_i32 m0, s7, 0xc000
	ds_read_b128 v[184:187], v157
	ds_read_b128 v[188:191], v157 offset:1024
	ds_read_b128 v[192:195], v157 offset:2048
	ds_read_b128 v[196:199], v157 offset:3072
	ds_read_b128 v[200:203], v157 offset:4096
	ds_read_b128 v[204:207], v157 offset:5120
	ds_read_b128 v[208:211], v157 offset:6144
	ds_read_b128 v[212:215], v157 offset:7168
	global_load_lds_dwordx4 v144, s[42:43]
	s_add_i32 m0, s7, 0xe000
	s_nop 0
	global_load_lds_dwordx4 v146, s[42:43]
	s_waitcnt lgkmcnt(8)
	s_barrier
	s_waitcnt lgkmcnt(0)
	s_setprio 1
	s_waitcnt lgkmcnt(0)
	v_mfma_f32_16x16x32_bf16 v[126:129], v[148:151], v[184:187], v[126:129]
	v_mfma_f32_16x16x32_bf16 v[122:125], v[162:165], v[184:187], v[122:125]
	v_mfma_f32_16x16x32_bf16 v[110:113], v[148:151], v[192:195], v[110:113]
	v_mfma_f32_16x16x32_bf16 v[106:109], v[162:165], v[192:195], v[106:109]
	v_mfma_f32_16x16x32_bf16 v[94:97], v[148:151], v[200:203], v[94:97]
	v_mfma_f32_16x16x32_bf16 v[90:93], v[162:165], v[200:203], v[90:93]
	v_mfma_f32_16x16x32_bf16 v[78:81], v[148:151], v[208:211], v[78:81]
	v_mfma_f32_16x16x32_bf16 v[74:77], v[162:165], v[208:211], v[74:77]
	v_mfma_f32_16x16x32_bf16 v[126:129], v[158:161], v[188:191], v[126:129]
	v_mfma_f32_16x16x32_bf16 v[122:125], v[180:183], v[188:191], v[122:125]
	v_mfma_f32_16x16x32_bf16 v[110:113], v[158:161], v[196:199], v[110:113]
	v_mfma_f32_16x16x32_bf16 v[106:109], v[180:183], v[196:199], v[106:109]
	v_mfma_f32_16x16x32_bf16 v[94:97], v[158:161], v[204:207], v[94:97]
	v_mfma_f32_16x16x32_bf16 v[90:93], v[180:183], v[204:207], v[90:93]
	v_mfma_f32_16x16x32_bf16 v[78:81], v[158:161], v[212:215], v[78:81]
	v_mfma_f32_16x16x32_bf16 v[74:77], v[180:183], v[212:215], v[74:77]
	s_setprio 0
	s_barrier
	s_add_i32 s60, 0, 0x14000
	s_add_i32 s58, s58, s6
	ds_read_b128 v[216:219], v134 offset:16384
	ds_read_b128 v[220:223], v134 offset:17408
	ds_read_b128 v[224:227], v134 offset:18432
	ds_read_b128 v[228:231], v134 offset:19456
	s_mov_b32 m0, s58
	global_load_lds_dwordx4 v0, s[26:27]
	s_add_i32 m0, s58, 0x2000
	s_nop 0
	global_load_lds_dwordx4 v138, s[26:27]
	s_barrier
	s_waitcnt lgkmcnt(0)
	s_setprio 1
	s_waitcnt lgkmcnt(0)
	v_mfma_f32_16x16x32_bf16 v[118:121], v[216:219], v[184:187], v[118:121]
	v_mfma_f32_16x16x32_bf16 v[114:117], v[224:227], v[184:187], v[114:117]
	v_mfma_f32_16x16x32_bf16 v[102:105], v[216:219], v[192:195], v[102:105]
	v_mfma_f32_16x16x32_bf16 v[98:101], v[224:227], v[192:195], v[98:101]
	v_mfma_f32_16x16x32_bf16 v[86:89], v[216:219], v[200:203], v[86:89]
	v_mfma_f32_16x16x32_bf16 v[82:85], v[224:227], v[200:203], v[82:85]
	v_mfma_f32_16x16x32_bf16 v[70:73], v[216:219], v[208:211], v[70:73]
	v_mfma_f32_16x16x32_bf16 v[66:69], v[224:227], v[208:211], v[66:69]
	v_mfma_f32_16x16x32_bf16 v[118:121], v[220:223], v[188:191], v[118:121]
	v_mfma_f32_16x16x32_bf16 v[114:117], v[228:231], v[188:191], v[114:117]
	v_mfma_f32_16x16x32_bf16 v[102:105], v[220:223], v[196:199], v[102:105]
	v_mfma_f32_16x16x32_bf16 v[98:101], v[228:231], v[196:199], v[98:101]
	v_mfma_f32_16x16x32_bf16 v[86:89], v[220:223], v[204:207], v[86:89]
	v_mfma_f32_16x16x32_bf16 v[82:85], v[228:231], v[204:207], v[82:85]
	v_mfma_f32_16x16x32_bf16 v[70:73], v[220:223], v[212:215], v[70:73]
	v_mfma_f32_16x16x32_bf16 v[66:69], v[228:231], v[212:215], v[66:69]
	s_setprio 0
	s_mov_b32 m0, s7
	s_add_u32 vcc_lo, s44, s10
	s_addc_u32 vcc_hi, s45, s11
	s_barrier
	ds_read_b128 v[184:187], v157 offset:16384
	ds_read_b128 v[188:191], v157 offset:17408
	ds_read_b128 v[192:195], v157 offset:18432
	ds_read_b128 v[196:199], v157 offset:19456
	ds_read_b128 v[200:203], v157 offset:20480
	ds_read_b128 v[204:207], v157 offset:21504
	ds_read_b128 v[208:211], v157 offset:22528
	ds_read_b128 v[212:215], v157 offset:23552
	global_load_lds_dwordx4 v142, s[44:45]
	s_mov_b32 m0, s14
	s_nop 0
	global_load_lds_dwordx4 v140, s[44:45]
	s_barrier
	s_waitcnt lgkmcnt(0)
	s_setprio 1
	s_waitcnt lgkmcnt(0)
	v_mfma_f32_16x16x32_bf16 v[62:65], v[148:151], v[184:187], v[62:65]
	v_mfma_f32_16x16x32_bf16 v[58:61], v[162:165], v[184:187], v[58:61]
	v_mfma_f32_16x16x32_bf16 v[46:49], v[148:151], v[192:195], v[46:49]
	v_mfma_f32_16x16x32_bf16 v[42:45], v[162:165], v[192:195], v[42:45]
	v_mfma_f32_16x16x32_bf16 v[30:33], v[148:151], v[200:203], v[30:33]
	v_mfma_f32_16x16x32_bf16 v[26:29], v[162:165], v[200:203], v[26:29]
	v_mfma_f32_16x16x32_bf16 v[14:17], v[148:151], v[208:211], v[14:17]
	v_mfma_f32_16x16x32_bf16 v[10:13], v[162:165], v[208:211], v[10:13]
	v_mfma_f32_16x16x32_bf16 v[62:65], v[158:161], v[188:191], v[62:65]
	v_mfma_f32_16x16x32_bf16 v[58:61], v[180:183], v[188:191], v[58:61]
	v_mfma_f32_16x16x32_bf16 v[46:49], v[158:161], v[196:199], v[46:49]
	v_mfma_f32_16x16x32_bf16 v[42:45], v[180:183], v[196:199], v[42:45]
	v_mfma_f32_16x16x32_bf16 v[30:33], v[158:161], v[204:207], v[30:33]
	v_mfma_f32_16x16x32_bf16 v[26:29], v[180:183], v[204:207], v[26:29]
	v_mfma_f32_16x16x32_bf16 v[14:17], v[158:161], v[212:215], v[14:17]
	v_mfma_f32_16x16x32_bf16 v[10:13], v[180:183], v[212:215], v[10:13]
	s_setprio 0
	s_barrier
	s_add_u32 s58, s26, 0x80000
	s_addc_u32 s59, s27, 0
	s_add_i32 s60, s60, s6
	s_mov_b32 m0, s60
	s_nop 0
	global_load_lds_dwordx4 v0, s[58:59]
	s_add_i32 m0, s60, 0x2000
	s_nop 0
	global_load_lds_dwordx4 v138, s[58:59]
	s_waitcnt vmcnt(6)
	s_barrier
	s_setprio 1
	v_mfma_f32_16x16x32_bf16 v[54:57], v[216:219], v[184:187], v[54:57]
	v_mfma_f32_16x16x32_bf16 v[50:53], v[224:227], v[184:187], v[50:53]
	v_mfma_f32_16x16x32_bf16 v[38:41], v[216:219], v[192:195], v[38:41]
	v_mfma_f32_16x16x32_bf16 v[34:37], v[224:227], v[192:195], v[34:37]
	v_mfma_f32_16x16x32_bf16 v[22:25], v[216:219], v[200:203], v[22:25]
	v_mfma_f32_16x16x32_bf16 v[18:21], v[224:227], v[200:203], v[18:21]
	v_mfma_f32_16x16x32_bf16 v[6:9], v[216:219], v[208:211], v[6:9]
	v_mfma_f32_16x16x32_bf16 v[2:5], v[224:227], v[208:211], v[2:5]
	v_mfma_f32_16x16x32_bf16 v[54:57], v[220:223], v[188:191], v[54:57]
	v_mfma_f32_16x16x32_bf16 v[50:53], v[228:231], v[188:191], v[50:53]
	v_mfma_f32_16x16x32_bf16 v[38:41], v[220:223], v[196:199], v[38:41]
	v_mfma_f32_16x16x32_bf16 v[34:37], v[228:231], v[196:199], v[34:37]
	v_mfma_f32_16x16x32_bf16 v[22:25], v[220:223], v[204:207], v[22:25]
	v_mfma_f32_16x16x32_bf16 v[18:21], v[228:231], v[204:207], v[18:21]
	v_mfma_f32_16x16x32_bf16 v[6:9], v[220:223], v[212:215], v[6:9]
	v_mfma_f32_16x16x32_bf16 v[2:5], v[228:231], v[212:215], v[2:5]
	s_setprio 0
	s_add_i32 s58, 0, 0x18000
	s_barrier
	ds_read_b128 v[148:151], v134 offset:32768
	ds_read_b128 v[158:161], v134 offset:33792
	ds_read_b128 v[162:165], v134 offset:34816
	ds_read_b128 v[180:183], v134 offset:35840
	s_add_u32 s44, s44, 0x80000
	s_addc_u32 s45, s45, 0
	s_mov_b32 m0, s46
	ds_read_b128 v[184:187], v157 offset:32768
	ds_read_b128 v[188:191], v157 offset:33792
	ds_read_b128 v[192:195], v157 offset:34816
	ds_read_b128 v[196:199], v157 offset:35840
	ds_read_b128 v[200:203], v157 offset:36864
	ds_read_b128 v[204:207], v157 offset:37888
	ds_read_b128 v[208:211], v157 offset:38912
	ds_read_b128 v[212:215], v157 offset:39936
	global_load_lds_dwordx4 v142, s[44:45]
	s_mov_b32 m0, s47
	s_nop 0
	global_load_lds_dwordx4 v140, s[44:45]
	s_waitcnt lgkmcnt(8)
	s_barrier
	s_waitcnt lgkmcnt(0)
	s_setprio 1
	s_waitcnt lgkmcnt(0)
	v_mfma_f32_16x16x32_bf16 v[126:129], v[148:151], v[184:187], v[126:129]
	v_mfma_f32_16x16x32_bf16 v[122:125], v[162:165], v[184:187], v[122:125]
	v_mfma_f32_16x16x32_bf16 v[110:113], v[148:151], v[192:195], v[110:113]
	v_mfma_f32_16x16x32_bf16 v[106:109], v[162:165], v[192:195], v[106:109]
	v_mfma_f32_16x16x32_bf16 v[94:97], v[148:151], v[200:203], v[94:97]
	v_mfma_f32_16x16x32_bf16 v[90:93], v[162:165], v[200:203], v[90:93]
	v_mfma_f32_16x16x32_bf16 v[78:81], v[148:151], v[208:211], v[78:81]
	v_mfma_f32_16x16x32_bf16 v[74:77], v[162:165], v[208:211], v[74:77]
	v_mfma_f32_16x16x32_bf16 v[126:129], v[158:161], v[188:191], v[126:129]
	v_mfma_f32_16x16x32_bf16 v[122:125], v[180:183], v[188:191], v[122:125]
	v_mfma_f32_16x16x32_bf16 v[110:113], v[158:161], v[196:199], v[110:113]
	v_mfma_f32_16x16x32_bf16 v[106:109], v[180:183], v[196:199], v[106:109]
	v_mfma_f32_16x16x32_bf16 v[94:97], v[158:161], v[204:207], v[94:97]
	v_mfma_f32_16x16x32_bf16 v[90:93], v[180:183], v[204:207], v[90:93]
	v_mfma_f32_16x16x32_bf16 v[78:81], v[158:161], v[212:215], v[78:81]
	v_mfma_f32_16x16x32_bf16 v[74:77], v[180:183], v[212:215], v[74:77]
	s_setprio 0
	s_barrier
	s_add_i32 s44, 0, 0x1c000
	s_add_i32 s45, s58, s6
	s_add_u32 s100, s26, s10
	s_addc_u32 s101, s27, s11
	s_mov_b32 m0, s45
	ds_read_b128 v[216:219], v134 offset:49152
	ds_read_b128 v[220:223], v134 offset:50176
	ds_read_b128 v[224:227], v134 offset:51200
	ds_read_b128 v[228:231], v134 offset:52224
	global_load_lds_dwordx4 v0, s[100:101]
	s_add_u32 s100, s26, s10
	s_addc_u32 s101, s27, s11
	s_add_i32 m0, s45, 0x2000
	s_nop 0
	global_load_lds_dwordx4 v138, s[100:101]
	s_barrier
	s_waitcnt lgkmcnt(0)
	s_setprio 1
	s_waitcnt lgkmcnt(0)
	v_mfma_f32_16x16x32_bf16 v[118:121], v[216:219], v[184:187], v[118:121]
	v_mfma_f32_16x16x32_bf16 v[114:117], v[224:227], v[184:187], v[114:117]
	v_mfma_f32_16x16x32_bf16 v[102:105], v[216:219], v[192:195], v[102:105]
	v_mfma_f32_16x16x32_bf16 v[98:101], v[224:227], v[192:195], v[98:101]
	v_mfma_f32_16x16x32_bf16 v[86:89], v[216:219], v[200:203], v[86:89]
	v_mfma_f32_16x16x32_bf16 v[82:85], v[224:227], v[200:203], v[82:85]
	v_mfma_f32_16x16x32_bf16 v[70:73], v[216:219], v[208:211], v[70:73]
	v_mfma_f32_16x16x32_bf16 v[66:69], v[224:227], v[208:211], v[66:69]
	v_mfma_f32_16x16x32_bf16 v[118:121], v[220:223], v[188:191], v[118:121]
	v_mfma_f32_16x16x32_bf16 v[114:117], v[228:231], v[188:191], v[114:117]
	v_mfma_f32_16x16x32_bf16 v[102:105], v[220:223], v[196:199], v[102:105]
	v_mfma_f32_16x16x32_bf16 v[98:101], v[228:231], v[196:199], v[98:101]
	v_mfma_f32_16x16x32_bf16 v[86:89], v[220:223], v[204:207], v[86:89]
	v_mfma_f32_16x16x32_bf16 v[82:85], v[228:231], v[204:207], v[82:85]
	v_mfma_f32_16x16x32_bf16 v[70:73], v[220:223], v[212:215], v[70:73]
	v_mfma_f32_16x16x32_bf16 v[66:69], v[228:231], v[212:215], v[66:69]
	s_setprio 0
	s_mov_b32 m0, s48
	s_barrier
	ds_read_b128 v[184:187], v157 offset:49152
	ds_read_b128 v[188:191], v157 offset:50176
	ds_read_b128 v[192:195], v157 offset:51200
	ds_read_b128 v[196:199], v157 offset:52224
	ds_read_b128 v[200:203], v157 offset:53248
	ds_read_b128 v[204:207], v157 offset:54272
	ds_read_b128 v[208:211], v157 offset:55296
	ds_read_b128 v[212:215], v157 offset:56320
	global_load_lds_dwordx4 v142, vcc
	s_mov_b32 m0, s49
	s_nop 0
	global_load_lds_dwordx4 v140, vcc
	s_barrier
	s_waitcnt lgkmcnt(0)
	s_setprio 1
	s_waitcnt lgkmcnt(0)
	v_mfma_f32_16x16x32_bf16 v[62:65], v[148:151], v[184:187], v[62:65]
	v_mfma_f32_16x16x32_bf16 v[58:61], v[162:165], v[184:187], v[58:61]
	v_mfma_f32_16x16x32_bf16 v[46:49], v[148:151], v[192:195], v[46:49]
	v_mfma_f32_16x16x32_bf16 v[42:45], v[162:165], v[192:195], v[42:45]
	v_mfma_f32_16x16x32_bf16 v[30:33], v[148:151], v[200:203], v[30:33]
	v_mfma_f32_16x16x32_bf16 v[26:29], v[162:165], v[200:203], v[26:29]
	v_mfma_f32_16x16x32_bf16 v[14:17], v[148:151], v[208:211], v[14:17]
	v_mfma_f32_16x16x32_bf16 v[10:13], v[162:165], v[208:211], v[10:13]
	v_mfma_f32_16x16x32_bf16 v[62:65], v[158:161], v[188:191], v[62:65]
	v_mfma_f32_16x16x32_bf16 v[58:61], v[180:183], v[188:191], v[58:61]
	v_mfma_f32_16x16x32_bf16 v[46:49], v[158:161], v[196:199], v[46:49]
	v_mfma_f32_16x16x32_bf16 v[42:45], v[180:183], v[196:199], v[42:45]
	v_mfma_f32_16x16x32_bf16 v[30:33], v[158:161], v[204:207], v[30:33]
	v_mfma_f32_16x16x32_bf16 v[26:29], v[180:183], v[204:207], v[26:29]
	v_mfma_f32_16x16x32_bf16 v[14:17], v[158:161], v[212:215], v[14:17]
	v_mfma_f32_16x16x32_bf16 v[10:13], v[180:183], v[212:215], v[10:13]
	s_setprio 0
	s_barrier
	s_add_u32 s26, s26, 0x80080
	s_addc_u32 s27, s27, 0
	s_add_i32 s44, s44, s6
	s_mov_b32 m0, s44
	s_nop 0
	global_load_lds_dwordx4 v0, s[26:27]
	s_add_i32 m0, s44, 0x2000
	s_nop 0
	global_load_lds_dwordx4 v138, s[26:27]
	s_waitcnt vmcnt(6)
	s_barrier
	s_setprio 1
	v_mfma_f32_16x16x32_bf16 v[54:57], v[216:219], v[184:187], v[54:57]
	v_mfma_f32_16x16x32_bf16 v[50:53], v[224:227], v[184:187], v[50:53]
	v_mfma_f32_16x16x32_bf16 v[38:41], v[216:219], v[192:195], v[38:41]
	v_mfma_f32_16x16x32_bf16 v[34:37], v[224:227], v[192:195], v[34:37]
	v_mfma_f32_16x16x32_bf16 v[22:25], v[216:219], v[200:203], v[22:25]
	v_mfma_f32_16x16x32_bf16 v[18:21], v[224:227], v[200:203], v[18:21]
	v_mfma_f32_16x16x32_bf16 v[6:9], v[216:219], v[208:211], v[6:9]
	v_mfma_f32_16x16x32_bf16 v[2:5], v[224:227], v[208:211], v[2:5]
	v_mfma_f32_16x16x32_bf16 v[54:57], v[220:223], v[188:191], v[54:57]
	v_mfma_f32_16x16x32_bf16 v[50:53], v[228:231], v[188:191], v[50:53]
	v_mfma_f32_16x16x32_bf16 v[38:41], v[220:223], v[196:199], v[38:41]
	v_mfma_f32_16x16x32_bf16 v[34:37], v[228:231], v[196:199], v[34:37]
	v_mfma_f32_16x16x32_bf16 v[22:25], v[220:223], v[204:207], v[22:25]
	v_mfma_f32_16x16x32_bf16 v[18:21], v[228:231], v[204:207], v[18:21]
	v_mfma_f32_16x16x32_bf16 v[6:9], v[220:223], v[212:215], v[6:9]
	v_mfma_f32_16x16x32_bf16 v[2:5], v[228:231], v[212:215], v[2:5]
	s_setprio 0
	s_add_i32 s57, s57, 2
	s_add_u32 s42, s42, 0x100
	s_addc_u32 s43, s43, 0
	s_add_u32 s55, s55, 0x100
	s_addc_u32 s56, s56, 0
	s_cmp_gt_u32 s57, 29
	s_barrier
	s_cbranch_scc0 .LBB0_1034
	v_lshl_add_u32 v150, s52, 8, v154
	v_lshl_or_b32 v134, s51, 8, v156
	v_ashrrev_i32_e32 v151, 31, v150
	v_ashrrev_i32_e32 v135, 31, v134
	v_lshlrev_b64 v[148:149], 13, v[150:151]
	v_lshl_add_u64 v[148:149], s[76:77], 0, v[148:149]
	v_lshlrev_b64 v[152:153], 2, v[134:135]
	v_lshl_add_u64 v[158:159], v[148:149], 0, v[152:153]
	v_readlane_b32 s56, v254, 30
	v_readlane_b32 s54, v254, 32
	v_readlane_b32 s60, v254, 39
	s_mov_b32 s51, s0
	s_mov_b32 s52, s22
	s_mov_b64 s[42:43], s[24:25]
	v_readlane_b32 s57, v254, 31
	v_readlane_b32 s55, v254, 33
	v_readlane_b32 s44, v254, 46
	v_readlane_b32 s61, v254, 40
	v_readlane_b32 s45, v254, 47
	v_mov_b64_e32 v[162:163], v[158:159]
	global_load_dwordx4 v[180:183], v[162:163], off
	global_load_dwordx4 v[184:187], v[162:163], off offset:16
	global_load_dwordx4 v[188:191], v[162:163], off offset:512
	global_load_dwordx4 v[192:195], v[162:163], off offset:528
	s_mov_b64 s[26:27], 0x20000
	v_lshl_add_u64 v[164:165], v[158:159], 0, s[26:27]
	global_load_dwordx4 v[196:199], v[164:165], off
	global_load_dwordx4 v[200:203], v[164:165], off offset:16
	global_load_dwordx4 v[204:207], v[164:165], off offset:512
	global_load_dwordx4 v[208:211], v[164:165], off offset:528
	s_mov_b64 s[26:27], 0x40000
	v_lshl_add_u64 v[150:151], v[158:159], 0, s[26:27]
	global_load_dwordx4 v[212:215], v[150:151], off
	global_load_dwordx4 v[216:219], v[150:151], off offset:16
	global_load_dwordx4 v[220:223], v[150:151], off offset:512
	global_load_dwordx4 v[224:227], v[150:151], off offset:528
	s_waitcnt vmcnt(8)
	v_pk_add_f32 v[126:127], v[126:127], v[180:181]
	v_pk_add_f32 v[128:129], v[128:129], v[182:183]
	v_pk_add_f32 v[122:123], v[122:123], v[184:185]
	v_pk_add_f32 v[124:125], v[124:125], v[186:187]
	v_pk_add_f32 v[118:119], v[118:119], v[188:189]
	v_pk_add_f32 v[120:121], v[120:121], v[190:191]
	v_pk_add_f32 v[114:115], v[114:115], v[192:193]
	v_pk_add_f32 v[116:117], v[116:117], v[194:195]
	global_store_dwordx4 v[162:163], v[126:129], off
	global_store_dwordx4 v[162:163], v[122:125], off offset:16
	global_store_dwordx4 v[162:163], v[118:121], off offset:512
	global_store_dwordx4 v[162:163], v[114:117], off offset:528
	s_mov_b64 s[26:27], 0x60000
	v_lshl_add_u64 v[228:229], v[158:159], 0, s[26:27]
	global_load_dwordx4 v[180:183], v[228:229], off
	global_load_dwordx4 v[184:187], v[228:229], off offset:16
	global_load_dwordx4 v[188:191], v[228:229], off offset:512
	global_load_dwordx4 v[192:195], v[228:229], off offset:528
	s_waitcnt vmcnt(12)
	v_pk_add_f32 v[110:111], v[110:111], v[196:197]
	v_pk_add_f32 v[112:113], v[112:113], v[198:199]
	v_pk_add_f32 v[106:107], v[106:107], v[200:201]
	v_pk_add_f32 v[108:109], v[108:109], v[202:203]
	v_pk_add_f32 v[102:103], v[102:103], v[204:205]
	v_pk_add_f32 v[104:105], v[104:105], v[206:207]
	v_pk_add_f32 v[98:99], v[98:99], v[208:209]
	v_pk_add_f32 v[100:101], v[100:101], v[210:211]
	global_store_dwordx4 v[164:165], v[110:113], off
	global_store_dwordx4 v[164:165], v[106:109], off offset:16
	global_store_dwordx4 v[164:165], v[102:105], off offset:512
	global_store_dwordx4 v[164:165], v[98:101], off offset:528
	s_mov_b64 s[26:27], 0x100000
	v_lshl_add_u64 v[162:163], v[158:159], 0, s[26:27]
	global_load_dwordx4 v[196:199], v[162:163], off
	global_load_dwordx4 v[200:203], v[162:163], off offset:16
	global_load_dwordx4 v[204:207], v[162:163], off offset:512
	global_load_dwordx4 v[208:211], v[162:163], off offset:528
	s_waitcnt vmcnt(16)
	v_pk_add_f32 v[94:95], v[94:95], v[212:213]
	v_pk_add_f32 v[96:97], v[96:97], v[214:215]
	v_pk_add_f32 v[90:91], v[90:91], v[216:217]
	v_pk_add_f32 v[92:93], v[92:93], v[218:219]
	v_pk_add_f32 v[86:87], v[86:87], v[220:221]
	v_pk_add_f32 v[88:89], v[88:89], v[222:223]
	v_pk_add_f32 v[82:83], v[82:83], v[224:225]
	v_pk_add_f32 v[84:85], v[84:85], v[226:227]
	global_store_dwordx4 v[150:151], v[94:97], off
	global_store_dwordx4 v[150:151], v[90:93], off offset:16
	global_store_dwordx4 v[150:151], v[86:89], off offset:512
	global_store_dwordx4 v[150:151], v[82:85], off offset:528
	s_mov_b64 s[26:27], 0x120000
	v_lshl_add_u64 v[164:165], v[158:159], 0, s[26:27]
	global_load_dwordx4 v[212:215], v[164:165], off
	global_load_dwordx4 v[216:219], v[164:165], off offset:16
	global_load_dwordx4 v[220:223], v[164:165], off offset:512
	global_load_dwordx4 v[224:227], v[164:165], off offset:528
	s_waitcnt vmcnt(16)
	v_pk_add_f32 v[78:79], v[78:79], v[180:181]
	v_pk_add_f32 v[80:81], v[80:81], v[182:183]
	v_pk_add_f32 v[74:75], v[74:75], v[184:185]
	v_pk_add_f32 v[76:77], v[76:77], v[186:187]
	v_pk_add_f32 v[70:71], v[70:71], v[188:189]
	v_pk_add_f32 v[72:73], v[72:73], v[190:191]
	v_pk_add_f32 v[66:67], v[66:67], v[192:193]
	v_pk_add_f32 v[68:69], v[68:69], v[194:195]
	global_store_dwordx4 v[228:229], v[78:81], off
	global_store_dwordx4 v[228:229], v[74:77], off offset:16
	global_store_dwordx4 v[228:229], v[70:73], off offset:512
	global_store_dwordx4 v[228:229], v[66:69], off offset:528
	s_mov_b64 s[26:27], 0x140000
	v_lshl_add_u64 v[150:151], v[158:159], 0, s[26:27]
	global_load_dwordx4 v[180:183], v[150:151], off
	global_load_dwordx4 v[184:187], v[150:151], off offset:16
	global_load_dwordx4 v[188:191], v[150:151], off offset:512
	global_load_dwordx4 v[192:195], v[150:151], off offset:528
	s_waitcnt vmcnt(16)
	v_pk_add_f32 v[62:63], v[62:63], v[196:197]
	v_pk_add_f32 v[64:65], v[64:65], v[198:199]
	v_pk_add_f32 v[58:59], v[58:59], v[200:201]
	v_pk_add_f32 v[60:61], v[60:61], v[202:203]
	v_pk_add_f32 v[54:55], v[54:55], v[204:205]
	v_pk_add_f32 v[56:57], v[56:57], v[206:207]
	v_pk_add_f32 v[50:51], v[50:51], v[208:209]
	v_pk_add_f32 v[52:53], v[52:53], v[210:211]
	global_store_dwordx4 v[162:163], v[62:65], off
	global_store_dwordx4 v[162:163], v[58:61], off offset:16
	global_store_dwordx4 v[162:163], v[54:57], off offset:512
	global_store_dwordx4 v[162:163], v[50:53], off offset:528
	s_mov_b64 s[26:27], 0x160000
	v_lshl_add_u64 v[228:229], v[158:159], 0, s[26:27]
	global_load_dwordx4 v[196:199], v[228:229], off
	global_load_dwordx4 v[200:203], v[228:229], off offset:16
	global_load_dwordx4 v[204:207], v[228:229], off offset:512
	global_load_dwordx4 v[208:211], v[228:229], off offset:528
	s_waitcnt vmcnt(16)
	v_pk_add_f32 v[46:47], v[46:47], v[212:213]
	v_pk_add_f32 v[48:49], v[48:49], v[214:215]
	v_pk_add_f32 v[42:43], v[42:43], v[216:217]
	v_pk_add_f32 v[44:45], v[44:45], v[218:219]
	v_pk_add_f32 v[38:39], v[38:39], v[220:221]
	v_pk_add_f32 v[40:41], v[40:41], v[222:223]
	v_pk_add_f32 v[34:35], v[34:35], v[224:225]
	v_pk_add_f32 v[36:37], v[36:37], v[226:227]
	global_store_dwordx4 v[164:165], v[46:49], off
	global_store_dwordx4 v[164:165], v[42:45], off offset:16
	global_store_dwordx4 v[164:165], v[38:41], off offset:512
	global_store_dwordx4 v[164:165], v[34:37], off offset:528
	s_waitcnt vmcnt(12)
	v_pk_add_f32 v[30:31], v[30:31], v[180:181]
	v_pk_add_f32 v[32:33], v[32:33], v[182:183]
	v_pk_add_f32 v[26:27], v[26:27], v[184:185]
	v_pk_add_f32 v[28:29], v[28:29], v[186:187]
	v_pk_add_f32 v[22:23], v[22:23], v[188:189]
	v_pk_add_f32 v[24:25], v[24:25], v[190:191]
	v_pk_add_f32 v[18:19], v[18:19], v[192:193]
	v_pk_add_f32 v[20:21], v[20:21], v[194:195]
	global_store_dwordx4 v[150:151], v[30:33], off
	global_store_dwordx4 v[150:151], v[26:29], off offset:16
	global_store_dwordx4 v[150:151], v[22:25], off offset:512
	global_store_dwordx4 v[150:151], v[18:21], off offset:528
	s_waitcnt vmcnt(8)
	v_pk_add_f32 v[14:15], v[14:15], v[196:197]
	v_pk_add_f32 v[16:17], v[16:17], v[198:199]
	v_pk_add_f32 v[10:11], v[10:11], v[200:201]
	v_pk_add_f32 v[12:13], v[12:13], v[202:203]
	v_pk_add_f32 v[6:7], v[6:7], v[204:205]
	v_pk_add_f32 v[8:9], v[8:9], v[206:207]
	v_pk_add_f32 v[2:3], v[2:3], v[208:209]
	v_pk_add_f32 v[4:5], v[4:5], v[210:211]
	global_store_dwordx4 v[228:229], v[14:17], off
	global_store_dwordx4 v[228:229], v[10:13], off offset:16
	global_store_dwordx4 v[228:229], v[6:9], off offset:512
	global_store_dwordx4 v[228:229], v[2:5], off offset:528
	s_mov_b32 s1, 0x160000
	s_and_b64 vcc, exec, s[38:39]
	s_mov_b64 s[26:27], s[40:41]
	s_cbranch_vccz .LBB0_1027
	s_waitcnt vmcnt(0)
	v_readlane_b32 s52, v254, 26
	v_readlane_b32 s50, v254, 28
	s_mov_b64 s[58:59], s[84:85]
	s_cmpk_gt_u32 s4, 0xff
	v_readlane_b32 s53, v254, 27
	v_readlane_b32 s51, v254, 29
	s_cbranch_scc1 .LBB0_1038
	s_barrier
